# kloop-dma-waits-vmcnt10-one-phase-before-read
# speedup vs baseline: 1.0153x; 1.0090x over previous
; #define PG8_STAGE(bufoff, gbase, hoff, imm) do { _Pragma("unroll") for (int _i = 0; _i < 2; ++_i) { \
;         asm volatile("s_mov_b32 m0, %0\n\ts_nop 0\n\tglobal_load_lds_dwordx4 %1, %2" \
;             :: "s"(lds0 + (unsigned)((bufoff) + _i * 8192)), "v"(voff0), "s"((const char*)(gbase) + (size_t)(hoff) + (size_t)(_i * 8192)) : "memory"); } } while (0)
; #define PG8_LDA(dst, b, h) do { _Pragma("unroll") for (int m = 0; m < 4; ++m) _Pragma("unroll") for (int k = 0; k < 2; ++k) dst[m][k] = *(const LAS bf16x8*)(lds + PG8_SA(b, h) + aoff + m * 2048 + k * 1024); } while (0)
; #define PG8_LDB(dst, b, h) do { _Pragma("unroll") for (int n = 0; n < 2; ++n) _Pragma("unroll") for (int k = 0; k < 2; ++k) dst[n][k] = *(const LAS bf16x8*)(lds + PG8_SB(b, h) + boff + n * 2048 + k * 1024); } while (0)
; #define PG8_MMA(ai, bj, At, Bt) do { __builtin_amdgcn_s_setprio(1); _Pragma("unroll") for (int m = 0; m < 4; ++m) _Pragma("unroll") for (int n = 0; n < 2; ++n) _Pragma("unroll") for (int k = 0; k < 2; ++k) \
;         acc[ai][bj][m][n] = __builtin_amdgcn_mfma_f32_16x16x32_bf16(Bt[n][k], At[m][k], acc[ai][bj][m][n], 0, 0, 0); __builtin_amdgcn_s_setprio(0); } while (0)
; #define PG8_WAIT_L(n) asm volatile("s_waitcnt lgkmcnt(" #n ")" ::: "memory")
; #define PG8_BAR __builtin_amdgcn_s_barrier()
; #define PG8_SCHED __builtin_amdgcn_sched_barrier(0)
; template <class Epi>
; __device__ __forceinline__ void gemm_phase(LAS unsigned char* lds, const Gemm g, const StaticOrder& S, const Epi& E) {
;     ...
;         for (int t = 0; t < nt; t += 2) {
;             const bool last = (t == nt - 2);
;             if (last) E.pre(cur, wid, lane, (unsigned)(size_t)(lds + STAGE_BYTES));
;             const char* aT = cA + (size_t)t * KS;
;             const char* a2 = last ? nA : aT + 2 * KS; const char* b2 = last ? nB : cB + (size_t)(t + 2) * KS;
;             PG8_LDB(B0, 0, 0); PG8_SCHED; PG8_LDA(At, 0, 0); PG8_STAGE(PG8_SA(1, 1), aT + KS, hA, 0);
;             PG8_WAIT_L(8); PG8_BAR; PG8_WAIT_L(0); PG8_MMA(0, 0, At, B0); PG8_BAR; PG8_SCHED;
;             PG8_LDB(B1, 0, 1); PG8_STAGE(PG8_SB(0, 0), b2, 0, 0);
;             PG8_BAR; PG8_WAIT_L(0); PG8_MMA(0, 1, At, B1); PG8_BAR;
;             PG8_LDA(At, 0, 1); PG8_STAGE(PG8_SA(0, 0), a2, 0, 0);
;             PG8_BAR; PG8_WAIT_L(0); PG8_MMA(1, 0, At, B0); PG8_BAR; PG8_SCHED;
.LBB0_293:
	s_add_u32 s52, s8, 0x8000
	s_addc_u32 s53, s9, 0
	ds_read_b128 v[128:131], v224
	ds_read_b128 v[132:135], v224 offset:1024
	ds_read_b128 v[136:139], v224 offset:2048
	ds_read_b128 v[140:143], v224 offset:3072
	s_add_u32 s54, s8, 0x84000
	s_addc_u32 s55, s9, 0
	s_add_u32 s96, s8, 0x86000
	s_addc_u32 s97, s9, 0
	s_cmp_eq_u32 s95, 4
	s_cselect_b32 s9, s0, s53
	s_cselect_b32 s8, s1, s52
	ds_read_b128 v[144:147], v225
	ds_read_b128 v[148:151], v225 offset:1024
	ds_read_b128 v[152:155], v225 offset:2048
	ds_read_b128 v[156:159], v225 offset:3072
	ds_read_b128 v[160:163], v225 offset:4096
	ds_read_b128 v[164:167], v225 offset:5120
	ds_read_b128 v[168:171], v225 offset:6144
	ds_read_b128 v[172:175], v225 offset:7168
	s_mov_b32 m0, s86
	s_nop 0
	global_load_lds_dwordx4 v221, s[54:55]
	s_mov_b32 m0, s87
	s_nop 0
	global_load_lds_dwordx4 v221, s[96:97]
	s_waitcnt lgkmcnt(8)
	s_waitcnt vmcnt(10)
	s_barrier
	s_waitcnt lgkmcnt(0)
	s_setprio 1
	s_waitcnt lgkmcnt(7)
	v_mfma_f32_16x16x32_bf16 v[124:127], v[128:131], v[144:147], v[124:127]
	v_mfma_f32_16x16x32_bf16 v[120:123], v[136:139], v[144:147], v[120:123]
	s_waitcnt lgkmcnt(5)
	v_mfma_f32_16x16x32_bf16 v[116:119], v[128:131], v[152:155], v[116:119]
	v_mfma_f32_16x16x32_bf16 v[112:115], v[136:139], v[152:155], v[112:115]
	s_waitcnt lgkmcnt(3)
	v_mfma_f32_16x16x32_bf16 v[96:99], v[128:131], v[160:163], v[96:99]
	v_mfma_f32_16x16x32_bf16 v[88:91], v[136:139], v[160:163], v[88:91]
	s_waitcnt lgkmcnt(1)
	v_mfma_f32_16x16x32_bf16 v[80:83], v[128:131], v[168:171], v[80:83]
	v_mfma_f32_16x16x32_bf16 v[72:75], v[136:139], v[168:171], v[72:75]
	v_mfma_f32_16x16x32_bf16 v[124:127], v[132:135], v[148:151], v[124:127]
	v_mfma_f32_16x16x32_bf16 v[120:123], v[140:143], v[148:151], v[120:123]
	v_mfma_f32_16x16x32_bf16 v[116:119], v[132:135], v[156:159], v[116:119]
	v_mfma_f32_16x16x32_bf16 v[112:115], v[140:143], v[156:159], v[112:115]
	v_mfma_f32_16x16x32_bf16 v[96:99], v[132:135], v[164:167], v[96:99]
	v_mfma_f32_16x16x32_bf16 v[88:91], v[140:143], v[164:167], v[88:91]
	s_waitcnt lgkmcnt(0)
	v_mfma_f32_16x16x32_bf16 v[80:83], v[132:135], v[172:175], v[80:83]
	v_mfma_f32_16x16x32_bf16 v[72:75], v[140:143], v[172:175], v[72:75]
	s_setprio 0
	s_barrier
	ds_read_b128 v[176:179], v226
	ds_read_b128 v[180:183], v226 offset:1024
	ds_read_b128 v[184:187], v226 offset:2048
	ds_read_b128 v[188:191], v226 offset:3072
	s_cselect_b32 s54, s47, s93
	s_cselect_b32 s55, s45, s94
	s_mov_b32 m0, s60
	s_nop 0
	global_load_lds_dwordx4 v221, s[54:55]
	s_add_u32 s96, s54, 0x2000
	s_addc_u32 s97, s55, 0
	s_mov_b32 m0, s61
	s_nop 0
	global_load_lds_dwordx4 v221, s[96:97]
	s_waitcnt vmcnt(10)
	s_barrier
	s_waitcnt lgkmcnt(0)
	s_setprio 1
	s_waitcnt lgkmcnt(3)
	v_mfma_f32_16x16x32_bf16 v[108:111], v[176:179], v[144:147], v[108:111]
	s_waitcnt lgkmcnt(1)
	v_mfma_f32_16x16x32_bf16 v[104:107], v[184:187], v[144:147], v[104:107]
	v_mfma_f32_16x16x32_bf16 v[100:103], v[176:179], v[152:155], v[100:103]
	v_mfma_f32_16x16x32_bf16 v[92:95], v[184:187], v[152:155], v[92:95]
	v_mfma_f32_16x16x32_bf16 v[84:87], v[176:179], v[160:163], v[84:87]
	v_mfma_f32_16x16x32_bf16 v[76:79], v[184:187], v[160:163], v[76:79]
	v_mfma_f32_16x16x32_bf16 v[68:71], v[176:179], v[168:171], v[68:71]
	v_mfma_f32_16x16x32_bf16 v[64:67], v[184:187], v[168:171], v[64:67]
	v_mfma_f32_16x16x32_bf16 v[108:111], v[180:183], v[148:151], v[108:111]
	s_waitcnt lgkmcnt(0)
	v_mfma_f32_16x16x32_bf16 v[104:107], v[188:191], v[148:151], v[104:107]
	v_mfma_f32_16x16x32_bf16 v[100:103], v[180:183], v[156:159], v[100:103]
	v_mfma_f32_16x16x32_bf16 v[92:95], v[188:191], v[156:159], v[92:95]
	v_mfma_f32_16x16x32_bf16 v[84:87], v[180:183], v[164:167], v[84:87]
	v_mfma_f32_16x16x32_bf16 v[76:79], v[188:191], v[164:167], v[76:79]
	v_mfma_f32_16x16x32_bf16 v[68:71], v[180:183], v[172:175], v[68:71]
	v_mfma_f32_16x16x32_bf16 v[64:67], v[188:191], v[172:175], v[64:67]
	s_setprio 0
	s_barrier
	ds_read_b128 v[144:147], v225 offset:16384
	ds_read_b128 v[148:151], v225 offset:17408
	ds_read_b128 v[152:155], v225 offset:18432
	ds_read_b128 v[156:159], v225 offset:19456
	ds_read_b128 v[160:163], v225 offset:20480
	ds_read_b128 v[164:167], v225 offset:21504
	ds_read_b128 v[168:171], v225 offset:22528
	ds_read_b128 v[172:175], v225 offset:23552
	s_mov_b32 m0, s59
	s_nop 0
	global_load_lds_dwordx4 v221, s[8:9]
	s_add_u32 s96, s8, 0x2000
	s_addc_u32 s97, s9, 0
	s_mov_b32 m0, s62
	s_nop 0
	global_load_lds_dwordx4 v221, s[96:97]
	s_barrier
	s_waitcnt lgkmcnt(0)
	s_setprio 1
	s_waitcnt lgkmcnt(7)
	v_mfma_f32_16x16x32_bf16 v[60:63], v[128:131], v[144:147], v[60:63]
	v_mfma_f32_16x16x32_bf16 v[56:59], v[136:139], v[144:147], v[56:59]
	s_waitcnt lgkmcnt(5)
	v_mfma_f32_16x16x32_bf16 v[48:51], v[128:131], v[152:155], v[48:51]
	v_mfma_f32_16x16x32_bf16 v[40:43], v[136:139], v[152:155], v[40:43]
	s_waitcnt lgkmcnt(3)
	v_mfma_f32_16x16x32_bf16 v[32:35], v[128:131], v[160:163], v[32:35]
	v_mfma_f32_16x16x32_bf16 v[24:27], v[136:139], v[160:163], v[24:27]
	s_waitcnt lgkmcnt(1)
	v_mfma_f32_16x16x32_bf16 v[16:19], v[128:131], v[168:171], v[16:19]
	v_mfma_f32_16x16x32_bf16 v[8:11], v[136:139], v[168:171], v[8:11]
	v_mfma_f32_16x16x32_bf16 v[60:63], v[132:135], v[148:151], v[60:63]
	v_mfma_f32_16x16x32_bf16 v[56:59], v[140:143], v[148:151], v[56:59]
	v_mfma_f32_16x16x32_bf16 v[48:51], v[132:135], v[156:159], v[48:51]
	v_mfma_f32_16x16x32_bf16 v[40:43], v[140:143], v[156:159], v[40:43]
	v_mfma_f32_16x16x32_bf16 v[32:35], v[132:135], v[164:167], v[32:35]
	v_mfma_f32_16x16x32_bf16 v[24:27], v[140:143], v[164:167], v[24:27]
	s_waitcnt lgkmcnt(0)
	v_mfma_f32_16x16x32_bf16 v[16:19], v[132:135], v[172:175], v[16:19]
	v_mfma_f32_16x16x32_bf16 v[8:11], v[140:143], v[172:175], v[8:11]
	s_setprio 0
	s_barrier
; #define PG8_STAGE(bufoff, gbase, hoff, imm) do { _Pragma("unroll") for (int _i = 0; _i < 2; ++_i) { \
;         asm volatile("s_mov_b32 m0, %0\n\ts_nop 0\n\tglobal_load_lds_dwordx4 %1, %2" \
;             :: "s"(lds0 + (unsigned)((bufoff) + _i * 8192)), "v"(voff0), "s"((const char*)(gbase) + (size_t)(hoff) + (size_t)(_i * 8192)) : "memory"); } } while (0)
; #define PG8_LDA(dst, b, h) do { _Pragma("unroll") for (int m = 0; m < 4; ++m) _Pragma("unroll") for (int k = 0; k < 2; ++k) dst[m][k] = *(const LAS bf16x8*)(lds + PG8_SA(b, h) + aoff + m * 2048 + k * 1024); } while (0)
; #define PG8_LDB(dst, b, h) do { _Pragma("unroll") for (int n = 0; n < 2; ++n) _Pragma("unroll") for (int k = 0; k < 2; ++k) dst[n][k] = *(const LAS bf16x8*)(lds + PG8_SB(b, h) + boff + n * 2048 + k * 1024); } while (0)
; #define PG8_MMA(ai, bj, At, Bt) do { __builtin_amdgcn_s_setprio(1); _Pragma("unroll") for (int m = 0; m < 4; ++m) _Pragma("unroll") for (int n = 0; n < 2; ++n) _Pragma("unroll") for (int k = 0; k < 2; ++k) \
;         acc[ai][bj][m][n] = __builtin_amdgcn_mfma_f32_16x16x32_bf16(Bt[n][k], At[m][k], acc[ai][bj][m][n], 0, 0, 0); __builtin_amdgcn_s_setprio(0); } while (0)
; #define PG8_WAIT_V(n) asm volatile("s_waitcnt vmcnt(" #n ")" ::: "memory")
; #define PG8_WAIT_L(n) asm volatile("s_waitcnt lgkmcnt(" #n ")" ::: "memory")
; #define PG8_BAR __builtin_amdgcn_s_barrier()
; #define PG8_SCHED __builtin_amdgcn_sched_barrier(0)
; template <class Epi>
; __device__ __forceinline__ void gemm_phase(LAS unsigned char* lds, const Gemm g, const StaticOrder& S, const Epi& E) {
;     ...
;             PG8_STAGE(PG8_SB(0, 1), b2, hB, 0);
;             PG8_WAIT_V(6); PG8_BAR; PG8_MMA(1, 1, At, B1); PG8_BAR;
;             PG8_LDB(B0, 1, 0); PG8_SCHED; PG8_LDA(At, 1, 0); PG8_STAGE(PG8_SA(0, 1), a2, hA, 0);
;             PG8_WAIT_L(8); PG8_BAR; PG8_WAIT_L(0); PG8_MMA(0, 0, At, B0); PG8_BAR; PG8_SCHED;
;             PG8_LDB(B1, 1, 1); PG8_STAGE(PG8_SB(1, 0), b2 + KS, 0, 0);
;             PG8_BAR; PG8_WAIT_L(0); PG8_MMA(0, 1, At, B1); PG8_BAR;
	s_add_u32 s96, s54, 0x20000
	s_addc_u32 s97, s55, 0
	s_mov_b32 m0, s63
	s_nop 0
	global_load_lds_dwordx4 v221, s[96:97]
	s_add_u32 s96, s54, 0x22000
	s_addc_u32 s97, s55, 0
	s_mov_b32 m0, s64
	s_nop 0
	global_load_lds_dwordx4 v221, s[96:97]
	s_waitcnt vmcnt(10)
	s_barrier
	s_setprio 1
	v_mfma_f32_16x16x32_bf16 v[52:55], v[176:179], v[144:147], v[52:55]
	v_mfma_f32_16x16x32_bf16 v[44:47], v[184:187], v[144:147], v[44:47]
	v_mfma_f32_16x16x32_bf16 v[36:39], v[176:179], v[152:155], v[36:39]
	v_mfma_f32_16x16x32_bf16 v[28:31], v[184:187], v[152:155], v[28:31]
	v_mfma_f32_16x16x32_bf16 v[20:23], v[176:179], v[160:163], v[20:23]
	v_mfma_f32_16x16x32_bf16 v[12:15], v[184:187], v[160:163], v[12:15]
	v_mfma_f32_16x16x32_bf16 v[4:7], v[176:179], v[168:171], v[4:7]
	v_mfma_f32_16x16x32_bf16 v[0:3], v[184:187], v[168:171], v[0:3]
	v_mfma_f32_16x16x32_bf16 v[52:55], v[180:183], v[148:151], v[52:55]
	v_mfma_f32_16x16x32_bf16 v[44:47], v[188:191], v[148:151], v[44:47]
	v_mfma_f32_16x16x32_bf16 v[36:39], v[180:183], v[156:159], v[36:39]
	v_mfma_f32_16x16x32_bf16 v[28:31], v[188:191], v[156:159], v[28:31]
	v_mfma_f32_16x16x32_bf16 v[20:23], v[180:183], v[164:167], v[20:23]
	v_mfma_f32_16x16x32_bf16 v[12:15], v[188:191], v[164:167], v[12:15]
	v_mfma_f32_16x16x32_bf16 v[4:7], v[180:183], v[172:175], v[4:7]
	v_mfma_f32_16x16x32_bf16 v[0:3], v[188:191], v[172:175], v[0:3]
	s_setprio 0
	s_barrier
	ds_read_b128 v[128:131], v227
	ds_read_b128 v[132:135], v227 offset:1024
	ds_read_b128 v[136:139], v227 offset:2048
	ds_read_b128 v[140:143], v227 offset:3072
	ds_read_b128 v[144:147], v225 offset:32768
	ds_read_b128 v[148:151], v225 offset:33792
	ds_read_b128 v[152:155], v225 offset:34816
	ds_read_b128 v[156:159], v225 offset:35840
	ds_read_b128 v[160:163], v225 offset:36864
	ds_read_b128 v[164:167], v225 offset:37888
	ds_read_b128 v[168:171], v225 offset:38912
	ds_read_b128 v[172:175], v225 offset:39936
	s_add_u32 s96, s8, 0x80000
	s_addc_u32 s97, s9, 0
	s_mov_b32 m0, s65
	s_nop 0
	global_load_lds_dwordx4 v221, s[96:97]
	s_add_u32 s96, s8, 0x82000
	s_addc_u32 s97, s9, 0
	s_mov_b32 m0, s66
	s_nop 0
	global_load_lds_dwordx4 v221, s[96:97]
	s_waitcnt lgkmcnt(8)
	s_waitcnt vmcnt(10)
	s_barrier
	s_waitcnt lgkmcnt(0)
	s_setprio 1
	s_waitcnt lgkmcnt(7)
	v_mfma_f32_16x16x32_bf16 v[124:127], v[128:131], v[144:147], v[124:127]
	v_mfma_f32_16x16x32_bf16 v[120:123], v[136:139], v[144:147], v[120:123]
	s_waitcnt lgkmcnt(5)
	v_mfma_f32_16x16x32_bf16 v[116:119], v[128:131], v[152:155], v[116:119]
	v_mfma_f32_16x16x32_bf16 v[112:115], v[136:139], v[152:155], v[112:115]
	s_waitcnt lgkmcnt(3)
	v_mfma_f32_16x16x32_bf16 v[96:99], v[128:131], v[160:163], v[96:99]
	v_mfma_f32_16x16x32_bf16 v[88:91], v[136:139], v[160:163], v[88:91]
	s_waitcnt lgkmcnt(1)
	v_mfma_f32_16x16x32_bf16 v[80:83], v[128:131], v[168:171], v[80:83]
	v_mfma_f32_16x16x32_bf16 v[72:75], v[136:139], v[168:171], v[72:75]
	v_mfma_f32_16x16x32_bf16 v[124:127], v[132:135], v[148:151], v[124:127]
	v_mfma_f32_16x16x32_bf16 v[120:123], v[140:143], v[148:151], v[120:123]
	v_mfma_f32_16x16x32_bf16 v[116:119], v[132:135], v[156:159], v[116:119]
	v_mfma_f32_16x16x32_bf16 v[112:115], v[140:143], v[156:159], v[112:115]
	v_mfma_f32_16x16x32_bf16 v[96:99], v[132:135], v[164:167], v[96:99]
	v_mfma_f32_16x16x32_bf16 v[88:91], v[140:143], v[164:167], v[88:91]
	s_waitcnt lgkmcnt(0)
	v_mfma_f32_16x16x32_bf16 v[80:83], v[132:135], v[172:175], v[80:83]
	v_mfma_f32_16x16x32_bf16 v[72:75], v[140:143], v[172:175], v[72:75]
	s_setprio 0
	s_barrier
	ds_read_b128 v[176:179], v228
	ds_read_b128 v[180:183], v228 offset:1024
	ds_read_b128 v[184:187], v228 offset:2048
	ds_read_b128 v[188:191], v228 offset:3072
	s_add_u32 s96, s54, 0x4000
	s_addc_u32 s97, s55, 0
	s_mov_b32 m0, s69
	s_nop 0
	global_load_lds_dwordx4 v221, s[96:97]
	s_add_u32 s96, s54, 0x6000
	s_addc_u32 s97, s55, 0
	s_mov_b32 m0, s70
	s_nop 0
	global_load_lds_dwordx4 v221, s[96:97]
	s_waitcnt vmcnt(10)
	s_barrier
	s_waitcnt lgkmcnt(0)
	s_setprio 1
	s_waitcnt lgkmcnt(3)
	v_mfma_f32_16x16x32_bf16 v[108:111], v[176:179], v[144:147], v[108:111]
	s_waitcnt lgkmcnt(1)
	v_mfma_f32_16x16x32_bf16 v[104:107], v[184:187], v[144:147], v[104:107]
	v_mfma_f32_16x16x32_bf16 v[100:103], v[176:179], v[152:155], v[100:103]
	v_mfma_f32_16x16x32_bf16 v[92:95], v[184:187], v[152:155], v[92:95]
	v_mfma_f32_16x16x32_bf16 v[84:87], v[176:179], v[160:163], v[84:87]
	v_mfma_f32_16x16x32_bf16 v[76:79], v[184:187], v[160:163], v[76:79]
	v_mfma_f32_16x16x32_bf16 v[68:71], v[176:179], v[168:171], v[68:71]
	v_mfma_f32_16x16x32_bf16 v[64:67], v[184:187], v[168:171], v[64:67]
	v_mfma_f32_16x16x32_bf16 v[108:111], v[180:183], v[148:151], v[108:111]
	s_waitcnt lgkmcnt(0)
	v_mfma_f32_16x16x32_bf16 v[104:107], v[188:191], v[148:151], v[104:107]
	v_mfma_f32_16x16x32_bf16 v[100:103], v[180:183], v[156:159], v[100:103]
	v_mfma_f32_16x16x32_bf16 v[92:95], v[188:191], v[156:159], v[92:95]
	v_mfma_f32_16x16x32_bf16 v[84:87], v[180:183], v[164:167], v[84:87]
	v_mfma_f32_16x16x32_bf16 v[76:79], v[188:191], v[164:167], v[76:79]
	v_mfma_f32_16x16x32_bf16 v[68:71], v[180:183], v[172:175], v[68:71]
	v_mfma_f32_16x16x32_bf16 v[64:67], v[188:191], v[172:175], v[64:67]
	s_setprio 0
	s_barrier
; #define PG8_STAGE(bufoff, gbase, hoff, imm) do { _Pragma("unroll") for (int _i = 0; _i < 2; ++_i) { \
;         asm volatile("s_mov_b32 m0, %0\n\ts_nop 0\n\tglobal_load_lds_dwordx4 %1, %2" \
;             :: "s"(lds0 + (unsigned)((bufoff) + _i * 8192)), "v"(voff0), "s"((const char*)(gbase) + (size_t)(hoff) + (size_t)(_i * 8192)) : "memory"); } } while (0)
; #define PG8_LDA(dst, b, h) do { _Pragma("unroll") for (int m = 0; m < 4; ++m) _Pragma("unroll") for (int k = 0; k < 2; ++k) dst[m][k] = *(const LAS bf16x8*)(lds + PG8_SA(b, h) + aoff + m * 2048 + k * 1024); } while (0)
; #define PG8_MMA(ai, bj, At, Bt) do { __builtin_amdgcn_s_setprio(1); _Pragma("unroll") for (int m = 0; m < 4; ++m) _Pragma("unroll") for (int n = 0; n < 2; ++n) _Pragma("unroll") for (int k = 0; k < 2; ++k) \
;         acc[ai][bj][m][n] = __builtin_amdgcn_mfma_f32_16x16x32_bf16(Bt[n][k], At[m][k], acc[ai][bj][m][n], 0, 0, 0); __builtin_amdgcn_s_setprio(0); } while (0)
; #define PG8_WAIT_V(n) asm volatile("s_waitcnt vmcnt(" #n ")" ::: "memory")
; #define PG8_WAIT_L(n) asm volatile("s_waitcnt lgkmcnt(" #n ")" ::: "memory")
; #define PG8_BAR __builtin_amdgcn_s_barrier()
; #define PG8_SCHED __builtin_amdgcn_sched_barrier(0)
; template <class Epi>
; __device__ __forceinline__ void gemm_phase(LAS unsigned char* lds, const Gemm g, const StaticOrder& S, const Epi& E) {
;     ...
;             PG8_LDA(At, 1, 1); PG8_STAGE(PG8_SA(1, 0), a2 + KS, 0, 0);
;             PG8_BAR; PG8_WAIT_L(0); PG8_MMA(1, 0, At, B0); PG8_BAR; PG8_SCHED;
;             PG8_STAGE(PG8_SB(1, 1), b2 + KS, hB, 0);
;             PG8_WAIT_V(6); PG8_BAR; PG8_MMA(1, 1, At, B1); PG8_BAR;
;     __device__ __forceinline__ void operator()(f32x4 (&acc)[2][2][4][2], const Unit& u, int wr, int wc, int fr, int fq, LAS unsigned char*) const {
;         const int b = u.pm >> 6;
;         const int col0 = u.pn * BM + wc * 32 + 8 * fq;
;         const size_t off0 = (size_t)(u.pm * BM + wr * 64 + fr) * D + col0;
;         f32x4 sc[2][2];
; #pragma unroll
;         for (int bj = 0; bj < 2; ++bj)
; #pragma unroll
;             for (int n = 0; n < 2; ++n) { f32x4 gt = *(const f32x4*)(gate + (size_t)b * MODW + col0 + bj * HALF + n * 4); sc[bj][n] = gt + 1.0f;
;                 if (cs) sc[bj][n] *= *(const f32x4*)(cs + col0 + bj * HALF + n * 4); }
	ds_read_b128 v[144:147], v225 offset:49152
	ds_read_b128 v[148:151], v225 offset:50176
	ds_read_b128 v[152:155], v225 offset:51200
	ds_read_b128 v[156:159], v225 offset:52224
	ds_read_b128 v[160:163], v225 offset:53248
	ds_read_b128 v[164:167], v225 offset:54272
	ds_read_b128 v[168:171], v225 offset:55296
	ds_read_b128 v[172:175], v225 offset:56320
	s_add_u32 s96, s8, 0x4000
	s_addc_u32 s97, s9, 0
	s_mov_b32 m0, s71
	s_nop 0
	global_load_lds_dwordx4 v221, s[96:97]
	s_add_u32 s8, s8, 0x6000
	s_addc_u32 s9, s9, 0
	s_mov_b32 m0, s72
	s_nop 0
	global_load_lds_dwordx4 v221, s[8:9]
	s_barrier
	s_waitcnt lgkmcnt(0)
	s_setprio 1
	s_waitcnt lgkmcnt(7)
	v_mfma_f32_16x16x32_bf16 v[60:63], v[128:131], v[144:147], v[60:63]
	v_mfma_f32_16x16x32_bf16 v[56:59], v[136:139], v[144:147], v[56:59]
	s_waitcnt lgkmcnt(5)
	v_mfma_f32_16x16x32_bf16 v[48:51], v[128:131], v[152:155], v[48:51]
	v_mfma_f32_16x16x32_bf16 v[40:43], v[136:139], v[152:155], v[40:43]
	s_waitcnt lgkmcnt(3)
	v_mfma_f32_16x16x32_bf16 v[32:35], v[128:131], v[160:163], v[32:35]
	v_mfma_f32_16x16x32_bf16 v[24:27], v[136:139], v[160:163], v[24:27]
	s_waitcnt lgkmcnt(1)
	v_mfma_f32_16x16x32_bf16 v[16:19], v[128:131], v[168:171], v[16:19]
	v_mfma_f32_16x16x32_bf16 v[8:11], v[136:139], v[168:171], v[8:11]
	v_mfma_f32_16x16x32_bf16 v[60:63], v[132:135], v[148:151], v[60:63]
	v_mfma_f32_16x16x32_bf16 v[56:59], v[140:143], v[148:151], v[56:59]
	v_mfma_f32_16x16x32_bf16 v[48:51], v[132:135], v[156:159], v[48:51]
	v_mfma_f32_16x16x32_bf16 v[40:43], v[140:143], v[156:159], v[40:43]
	v_mfma_f32_16x16x32_bf16 v[32:35], v[132:135], v[164:167], v[32:35]
	v_mfma_f32_16x16x32_bf16 v[24:27], v[140:143], v[164:167], v[24:27]
	s_waitcnt lgkmcnt(0)
	v_mfma_f32_16x16x32_bf16 v[16:19], v[132:135], v[172:175], v[16:19]
	v_mfma_f32_16x16x32_bf16 v[8:11], v[140:143], v[172:175], v[8:11]
	s_setprio 0
	s_barrier
	s_add_u32 s8, s54, 0x24000
	s_addc_u32 s9, s55, 0
	s_mov_b32 m0, s73
	s_nop 0
	global_load_lds_dwordx4 v221, s[8:9]
	s_add_u32 s8, s54, 0x26000
	s_addc_u32 s9, s55, 0
	s_mov_b32 m0, s85
	s_nop 0
	global_load_lds_dwordx4 v221, s[8:9]
	s_waitcnt vmcnt(10)
	s_barrier
	s_setprio 1
	v_mfma_f32_16x16x32_bf16 v[52:55], v[176:179], v[144:147], v[52:55]
	v_mfma_f32_16x16x32_bf16 v[44:47], v[184:187], v[144:147], v[44:47]
	v_mfma_f32_16x16x32_bf16 v[36:39], v[176:179], v[152:155], v[36:39]
	v_mfma_f32_16x16x32_bf16 v[28:31], v[184:187], v[152:155], v[28:31]
	v_mfma_f32_16x16x32_bf16 v[20:23], v[176:179], v[160:163], v[20:23]
	v_mfma_f32_16x16x32_bf16 v[12:15], v[184:187], v[160:163], v[12:15]
	v_mfma_f32_16x16x32_bf16 v[4:7], v[176:179], v[168:171], v[4:7]
	v_mfma_f32_16x16x32_bf16 v[0:3], v[184:187], v[168:171], v[0:3]
	v_mfma_f32_16x16x32_bf16 v[52:55], v[180:183], v[148:151], v[52:55]
	v_mfma_f32_16x16x32_bf16 v[44:47], v[188:191], v[148:151], v[44:47]
	v_mfma_f32_16x16x32_bf16 v[36:39], v[180:183], v[156:159], v[36:39]
	v_mfma_f32_16x16x32_bf16 v[28:31], v[188:191], v[156:159], v[28:31]
	v_mfma_f32_16x16x32_bf16 v[20:23], v[180:183], v[164:167], v[20:23]
	v_mfma_f32_16x16x32_bf16 v[12:15], v[188:191], v[164:167], v[12:15]
	v_mfma_f32_16x16x32_bf16 v[4:7], v[180:183], v[172:175], v[4:7]
	v_mfma_f32_16x16x32_bf16 v[0:3], v[188:191], v[172:175], v[0:3]
	s_setprio 0
	s_add_i32 s95, s95, 2
	s_add_u32 s93, s93, 0x8000
	s_addc_u32 s94, s94, 0
	s_cmp_gt_u32 s95, 5
	s_mov_b64 s[8:9], s[52:53]
	s_barrier
	s_cbranch_scc0 .LBB0_293
	s_ashr_i32 s0, s89, 6
	v_lshl_or_b32 v128, s92, 8, v223
	s_mul_hi_i32 s1, s0, 0xc000
	s_mul_i32 s0, s0, 0xc000
	v_ashrrev_i32_e32 v129, 31, v128
	s_add_u32 s0, s67, s0
	s_addc_u32 s1, s68, s1
	v_lshlrev_b64 v[130:131], 2, v[128:129]
	v_lshl_add_u64 v[132:133], s[0:1], 0, v[130:131]
	global_load_dwordx4 v[134:137], v[132:133], off
	v_cndmask_b32_e64 v138, 0, 1, s[42:43]
	v_cmp_ne_u32_e64 s[8:9], 1, v138
	v_lshl_add_u64 v[130:131], s[38:39], 0, v[130:131]
	s_andn2_b64 vcc, exec, s[42:43]
	s_waitcnt vmcnt(0)
	v_pk_add_f32 v[198:199], v[136:137], 1.0 op_sel_hi:[1,0]
	v_pk_add_f32 v[196:197], v[134:135], 1.0 op_sel_hi:[1,0]
	s_cbranch_vccnz .LBB0_296
	global_load_dwordx4 v[134:137], v[130:131], off
	s_waitcnt vmcnt(0)
	v_pk_mul_f32 v[198:199], v[198:199], v[136:137]
	v_pk_mul_f32 v[196:197], v[196:197], v[134:135]

; #define PG8_STAGE(bufoff, gbase, hoff, imm) do { _Pragma("unroll") for (int _i = 0; _i < 2; ++_i) { \
;         asm volatile("s_mov_b32 m0, %0\n\ts_nop 0\n\tglobal_load_lds_dwordx4 %1, %2" \
;             :: "s"(lds0 + (unsigned)((bufoff) + _i * 8192)), "v"(voff0), "s"((const char*)(gbase) + (size_t)(hoff) + (size_t)(_i * 8192)) : "memory"); } } while (0)
; #define PG8_LDA(dst, b, h) do { _Pragma("unroll") for (int m = 0; m < 4; ++m) _Pragma("unroll") for (int k = 0; k < 2; ++k) dst[m][k] = *(const LAS bf16x8*)(lds + PG8_SA(b, h) + aoff + m * 2048 + k * 1024); } while (0)
; #define PG8_LDB(dst, b, h) do { _Pragma("unroll") for (int n = 0; n < 2; ++n) _Pragma("unroll") for (int k = 0; k < 2; ++k) dst[n][k] = *(const LAS bf16x8*)(lds + PG8_SB(b, h) + boff + n * 2048 + k * 1024); } while (0)
; #define PG8_MMA(ai, bj, At, Bt) do { __builtin_amdgcn_s_setprio(1); _Pragma("unroll") for (int m = 0; m < 4; ++m) _Pragma("unroll") for (int n = 0; n < 2; ++n) _Pragma("unroll") for (int k = 0; k < 2; ++k) \
;         acc[ai][bj][m][n] = __builtin_amdgcn_mfma_f32_16x16x32_bf16(Bt[n][k], At[m][k], acc[ai][bj][m][n], 0, 0, 0); __builtin_amdgcn_s_setprio(0); } while (0)
; #define PG8_WAIT_L(n) asm volatile("s_waitcnt lgkmcnt(" #n ")" ::: "memory")
; #define PG8_BAR __builtin_amdgcn_s_barrier()
; #define PG8_SCHED __builtin_amdgcn_sched_barrier(0)
; template <class Epi>
; __device__ __forceinline__ void gemm_phase(LAS unsigned char* lds, const Gemm g, const StaticOrder& S, const Epi& E) {
;     ...
;         for (int t = 0; t < nt; t += 2) {
;             const bool last = (t == nt - 2);
;             if (last) E.pre(cur, wid, lane, (unsigned)(size_t)(lds + STAGE_BYTES));
;             const char* aT = cA + (size_t)t * KS;
;             const char* a2 = last ? nA : aT + 2 * KS; const char* b2 = last ? nB : cB + (size_t)(t + 2) * KS;
;             PG8_LDB(B0, 0, 0); PG8_SCHED; PG8_LDA(At, 0, 0); PG8_STAGE(PG8_SA(1, 1), aT + KS, hA, 0);
;             PG8_WAIT_L(8); PG8_BAR; PG8_WAIT_L(0); PG8_MMA(0, 0, At, B0); PG8_BAR; PG8_SCHED;
;             PG8_LDB(B1, 0, 1); PG8_STAGE(PG8_SB(0, 0), b2, 0, 0);
;             PG8_BAR; PG8_WAIT_L(0); PG8_MMA(0, 1, At, B1); PG8_BAR;
;             PG8_LDA(At, 0, 1); PG8_STAGE(PG8_SA(0, 0), a2, 0, 0);
;             PG8_BAR; PG8_WAIT_L(0); PG8_MMA(1, 0, At, B0); PG8_BAR; PG8_SCHED;
.LBB0_434:
	s_add_u32 s56, s54, 0x8000
	v_add_u32_e32 v128, 0x10000, v133
	s_addc_u32 s57, s55, 0
	ds_read_b128 v[136:139], v128
	ds_read_b128 v[140:143], v128 offset:1024
	ds_read_b128 v[144:147], v128 offset:2048
	ds_read_b128 v[148:151], v128 offset:3072
	s_add_u32 s58, s54, 0x84000
	s_addc_u32 s59, s55, 0
	s_add_u32 s66, s54, 0x86000
	s_addc_u32 s67, s55, 0
	s_cmp_eq_u32 s65, 28
	s_cselect_b32 s55, s0, s57
	s_cselect_b32 s54, s1, s56
	ds_read_b128 v[152:155], v134
	ds_read_b128 v[156:159], v134 offset:1024
	ds_read_b128 v[160:163], v134 offset:2048
	ds_read_b128 v[164:167], v134 offset:3072
	ds_read_b128 v[168:171], v134 offset:4096
	ds_read_b128 v[172:175], v134 offset:5120
	ds_read_b128 v[176:179], v134 offset:6144
	ds_read_b128 v[180:183], v134 offset:7168
	s_mov_b32 m0, s50
	s_nop 0
	global_load_lds_dwordx4 v130, s[58:59]
	s_mov_b32 m0, s51
	s_nop 0
	global_load_lds_dwordx4 v130, s[66:67]
	s_waitcnt lgkmcnt(8)
	s_waitcnt vmcnt(10)
	s_barrier
	s_waitcnt lgkmcnt(0)
	s_setprio 1
	s_waitcnt lgkmcnt(7)
	v_mfma_f32_16x16x32_bf16 v[124:127], v[136:139], v[152:155], v[124:127]
	v_mfma_f32_16x16x32_bf16 v[120:123], v[144:147], v[152:155], v[120:123]
	s_waitcnt lgkmcnt(5)
	v_mfma_f32_16x16x32_bf16 v[116:119], v[136:139], v[160:163], v[116:119]
	v_mfma_f32_16x16x32_bf16 v[108:111], v[144:147], v[160:163], v[108:111]
	s_waitcnt lgkmcnt(3)
	v_mfma_f32_16x16x32_bf16 v[100:103], v[136:139], v[168:171], v[100:103]
	v_mfma_f32_16x16x32_bf16 v[92:95], v[144:147], v[168:171], v[92:95]
	s_waitcnt lgkmcnt(1)
	v_mfma_f32_16x16x32_bf16 v[84:87], v[136:139], v[176:179], v[84:87]
	v_mfma_f32_16x16x32_bf16 v[76:79], v[144:147], v[176:179], v[76:79]
	v_mfma_f32_16x16x32_bf16 v[124:127], v[140:143], v[156:159], v[124:127]
	v_mfma_f32_16x16x32_bf16 v[120:123], v[148:151], v[156:159], v[120:123]
	v_mfma_f32_16x16x32_bf16 v[116:119], v[140:143], v[164:167], v[116:119]
	v_mfma_f32_16x16x32_bf16 v[108:111], v[148:151], v[164:167], v[108:111]
	v_mfma_f32_16x16x32_bf16 v[100:103], v[140:143], v[172:175], v[100:103]
	v_mfma_f32_16x16x32_bf16 v[92:95], v[148:151], v[172:175], v[92:95]
	s_waitcnt lgkmcnt(0)
	v_mfma_f32_16x16x32_bf16 v[84:87], v[140:143], v[180:183], v[84:87]
	v_mfma_f32_16x16x32_bf16 v[76:79], v[148:151], v[180:183], v[76:79]
	s_setprio 0
	s_barrier
	v_add_u32_e32 v128, 0x14000, v133
	ds_read_b128 v[184:187], v128
	ds_read_b128 v[200:203], v128 offset:1024
	ds_read_b128 v[204:207], v128 offset:2048
	ds_read_b128 v[208:211], v128 offset:3072
	s_cselect_b32 s58, s9, s63
	s_cselect_b32 s59, s7, s64
	s_mov_b32 m0, s26
	s_nop 0
	global_load_lds_dwordx4 v130, s[58:59]
	s_add_u32 s66, s58, 0x2000
	s_addc_u32 s67, s59, 0
	s_mov_b32 m0, s27
	s_nop 0
	global_load_lds_dwordx4 v130, s[66:67]
	s_waitcnt vmcnt(10)
	s_barrier
	s_waitcnt lgkmcnt(0)
	s_setprio 1
	s_waitcnt lgkmcnt(3)
	v_mfma_f32_16x16x32_bf16 v[112:115], v[184:187], v[152:155], v[112:115]
	s_waitcnt lgkmcnt(1)
	v_mfma_f32_16x16x32_bf16 v[104:107], v[204:207], v[152:155], v[104:107]
	v_mfma_f32_16x16x32_bf16 v[96:99], v[184:187], v[160:163], v[96:99]
	v_mfma_f32_16x16x32_bf16 v[88:91], v[204:207], v[160:163], v[88:91]
	v_mfma_f32_16x16x32_bf16 v[80:83], v[184:187], v[168:171], v[80:83]
	v_mfma_f32_16x16x32_bf16 v[72:75], v[204:207], v[168:171], v[72:75]
	v_mfma_f32_16x16x32_bf16 v[68:71], v[184:187], v[176:179], v[68:71]
	v_mfma_f32_16x16x32_bf16 v[64:67], v[204:207], v[176:179], v[64:67]
	v_mfma_f32_16x16x32_bf16 v[112:115], v[200:203], v[156:159], v[112:115]
	s_waitcnt lgkmcnt(0)
	v_mfma_f32_16x16x32_bf16 v[104:107], v[208:211], v[156:159], v[104:107]
	v_mfma_f32_16x16x32_bf16 v[96:99], v[200:203], v[164:167], v[96:99]
	v_mfma_f32_16x16x32_bf16 v[88:91], v[208:211], v[164:167], v[88:91]
	v_mfma_f32_16x16x32_bf16 v[80:83], v[200:203], v[172:175], v[80:83]
	v_mfma_f32_16x16x32_bf16 v[72:75], v[208:211], v[172:175], v[72:75]
	v_mfma_f32_16x16x32_bf16 v[68:71], v[200:203], v[180:183], v[68:71]
	v_mfma_f32_16x16x32_bf16 v[64:67], v[208:211], v[180:183], v[64:67]
	s_setprio 0
	s_barrier
	ds_read_b128 v[152:155], v134 offset:16384
	ds_read_b128 v[156:159], v134 offset:17408
	ds_read_b128 v[160:163], v134 offset:18432
	ds_read_b128 v[164:167], v134 offset:19456
	ds_read_b128 v[168:171], v134 offset:20480
	ds_read_b128 v[172:175], v134 offset:21504
	ds_read_b128 v[176:179], v134 offset:22528
	ds_read_b128 v[180:183], v134 offset:23552
	s_mov_b32 m0, s25
	s_nop 0
	global_load_lds_dwordx4 v130, s[54:55]
	s_add_u32 s66, s54, 0x2000
	s_addc_u32 s67, s55, 0
	s_mov_b32 m0, s28
	s_nop 0
	global_load_lds_dwordx4 v130, s[66:67]
	s_barrier
	s_waitcnt lgkmcnt(0)
	s_setprio 1
	s_waitcnt lgkmcnt(7)
	v_mfma_f32_16x16x32_bf16 v[60:63], v[136:139], v[152:155], v[60:63]
	v_mfma_f32_16x16x32_bf16 v[56:59], v[144:147], v[152:155], v[56:59]
	s_waitcnt lgkmcnt(5)
	v_mfma_f32_16x16x32_bf16 v[52:55], v[136:139], v[160:163], v[52:55]
	v_mfma_f32_16x16x32_bf16 v[44:47], v[144:147], v[160:163], v[44:47]
	s_waitcnt lgkmcnt(3)
	v_mfma_f32_16x16x32_bf16 v[36:39], v[136:139], v[168:171], v[36:39]
	v_mfma_f32_16x16x32_bf16 v[28:31], v[144:147], v[168:171], v[28:31]
	s_waitcnt lgkmcnt(1)
	v_mfma_f32_16x16x32_bf16 v[20:23], v[136:139], v[176:179], v[20:23]
	v_mfma_f32_16x16x32_bf16 v[12:15], v[144:147], v[176:179], v[12:15]
	v_mfma_f32_16x16x32_bf16 v[60:63], v[140:143], v[156:159], v[60:63]
	v_mfma_f32_16x16x32_bf16 v[56:59], v[148:151], v[156:159], v[56:59]
	v_mfma_f32_16x16x32_bf16 v[52:55], v[140:143], v[164:167], v[52:55]
	v_mfma_f32_16x16x32_bf16 v[44:47], v[148:151], v[164:167], v[44:47]
	v_mfma_f32_16x16x32_bf16 v[36:39], v[140:143], v[172:175], v[36:39]
	v_mfma_f32_16x16x32_bf16 v[28:31], v[148:151], v[172:175], v[28:31]
	s_waitcnt lgkmcnt(0)
	v_mfma_f32_16x16x32_bf16 v[20:23], v[140:143], v[180:183], v[20:23]
	v_mfma_f32_16x16x32_bf16 v[12:15], v[148:151], v[180:183], v[12:15]
	s_setprio 0
	s_barrier
; #define PG8_STAGE(bufoff, gbase, hoff, imm) do { _Pragma("unroll") for (int _i = 0; _i < 2; ++_i) { \
;         asm volatile("s_mov_b32 m0, %0\n\ts_nop 0\n\tglobal_load_lds_dwordx4 %1, %2" \
;             :: "s"(lds0 + (unsigned)((bufoff) + _i * 8192)), "v"(voff0), "s"((const char*)(gbase) + (size_t)(hoff) + (size_t)(_i * 8192)) : "memory"); } } while (0)
; #define PG8_LDA(dst, b, h) do { _Pragma("unroll") for (int m = 0; m < 4; ++m) _Pragma("unroll") for (int k = 0; k < 2; ++k) dst[m][k] = *(const LAS bf16x8*)(lds + PG8_SA(b, h) + aoff + m * 2048 + k * 1024); } while (0)
; #define PG8_LDB(dst, b, h) do { _Pragma("unroll") for (int n = 0; n < 2; ++n) _Pragma("unroll") for (int k = 0; k < 2; ++k) dst[n][k] = *(const LAS bf16x8*)(lds + PG8_SB(b, h) + boff + n * 2048 + k * 1024); } while (0)
; #define PG8_MMA(ai, bj, At, Bt) do { __builtin_amdgcn_s_setprio(1); _Pragma("unroll") for (int m = 0; m < 4; ++m) _Pragma("unroll") for (int n = 0; n < 2; ++n) _Pragma("unroll") for (int k = 0; k < 2; ++k) \
;         acc[ai][bj][m][n] = __builtin_amdgcn_mfma_f32_16x16x32_bf16(Bt[n][k], At[m][k], acc[ai][bj][m][n], 0, 0, 0); __builtin_amdgcn_s_setprio(0); } while (0)
; #define PG8_WAIT_V(n) asm volatile("s_waitcnt vmcnt(" #n ")" ::: "memory")
; #define PG8_WAIT_L(n) asm volatile("s_waitcnt lgkmcnt(" #n ")" ::: "memory")
; #define PG8_BAR __builtin_amdgcn_s_barrier()
; #define PG8_SCHED __builtin_amdgcn_sched_barrier(0)
; template <class Epi>
; __device__ __forceinline__ void gemm_phase(LAS unsigned char* lds, const Gemm g, const StaticOrder& S, const Epi& E) {
;     ...
;             PG8_STAGE(PG8_SB(0, 1), b2, hB, 0);
;             PG8_WAIT_V(6); PG8_BAR; PG8_MMA(1, 1, At, B1); PG8_BAR;
;             PG8_LDB(B0, 1, 0); PG8_SCHED; PG8_LDA(At, 1, 0); PG8_STAGE(PG8_SA(0, 1), a2, hA, 0);
;             PG8_WAIT_L(8); PG8_BAR; PG8_WAIT_L(0); PG8_MMA(0, 0, At, B0); PG8_BAR; PG8_SCHED;
;             PG8_LDB(B1, 1, 1); PG8_STAGE(PG8_SB(1, 0), b2 + KS, 0, 0);
;             PG8_BAR; PG8_WAIT_L(0); PG8_MMA(0, 1, At, B1); PG8_BAR;
;             PG8_LDA(At, 1, 1); PG8_STAGE(PG8_SA(1, 0), a2 + KS, 0, 0);
	s_add_u32 s66, s58, 0x80000
	s_addc_u32 s67, s59, 0
	s_mov_b32 m0, s29
	s_nop 0
	global_load_lds_dwordx4 v130, s[66:67]
	s_add_u32 s66, s58, 0x82000
	s_addc_u32 s67, s59, 0
	s_mov_b32 m0, s30
	s_nop 0
	global_load_lds_dwordx4 v130, s[66:67]
	s_waitcnt vmcnt(10)
	s_barrier
	s_setprio 1
	v_mfma_f32_16x16x32_bf16 v[48:51], v[184:187], v[152:155], v[48:51]
	v_mfma_f32_16x16x32_bf16 v[40:43], v[204:207], v[152:155], v[40:43]
	v_mfma_f32_16x16x32_bf16 v[32:35], v[184:187], v[160:163], v[32:35]
	v_mfma_f32_16x16x32_bf16 v[24:27], v[204:207], v[160:163], v[24:27]
	v_mfma_f32_16x16x32_bf16 v[16:19], v[184:187], v[168:171], v[16:19]
	v_mfma_f32_16x16x32_bf16 v[8:11], v[204:207], v[168:171], v[8:11]
	v_mfma_f32_16x16x32_bf16 v[4:7], v[184:187], v[176:179], v[4:7]
	v_mfma_f32_16x16x32_bf16 v[0:3], v[204:207], v[176:179], v[0:3]
	v_mfma_f32_16x16x32_bf16 v[48:51], v[200:203], v[156:159], v[48:51]
	v_mfma_f32_16x16x32_bf16 v[40:43], v[208:211], v[156:159], v[40:43]
	v_mfma_f32_16x16x32_bf16 v[32:35], v[200:203], v[164:167], v[32:35]
	v_mfma_f32_16x16x32_bf16 v[24:27], v[208:211], v[164:167], v[24:27]
	v_mfma_f32_16x16x32_bf16 v[16:19], v[200:203], v[172:175], v[16:19]
	v_mfma_f32_16x16x32_bf16 v[8:11], v[208:211], v[172:175], v[8:11]
	v_mfma_f32_16x16x32_bf16 v[4:7], v[200:203], v[180:183], v[4:7]
	v_mfma_f32_16x16x32_bf16 v[0:3], v[208:211], v[180:183], v[0:3]
	s_setprio 0
	v_add_u32_e32 v128, 0x18000, v133
	s_barrier
	ds_read_b128 v[136:139], v128
	ds_read_b128 v[140:143], v128 offset:1024
	ds_read_b128 v[144:147], v128 offset:2048
	ds_read_b128 v[148:151], v128 offset:3072
	ds_read_b128 v[152:155], v134 offset:32768
	ds_read_b128 v[156:159], v134 offset:33792
	ds_read_b128 v[160:163], v134 offset:34816
	ds_read_b128 v[164:167], v134 offset:35840
	ds_read_b128 v[168:171], v134 offset:36864
	ds_read_b128 v[172:175], v134 offset:37888
	ds_read_b128 v[176:179], v134 offset:38912
	ds_read_b128 v[180:183], v134 offset:39936
	s_add_u32 s66, s54, 0x80000
	s_addc_u32 s67, s55, 0
	s_mov_b32 m0, s34
	s_nop 0
	global_load_lds_dwordx4 v130, s[66:67]
	s_add_u32 s66, s54, 0x82000
	s_addc_u32 s67, s55, 0
	s_mov_b32 m0, s37
	s_nop 0
	global_load_lds_dwordx4 v130, s[66:67]
	s_waitcnt lgkmcnt(8)
	s_waitcnt vmcnt(10)
	s_barrier
	s_waitcnt lgkmcnt(0)
	s_setprio 1
	s_waitcnt lgkmcnt(7)
	v_mfma_f32_16x16x32_bf16 v[124:127], v[136:139], v[152:155], v[124:127]
	v_mfma_f32_16x16x32_bf16 v[120:123], v[144:147], v[152:155], v[120:123]
	s_waitcnt lgkmcnt(5)
	v_mfma_f32_16x16x32_bf16 v[116:119], v[136:139], v[160:163], v[116:119]
	v_mfma_f32_16x16x32_bf16 v[108:111], v[144:147], v[160:163], v[108:111]
	s_waitcnt lgkmcnt(3)
	v_mfma_f32_16x16x32_bf16 v[100:103], v[136:139], v[168:171], v[100:103]
	v_mfma_f32_16x16x32_bf16 v[92:95], v[144:147], v[168:171], v[92:95]
	s_waitcnt lgkmcnt(1)
	v_mfma_f32_16x16x32_bf16 v[84:87], v[136:139], v[176:179], v[84:87]
	v_mfma_f32_16x16x32_bf16 v[76:79], v[144:147], v[176:179], v[76:79]
	v_mfma_f32_16x16x32_bf16 v[124:127], v[140:143], v[156:159], v[124:127]
	v_mfma_f32_16x16x32_bf16 v[120:123], v[148:151], v[156:159], v[120:123]
	v_mfma_f32_16x16x32_bf16 v[116:119], v[140:143], v[164:167], v[116:119]
	v_mfma_f32_16x16x32_bf16 v[108:111], v[148:151], v[164:167], v[108:111]
	v_mfma_f32_16x16x32_bf16 v[100:103], v[140:143], v[172:175], v[100:103]
	v_mfma_f32_16x16x32_bf16 v[92:95], v[148:151], v[172:175], v[92:95]
	s_waitcnt lgkmcnt(0)
	v_mfma_f32_16x16x32_bf16 v[84:87], v[140:143], v[180:183], v[84:87]
	v_mfma_f32_16x16x32_bf16 v[76:79], v[148:151], v[180:183], v[76:79]
	s_setprio 0
	s_barrier
	v_add_u32_e32 v128, 0x1c000, v133
	ds_read_b128 v[184:187], v128
	ds_read_b128 v[200:203], v128 offset:1024
	ds_read_b128 v[204:207], v128 offset:2048
	ds_read_b128 v[208:211], v128 offset:3072
	s_add_u32 s66, s58, 0x4000
	s_addc_u32 s67, s59, 0
	s_mov_b32 m0, s38
	s_nop 0
	global_load_lds_dwordx4 v130, s[66:67]
	s_add_u32 s66, s58, 0x6000
	s_addc_u32 s67, s59, 0
	s_mov_b32 m0, s39
	s_nop 0
	global_load_lds_dwordx4 v130, s[66:67]
	s_waitcnt vmcnt(10)
	s_barrier
	s_waitcnt lgkmcnt(0)
	s_setprio 1
	s_waitcnt lgkmcnt(3)
	v_mfma_f32_16x16x32_bf16 v[112:115], v[184:187], v[152:155], v[112:115]
	s_waitcnt lgkmcnt(1)
	v_mfma_f32_16x16x32_bf16 v[104:107], v[204:207], v[152:155], v[104:107]
	v_mfma_f32_16x16x32_bf16 v[96:99], v[184:187], v[160:163], v[96:99]
	v_mfma_f32_16x16x32_bf16 v[88:91], v[204:207], v[160:163], v[88:91]
	v_mfma_f32_16x16x32_bf16 v[80:83], v[184:187], v[168:171], v[80:83]
	v_mfma_f32_16x16x32_bf16 v[72:75], v[204:207], v[168:171], v[72:75]
	v_mfma_f32_16x16x32_bf16 v[68:71], v[184:187], v[176:179], v[68:71]
	v_mfma_f32_16x16x32_bf16 v[64:67], v[204:207], v[176:179], v[64:67]
	v_mfma_f32_16x16x32_bf16 v[112:115], v[200:203], v[156:159], v[112:115]
	s_waitcnt lgkmcnt(0)
	v_mfma_f32_16x16x32_bf16 v[104:107], v[208:211], v[156:159], v[104:107]
	v_mfma_f32_16x16x32_bf16 v[96:99], v[200:203], v[164:167], v[96:99]
	v_mfma_f32_16x16x32_bf16 v[88:91], v[208:211], v[164:167], v[88:91]
	v_mfma_f32_16x16x32_bf16 v[80:83], v[200:203], v[172:175], v[80:83]
	v_mfma_f32_16x16x32_bf16 v[72:75], v[208:211], v[172:175], v[72:75]
	v_mfma_f32_16x16x32_bf16 v[68:71], v[200:203], v[180:183], v[68:71]
	v_mfma_f32_16x16x32_bf16 v[64:67], v[208:211], v[180:183], v[64:67]
	s_setprio 0
	s_barrier
	ds_read_b128 v[152:155], v134 offset:49152
	ds_read_b128 v[156:159], v134 offset:50176
	ds_read_b128 v[160:163], v134 offset:51200
	ds_read_b128 v[164:167], v134 offset:52224
	ds_read_b128 v[168:171], v134 offset:53248
	ds_read_b128 v[172:175], v134 offset:54272
	ds_read_b128 v[176:179], v134 offset:55296
	ds_read_b128 v[180:183], v134 offset:56320
	s_add_u32 s66, s54, 0x4000
	s_addc_u32 s67, s55, 0
	s_mov_b32 m0, s40
	s_nop 0
	global_load_lds_dwordx4 v130, s[66:67]
	s_add_u32 s54, s54, 0x6000
	s_addc_u32 s55, s55, 0
	s_mov_b32 m0, s41
	s_nop 0
	global_load_lds_dwordx4 v130, s[54:55]
	s_barrier
; #define PG8_STAGE(bufoff, gbase, hoff, imm) do { _Pragma("unroll") for (int _i = 0; _i < 2; ++_i) { \
;         asm volatile("s_mov_b32 m0, %0\n\ts_nop 0\n\tglobal_load_lds_dwordx4 %1, %2" \
;             :: "s"(lds0 + (unsigned)((bufoff) + _i * 8192)), "v"(voff0), "s"((const char*)(gbase) + (size_t)(hoff) + (size_t)(_i * 8192)) : "memory"); } } while (0)
; #define PG8_LDA(dst, b, h) do { _Pragma("unroll") for (int m = 0; m < 4; ++m) _Pragma("unroll") for (int k = 0; k < 2; ++k) dst[m][k] = *(const LAS bf16x8*)(lds + PG8_SA(b, h) + aoff + m * 2048 + k * 1024); } while (0)
; #define PG8_MMA(ai, bj, At, Bt) do { __builtin_amdgcn_s_setprio(1); _Pragma("unroll") for (int m = 0; m < 4; ++m) _Pragma("unroll") for (int n = 0; n < 2; ++n) _Pragma("unroll") for (int k = 0; k < 2; ++k) \
;         acc[ai][bj][m][n] = __builtin_amdgcn_mfma_f32_16x16x32_bf16(Bt[n][k], At[m][k], acc[ai][bj][m][n], 0, 0, 0); __builtin_amdgcn_s_setprio(0); } while (0)
; #define PG8_WAIT_V(n) asm volatile("s_waitcnt vmcnt(" #n ")" ::: "memory")
; #define PG8_WAIT_L(n) asm volatile("s_waitcnt lgkmcnt(" #n ")" ::: "memory")
; #define PG8_BAR __builtin_amdgcn_s_barrier()
; #define PG8_SCHED __builtin_amdgcn_sched_barrier(0)
; template <class Epi>
; __device__ __forceinline__ void gemm_phase(LAS unsigned char* lds, const Gemm g, const StaticOrder& S, const Epi& E) {
;     ...
;             PG8_LDA(At, 1, 1); PG8_STAGE(PG8_SA(1, 0), a2 + KS, 0, 0);
;             PG8_BAR; PG8_WAIT_L(0); PG8_MMA(1, 0, At, B0); PG8_BAR; PG8_SCHED;
;             PG8_STAGE(PG8_SB(1, 1), b2 + KS, hB, 0);
;             PG8_WAIT_V(6); PG8_BAR; PG8_MMA(1, 1, At, B1); PG8_BAR;
	s_waitcnt lgkmcnt(0)
	s_setprio 1
	s_waitcnt lgkmcnt(7)
	v_mfma_f32_16x16x32_bf16 v[60:63], v[136:139], v[152:155], v[60:63]
	v_mfma_f32_16x16x32_bf16 v[56:59], v[144:147], v[152:155], v[56:59]
	s_waitcnt lgkmcnt(5)
	v_mfma_f32_16x16x32_bf16 v[52:55], v[136:139], v[160:163], v[52:55]
	v_mfma_f32_16x16x32_bf16 v[44:47], v[144:147], v[160:163], v[44:47]
	s_waitcnt lgkmcnt(3)
	v_mfma_f32_16x16x32_bf16 v[36:39], v[136:139], v[168:171], v[36:39]
	v_mfma_f32_16x16x32_bf16 v[28:31], v[144:147], v[168:171], v[28:31]
	s_waitcnt lgkmcnt(1)
	v_mfma_f32_16x16x32_bf16 v[20:23], v[136:139], v[176:179], v[20:23]
	v_mfma_f32_16x16x32_bf16 v[12:15], v[144:147], v[176:179], v[12:15]
	v_mfma_f32_16x16x32_bf16 v[60:63], v[140:143], v[156:159], v[60:63]
	v_mfma_f32_16x16x32_bf16 v[56:59], v[148:151], v[156:159], v[56:59]
	v_mfma_f32_16x16x32_bf16 v[52:55], v[140:143], v[164:167], v[52:55]
	v_mfma_f32_16x16x32_bf16 v[44:47], v[148:151], v[164:167], v[44:47]
	v_mfma_f32_16x16x32_bf16 v[36:39], v[140:143], v[172:175], v[36:39]
	v_mfma_f32_16x16x32_bf16 v[28:31], v[148:151], v[172:175], v[28:31]
	s_waitcnt lgkmcnt(0)
	v_mfma_f32_16x16x32_bf16 v[20:23], v[140:143], v[180:183], v[20:23]
	v_mfma_f32_16x16x32_bf16 v[12:15], v[148:151], v[180:183], v[12:15]
	s_setprio 0
	s_barrier
	s_add_u32 s54, s58, 0x84000
	s_addc_u32 s55, s59, 0
	s_mov_b32 m0, s42
	s_nop 0
	global_load_lds_dwordx4 v130, s[54:55]
	s_add_u32 s54, s58, 0x86000
	s_addc_u32 s55, s59, 0
	s_mov_b32 m0, s43
	s_nop 0
	global_load_lds_dwordx4 v130, s[54:55]
	s_waitcnt vmcnt(10)
	s_barrier
	s_setprio 1
	v_mfma_f32_16x16x32_bf16 v[48:51], v[184:187], v[152:155], v[48:51]
	v_mfma_f32_16x16x32_bf16 v[40:43], v[204:207], v[152:155], v[40:43]
	v_mfma_f32_16x16x32_bf16 v[32:35], v[184:187], v[160:163], v[32:35]
	v_mfma_f32_16x16x32_bf16 v[24:27], v[204:207], v[160:163], v[24:27]
	v_mfma_f32_16x16x32_bf16 v[16:19], v[184:187], v[168:171], v[16:19]
	v_mfma_f32_16x16x32_bf16 v[8:11], v[204:207], v[168:171], v[8:11]
	v_mfma_f32_16x16x32_bf16 v[4:7], v[184:187], v[176:179], v[4:7]
	v_mfma_f32_16x16x32_bf16 v[0:3], v[204:207], v[176:179], v[0:3]
	v_mfma_f32_16x16x32_bf16 v[48:51], v[200:203], v[156:159], v[48:51]
	v_mfma_f32_16x16x32_bf16 v[40:43], v[208:211], v[156:159], v[40:43]
	v_mfma_f32_16x16x32_bf16 v[32:35], v[200:203], v[164:167], v[32:35]
	v_mfma_f32_16x16x32_bf16 v[24:27], v[208:211], v[164:167], v[24:27]
	v_mfma_f32_16x16x32_bf16 v[16:19], v[200:203], v[172:175], v[16:19]
	v_mfma_f32_16x16x32_bf16 v[8:11], v[208:211], v[172:175], v[8:11]
	v_mfma_f32_16x16x32_bf16 v[4:7], v[200:203], v[180:183], v[4:7]
	v_mfma_f32_16x16x32_bf16 v[0:3], v[208:211], v[180:183], v[0:3]
	s_setprio 0
	s_add_i32 s65, s65, 2
	s_add_u32 s63, s63, 0x8000
	s_addc_u32 s64, s64, 0
	s_cmp_gt_u32 s65, 29
	s_mov_b64 s[54:55], s[56:57]
	s_barrier
	s_cbranch_scc0 .LBB0_434
; #define LAS __attribute__((address_space(3)))
; __device__ __forceinline__ unsigned cvt_pk_bf16(float lo, float hi) { unsigned r; asm volatile("v_cvt_pk_bf16_f32 %0, %1, %2" : "=v"(r) : "v"(lo), "v"(hi)); return r; }
;     __device__ __forceinline__ void operator()(f32x4 (&acc)[2][2][4][2], const Unit& u, int wr, int wc, int fr, int fq, LAS unsigned char*) const {
;         const int row0 = u.pm * BM + wr * 64 + fr, col0 = u.pn * BM + wc * 32 + 8 * fq;
; #pragma unroll
;         for (int ai = 0; ai < 2; ++ai)
; #pragma unroll
;             for (int m = 0; m < 4; ++m) { bf16_t* rowp = O + (size_t)(row0 + ai * HALF + m * 16) * ldc + col0;
; #pragma unroll
;                 for (int bj = 0; bj < 2; ++bj) { const f32x4 v0 = acc[ai][bj][m][0], v1 = acc[ai][bj][m][1];
;                     u32x4 w; w.x = cvt_pk_bf16(v0[0], v0[1]); w.y = cvt_pk_bf16(v0[2], v0[3]); w.z = cvt_pk_bf16(v1[0], v1[1]); w.w = cvt_pk_bf16(v1[2], v1[3]);
;                     *(u32x4*)(rowp + bj * HALF) = w; } }
;     }
	v_lshl_add_u32 v136, s62, 8, v131
	v_lshl_or_b32 v128, s61, 8, v132
	v_ashrrev_i32_e32 v137, 31, v136
	v_ashrrev_i32_e32 v129, 31, v128
	v_lshlrev_b64 v[138:139], 12, v[136:137]
	v_lshl_add_u64 v[138:139], s[2:3], 0, v[138:139]
	v_lshlrev_b64 v[140:141], 1, v[128:129]
	v_lshl_add_u64 v[128:129], v[138:139], 0, v[140:141]
	v_cvt_pk_bf16_f32 v124, v124, v125
	v_cvt_pk_bf16_f32 v125, v126, v127
	v_cvt_pk_bf16_f32 v126, v120, v121
	v_cvt_pk_bf16_f32 v127, v122, v123
	global_store_dwordx4 v[128:129], v[124:127], off
	v_cvt_pk_bf16_f32 v112, v112, v113
	v_cvt_pk_bf16_f32 v113, v114, v115
	v_cvt_pk_bf16_f32 v114, v104, v105
	v_or_b32_e32 v104, 16, v136
	v_ashrrev_i32_e32 v105, 31, v104
	v_lshlrev_b64 v[104:105], 12, v[104:105]
	v_lshl_add_u64 v[104:105], s[2:3], 0, v[104:105]
	v_cvt_pk_bf16_f32 v115, v106, v107
	global_store_dwordx4 v[128:129], v[112:115], off offset:256
	s_mov_b64 s[0:1], 0x80000
	s_mov_b32 s61, s6
	v_lshl_add_u64 v[112:113], v[104:105], 0, v[140:141]
	v_cvt_pk_bf16_f32 v104, v116, v117
	v_cvt_pk_bf16_f32 v105, v118, v119
	v_cvt_pk_bf16_f32 v106, v108, v109
	v_cvt_pk_bf16_f32 v107, v110, v111
	global_store_dwordx4 v[112:113], v[104:107], off
	v_cvt_pk_bf16_f32 v96, v96, v97
	v_cvt_pk_bf16_f32 v97, v98, v99
	v_cvt_pk_bf16_f32 v98, v88, v89
	v_or_b32_e32 v88, 32, v136
	v_ashrrev_i32_e32 v89, 31, v88
	v_lshlrev_b64 v[88:89], 12, v[88:89]
	v_lshl_add_u64 v[88:89], s[2:3], 0, v[88:89]
	v_cvt_pk_bf16_f32 v99, v90, v91
	global_store_dwordx4 v[112:113], v[96:99], off offset:256
	s_mov_b32 s62, s8
	s_mov_b64 s[56:57], s[52:53]
	v_lshl_add_u64 v[96:97], v[88:89], 0, v[140:141]
	v_cvt_pk_bf16_f32 v88, v100, v101
	v_cvt_pk_bf16_f32 v89, v102, v103
	v_cvt_pk_bf16_f32 v90, v92, v93
	v_cvt_pk_bf16_f32 v91, v94, v95
	global_store_dwordx4 v[96:97], v[88:91], off
	v_cvt_pk_bf16_f32 v80, v80, v81
	v_cvt_pk_bf16_f32 v81, v82, v83
	v_cvt_pk_bf16_f32 v82, v72, v73
	v_or_b32_e32 v72, 48, v136
	v_ashrrev_i32_e32 v73, 31, v72
	v_lshlrev_b64 v[72:73], 12, v[72:73]
	v_lshl_add_u64 v[72:73], s[2:3], 0, v[72:73]
	v_cvt_pk_bf16_f32 v83, v74, v75
	global_store_dwordx4 v[96:97], v[80:83], off offset:256
	s_mov_b64 s[54:55], s[10:11]
	s_nop 0
	v_lshl_add_u64 v[80:81], v[72:73], 0, v[140:141]
	v_cvt_pk_bf16_f32 v72, v84, v85
	v_cvt_pk_bf16_f32 v73, v86, v87
	v_cvt_pk_bf16_f32 v74, v76, v77
	v_cvt_pk_bf16_f32 v75, v78, v79
	global_store_dwordx4 v[80:81], v[72:75], off
	v_cvt_pk_bf16_f32 v68, v68, v69
	v_cvt_pk_bf16_f32 v69, v70, v71
	v_cvt_pk_bf16_f32 v70, v64, v65
	v_cvt_pk_bf16_f32 v71, v66, v67
	global_store_dwordx4 v[80:81], v[68:71], off offset:256
	v_cvt_pk_bf16_f32 v60, v60, v61
	v_cvt_pk_bf16_f32 v61, v62, v63
	v_cvt_pk_bf16_f32 v62, v56, v57
	v_add_co_u32_e32 v56, vcc, s93, v128
	v_lshl_add_u64 v[64:65], v[128:129], 0, s[0:1]
	s_nop 0
	v_addc_co_u32_e32 v57, vcc, 0, v129, vcc
	v_cvt_pk_bf16_f32 v63, v58, v59
	global_store_dwordx4 v[56:57], v[60:63], off
	v_cvt_pk_bf16_f32 v48, v48, v49
	v_cvt_pk_bf16_f32 v49, v50, v51
	v_cvt_pk_bf16_f32 v50, v40, v41
	v_cvt_pk_bf16_f32 v51, v42, v43
	global_store_dwordx4 v[64:65], v[48:51], off offset:256
	s_mov_b64 s[0:1], 0x90000
	v_cvt_pk_bf16_f32 v40, v52, v53
	v_cvt_pk_bf16_f32 v41, v54, v55
	v_cvt_pk_bf16_f32 v42, v44, v45
	v_add_co_u32_e32 v44, vcc, s33, v128
	v_lshl_add_u64 v[48:49], v[128:129], 0, s[0:1]
	s_nop 0
	v_addc_co_u32_e32 v45, vcc, 0, v129, vcc
	v_cvt_pk_bf16_f32 v43, v46, v47
	global_store_dwordx4 v[44:45], v[40:43], off
	v_cvt_pk_bf16_f32 v32, v32, v33
	v_cvt_pk_bf16_f32 v33, v34, v35
	v_cvt_pk_bf16_f32 v34, v24, v25
	v_cvt_pk_bf16_f32 v35, v26, v27
	global_store_dwordx4 v[48:49], v[32:35], off offset:256
	s_mov_b64 s[0:1], 0xa0000
	v_cvt_pk_bf16_f32 v24, v36, v37
	v_cvt_pk_bf16_f32 v25, v38, v39
	v_cvt_pk_bf16_f32 v26, v28, v29
	v_add_co_u32_e32 v28, vcc, s18, v128
	v_lshl_add_u64 v[32:33], v[128:129], 0, s[0:1]
	s_nop 0
	v_addc_co_u32_e32 v29, vcc, 0, v129, vcc
	v_cvt_pk_bf16_f32 v27, v30, v31
	global_store_dwordx4 v[28:29], v[24:27], off
	v_cvt_pk_bf16_f32 v16, v16, v17
	v_cvt_pk_bf16_f32 v17, v18, v19
	v_cvt_pk_bf16_f32 v18, v8, v9
	v_cvt_pk_bf16_f32 v19, v10, v11
	global_store_dwordx4 v[32:33], v[16:19], off offset:256
	v_cvt_pk_bf16_f32 v8, v20, v21
	v_cvt_pk_bf16_f32 v9, v22, v23
	v_cvt_pk_bf16_f32 v10, v12, v13
	v_add_co_u32_e32 v12, vcc, s19, v128
	s_mov_b64 s[0:1], 0xb0000
	s_nop 0
	v_addc_co_u32_e32 v13, vcc, 0, v129, vcc
	v_lshl_add_u64 v[16:17], v[128:129], 0, s[0:1]
	s_and_b64 vcc, exec, s[4:5]
	v_cvt_pk_bf16_f32 v11, v14, v15
	global_store_dwordx4 v[12:13], v[8:11], off
	v_cvt_pk_bf16_f32 v4, v4, v5
	v_cvt_pk_bf16_f32 v5, v6, v7
	v_cvt_pk_bf16_f32 v6, v0, v1
	v_cvt_pk_bf16_f32 v7, v2, v3
	global_store_dwordx4 v[16:17], v[4:7], off offset:256
	s_cbranch_vccz .LBB0_427
	s_waitcnt vmcnt(0)
	s_cmpk_gt_u32 s16, 0xff
	v_readlane_b32 s38, v255, 44
	s_cbranch_scc1 .LBB0_438
	s_barrier

; #define PG8_STAGE(bufoff, gbase, hoff, imm) do { _Pragma("unroll") for (int _i = 0; _i < 2; ++_i) { \
;         asm volatile("s_mov_b32 m0, %0\n\ts_nop 0\n\tglobal_load_lds_dwordx4 %1, %2" \
;             :: "s"(lds0 + (unsigned)((bufoff) + _i * 8192)), "v"(voff0), "s"((const char*)(gbase) + (size_t)(hoff) + (size_t)(_i * 8192)) : "memory"); } } while (0)
; #define PG8_LDA(dst, b, h) do { _Pragma("unroll") for (int m = 0; m < 4; ++m) _Pragma("unroll") for (int k = 0; k < 2; ++k) dst[m][k] = *(const LAS bf16x8*)(lds + PG8_SA(b, h) + aoff + m * 2048 + k * 1024); } while (0)
; #define PG8_LDB(dst, b, h) do { _Pragma("unroll") for (int n = 0; n < 2; ++n) _Pragma("unroll") for (int k = 0; k < 2; ++k) dst[n][k] = *(const LAS bf16x8*)(lds + PG8_SB(b, h) + boff + n * 2048 + k * 1024); } while (0)
; #define PG8_MMA(ai, bj, At, Bt) do { __builtin_amdgcn_s_setprio(1); _Pragma("unroll") for (int m = 0; m < 4; ++m) _Pragma("unroll") for (int n = 0; n < 2; ++n) _Pragma("unroll") for (int k = 0; k < 2; ++k) \
;         acc[ai][bj][m][n] = __builtin_amdgcn_mfma_f32_16x16x32_bf16(Bt[n][k], At[m][k], acc[ai][bj][m][n], 0, 0, 0); __builtin_amdgcn_s_setprio(0); } while (0)
; #define PG8_WAIT_L(n) asm volatile("s_waitcnt lgkmcnt(" #n ")" ::: "memory")
; #define PG8_BAR __builtin_amdgcn_s_barrier()
; #define PG8_SCHED __builtin_amdgcn_sched_barrier(0)
; template <class Epi>
; __device__ __forceinline__ void gemm_phase(LAS unsigned char* lds, const Gemm g, const StaticOrder& S, const Epi& E) {
;     ...
;         for (int t = 0; t < nt; t += 2) {
;             const bool last = (t == nt - 2);
;             if (last) E.pre(cur, wid, lane, (unsigned)(size_t)(lds + STAGE_BYTES));
;             const char* aT = cA + (size_t)t * KS;
;             const char* a2 = last ? nA : aT + 2 * KS; const char* b2 = last ? nB : cB + (size_t)(t + 2) * KS;
;             PG8_LDB(B0, 0, 0); PG8_SCHED; PG8_LDA(At, 0, 0); PG8_STAGE(PG8_SA(1, 1), aT + KS, hA, 0);
;             PG8_WAIT_L(8); PG8_BAR; PG8_WAIT_L(0); PG8_MMA(0, 0, At, B0); PG8_BAR; PG8_SCHED;
;             PG8_LDB(B1, 0, 1); PG8_STAGE(PG8_SB(0, 0), b2, 0, 0);
;             PG8_BAR; PG8_WAIT_L(0); PG8_MMA(0, 1, At, B1); PG8_BAR;
;             PG8_LDA(At, 0, 1); PG8_STAGE(PG8_SA(0, 0), a2, 0, 0);
;             PG8_BAR; PG8_WAIT_L(0); PG8_MMA(1, 0, At, B0); PG8_BAR; PG8_SCHED;
.LBB0_506:
	v_add_u32_e32 v140, 0x10000, v202
	ds_read_b128 v[128:131], v140
	ds_read_b128 v[132:135], v140 offset:1024
	ds_read_b128 v[136:139], v140 offset:2048
	ds_read_b128 v[140:143], v140 offset:3072
	s_add_u32 s80, s78, 0x8000
	s_addc_u32 s81, s79, 0
	s_and_b64 s[82:83], s[84:85], exec
	s_cselect_b32 s83, s51, s81
	s_cselect_b32 s82, s71, s80
	ds_read_b128 v[144:147], v203
	ds_read_b128 v[148:151], v203 offset:1024
	ds_read_b128 v[152:155], v203 offset:2048
	ds_read_b128 v[156:159], v203 offset:3072
	ds_read_b128 v[160:163], v203 offset:4096
	ds_read_b128 v[164:167], v203 offset:5120
	ds_read_b128 v[204:207], v203 offset:6144
	ds_read_b128 v[208:211], v203 offset:7168
	s_add_u32 s48, s78, 0x84000
	s_addc_u32 s49, s79, 0
	s_mov_b32 m0, s87
	s_nop 0
	global_load_lds_dwordx4 v168, s[48:49]
	s_add_u32 s48, s78, 0x86000
	s_addc_u32 s49, s79, 0
	s_mov_b32 m0, s96
	s_nop 0
	global_load_lds_dwordx4 v168, s[48:49]
	s_waitcnt lgkmcnt(8)
	s_waitcnt vmcnt(10)
	s_barrier
	s_waitcnt lgkmcnt(0)
	s_setprio 1
	s_waitcnt lgkmcnt(7)
	v_mfma_f32_16x16x32_bf16 v[96:99], v[128:131], v[144:147], v[96:99]
	v_mfma_f32_16x16x32_bf16 v[44:47], v[136:139], v[144:147], v[44:47]
	s_waitcnt lgkmcnt(5)
	v_mfma_f32_16x16x32_bf16 v[92:95], v[128:131], v[152:155], v[92:95]
	v_mfma_f32_16x16x32_bf16 v[40:43], v[136:139], v[152:155], v[40:43]
	s_waitcnt lgkmcnt(3)
	v_mfma_f32_16x16x32_bf16 v[84:87], v[128:131], v[160:163], v[84:87]
	v_mfma_f32_16x16x32_bf16 v[36:39], v[136:139], v[160:163], v[36:39]
	s_waitcnt lgkmcnt(1)
	v_mfma_f32_16x16x32_bf16 v[124:127], v[128:131], v[204:207], v[124:127]
	v_mfma_f32_16x16x32_bf16 v[120:123], v[136:139], v[204:207], v[120:123]
	v_mfma_f32_16x16x32_bf16 v[96:99], v[132:135], v[148:151], v[96:99]
	v_mfma_f32_16x16x32_bf16 v[44:47], v[140:143], v[148:151], v[44:47]
	v_mfma_f32_16x16x32_bf16 v[92:95], v[132:135], v[156:159], v[92:95]
	v_mfma_f32_16x16x32_bf16 v[40:43], v[140:143], v[156:159], v[40:43]
	v_mfma_f32_16x16x32_bf16 v[84:87], v[132:135], v[164:167], v[84:87]
	v_mfma_f32_16x16x32_bf16 v[36:39], v[140:143], v[164:167], v[36:39]
	s_waitcnt lgkmcnt(0)
	v_mfma_f32_16x16x32_bf16 v[124:127], v[132:135], v[208:211], v[124:127]
	v_mfma_f32_16x16x32_bf16 v[120:123], v[140:143], v[208:211], v[120:123]
	s_setprio 0
	s_barrier
	v_add_u32_e32 v188, 0x14000, v202
	ds_read_b128 v[212:215], v188
	ds_read_b128 v[236:239], v188 offset:1024
	ds_read_b128 v[240:243], v188 offset:2048
	ds_read_b128 v[244:247], v188 offset:3072
	s_and_b64 s[48:49], s[84:85], exec
	s_cselect_b32 s78, s62, s9
	s_cselect_b32 s79, s69, s63
	s_mov_b32 m0, s25
	s_nop 0
	global_load_lds_dwordx4 v168, s[78:79]
	s_add_u32 s48, s78, 0x2000
	s_addc_u32 s49, s79, 0
	s_mov_b32 m0, s26
	s_nop 0
	global_load_lds_dwordx4 v168, s[48:49]
	s_waitcnt vmcnt(10)
	s_barrier
	s_waitcnt lgkmcnt(0)
	s_setprio 1
	s_waitcnt lgkmcnt(3)
	v_mfma_f32_16x16x32_bf16 v[80:83], v[212:215], v[144:147], v[80:83]
	s_waitcnt lgkmcnt(1)
	v_mfma_f32_16x16x32_bf16 v[32:35], v[240:243], v[144:147], v[32:35]
	v_mfma_f32_16x16x32_bf16 v[76:79], v[212:215], v[152:155], v[76:79]
	v_mfma_f32_16x16x32_bf16 v[28:31], v[240:243], v[152:155], v[28:31]
	v_mfma_f32_16x16x32_bf16 v[72:75], v[212:215], v[160:163], v[72:75]
	v_mfma_f32_16x16x32_bf16 v[24:27], v[240:243], v[160:163], v[24:27]
	v_mfma_f32_16x16x32_bf16 v[116:119], v[212:215], v[204:207], v[116:119]
	v_mfma_f32_16x16x32_bf16 v[112:115], v[240:243], v[204:207], v[112:115]
	v_mfma_f32_16x16x32_bf16 v[80:83], v[236:239], v[148:151], v[80:83]
	s_waitcnt lgkmcnt(0)
	v_mfma_f32_16x16x32_bf16 v[32:35], v[244:247], v[148:151], v[32:35]
	v_mfma_f32_16x16x32_bf16 v[76:79], v[236:239], v[156:159], v[76:79]
	v_mfma_f32_16x16x32_bf16 v[28:31], v[244:247], v[156:159], v[28:31]
	v_mfma_f32_16x16x32_bf16 v[72:75], v[236:239], v[164:167], v[72:75]
	v_mfma_f32_16x16x32_bf16 v[24:27], v[244:247], v[164:167], v[24:27]
	v_mfma_f32_16x16x32_bf16 v[116:119], v[236:239], v[208:211], v[116:119]
	v_mfma_f32_16x16x32_bf16 v[112:115], v[244:247], v[208:211], v[112:115]
	s_setprio 0
	s_barrier
	ds_read_b128 v[144:147], v203 offset:16384
	ds_read_b128 v[148:151], v203 offset:17408
	ds_read_b128 v[152:155], v203 offset:18432
	ds_read_b128 v[156:159], v203 offset:19456
	ds_read_b128 v[160:163], v203 offset:20480
	ds_read_b128 v[164:167], v203 offset:21504
	ds_read_b128 v[204:207], v203 offset:22528
	ds_read_b128 v[208:211], v203 offset:23552
	s_mov_b32 m0, s24
	s_nop 0
	global_load_lds_dwordx4 v168, s[82:83]
	s_add_u32 s48, s82, 0x2000
	s_addc_u32 s49, s83, 0
	s_mov_b32 m0, s27
	s_nop 0
	global_load_lds_dwordx4 v168, s[48:49]
	s_barrier
	s_waitcnt lgkmcnt(0)
	s_setprio 1
	s_waitcnt lgkmcnt(7)
	v_mfma_f32_16x16x32_bf16 v[68:71], v[128:131], v[144:147], v[68:71]
	v_mfma_f32_16x16x32_bf16 v[20:23], v[136:139], v[144:147], v[20:23]
	s_waitcnt lgkmcnt(5)
	v_mfma_f32_16x16x32_bf16 v[64:67], v[128:131], v[152:155], v[64:67]
	v_mfma_f32_16x16x32_bf16 v[16:19], v[136:139], v[152:155], v[16:19]
	s_waitcnt lgkmcnt(3)
	v_mfma_f32_16x16x32_bf16 v[60:63], v[128:131], v[160:163], v[60:63]
	v_mfma_f32_16x16x32_bf16 v[12:15], v[136:139], v[160:163], v[12:15]
	s_waitcnt lgkmcnt(1)
	v_mfma_f32_16x16x32_bf16 v[108:111], v[128:131], v[204:207], v[108:111]
	v_mfma_f32_16x16x32_bf16 v[104:107], v[136:139], v[204:207], v[104:107]
	v_mfma_f32_16x16x32_bf16 v[68:71], v[132:135], v[148:151], v[68:71]
	v_mfma_f32_16x16x32_bf16 v[20:23], v[140:143], v[148:151], v[20:23]
	v_mfma_f32_16x16x32_bf16 v[64:67], v[132:135], v[156:159], v[64:67]
	v_mfma_f32_16x16x32_bf16 v[16:19], v[140:143], v[156:159], v[16:19]
	v_mfma_f32_16x16x32_bf16 v[60:63], v[132:135], v[164:167], v[60:63]
	v_mfma_f32_16x16x32_bf16 v[12:15], v[140:143], v[164:167], v[12:15]
	s_waitcnt lgkmcnt(0)
	v_mfma_f32_16x16x32_bf16 v[108:111], v[132:135], v[208:211], v[108:111]
	v_mfma_f32_16x16x32_bf16 v[104:107], v[140:143], v[208:211], v[104:107]
	s_setprio 0
	s_barrier
; #define PG8_STAGE(bufoff, gbase, hoff, imm) do { _Pragma("unroll") for (int _i = 0; _i < 2; ++_i) { \
;         asm volatile("s_mov_b32 m0, %0\n\ts_nop 0\n\tglobal_load_lds_dwordx4 %1, %2" \
;             :: "s"(lds0 + (unsigned)((bufoff) + _i * 8192)), "v"(voff0), "s"((const char*)(gbase) + (size_t)(hoff) + (size_t)(_i * 8192)) : "memory"); } } while (0)
; #define PG8_LDA(dst, b, h) do { _Pragma("unroll") for (int m = 0; m < 4; ++m) _Pragma("unroll") for (int k = 0; k < 2; ++k) dst[m][k] = *(const LAS bf16x8*)(lds + PG8_SA(b, h) + aoff + m * 2048 + k * 1024); } while (0)
; #define PG8_LDB(dst, b, h) do { _Pragma("unroll") for (int n = 0; n < 2; ++n) _Pragma("unroll") for (int k = 0; k < 2; ++k) dst[n][k] = *(const LAS bf16x8*)(lds + PG8_SB(b, h) + boff + n * 2048 + k * 1024); } while (0)
; #define PG8_MMA(ai, bj, At, Bt) do { __builtin_amdgcn_s_setprio(1); _Pragma("unroll") for (int m = 0; m < 4; ++m) _Pragma("unroll") for (int n = 0; n < 2; ++n) _Pragma("unroll") for (int k = 0; k < 2; ++k) \
;         acc[ai][bj][m][n] = __builtin_amdgcn_mfma_f32_16x16x32_bf16(Bt[n][k], At[m][k], acc[ai][bj][m][n], 0, 0, 0); __builtin_amdgcn_s_setprio(0); } while (0)
; #define PG8_WAIT_V(n) asm volatile("s_waitcnt vmcnt(" #n ")" ::: "memory")
; #define PG8_WAIT_L(n) asm volatile("s_waitcnt lgkmcnt(" #n ")" ::: "memory")
; #define PG8_BAR __builtin_amdgcn_s_barrier()
; #define PG8_SCHED __builtin_amdgcn_sched_barrier(0)
; template <class Epi>
; __device__ __forceinline__ void gemm_phase(LAS unsigned char* lds, const Gemm g, const StaticOrder& S, const Epi& E) {
;     ...
;             PG8_STAGE(PG8_SB(0, 1), b2, hB, 0);
;             PG8_WAIT_V(6); PG8_BAR; PG8_MMA(1, 1, At, B1); PG8_BAR;
;             PG8_LDB(B0, 1, 0); PG8_SCHED; PG8_LDA(At, 1, 0); PG8_STAGE(PG8_SA(0, 1), a2, hA, 0);
;             PG8_WAIT_L(8); PG8_BAR; PG8_WAIT_L(0); PG8_MMA(0, 0, At, B0); PG8_BAR; PG8_SCHED;
	s_add_u32 s48, s78, 0x80000
	s_addc_u32 s49, s79, 0
	s_mov_b32 m0, s28
	s_nop 0
	global_load_lds_dwordx4 v168, s[48:49]
	s_add_u32 s48, s78, 0x82000
	s_addc_u32 s49, s79, 0
	s_mov_b32 m0, s29
	s_nop 0
	global_load_lds_dwordx4 v168, s[48:49]
	s_waitcnt vmcnt(10)
	s_barrier
	s_setprio 1
	v_mfma_f32_16x16x32_bf16 v[56:59], v[212:215], v[144:147], v[56:59]
	v_mfma_f32_16x16x32_bf16 v[8:11], v[240:243], v[144:147], v[8:11]
	v_mfma_f32_16x16x32_bf16 v[52:55], v[212:215], v[152:155], v[52:55]
	v_mfma_f32_16x16x32_bf16 v[4:7], v[240:243], v[152:155], v[4:7]
	v_mfma_f32_16x16x32_bf16 v[48:51], v[212:215], v[160:163], v[48:51]
	v_mfma_f32_16x16x32_bf16 v[0:3], v[240:243], v[160:163], v[0:3]
	v_mfma_f32_16x16x32_bf16 v[100:103], v[212:215], v[204:207], v[100:103]
	v_mfma_f32_16x16x32_bf16 v[88:91], v[240:243], v[204:207], v[88:91]
	v_mfma_f32_16x16x32_bf16 v[56:59], v[236:239], v[148:151], v[56:59]
	v_mfma_f32_16x16x32_bf16 v[8:11], v[244:247], v[148:151], v[8:11]
	v_mfma_f32_16x16x32_bf16 v[52:55], v[236:239], v[156:159], v[52:55]
	v_mfma_f32_16x16x32_bf16 v[4:7], v[244:247], v[156:159], v[4:7]
	v_mfma_f32_16x16x32_bf16 v[48:51], v[236:239], v[164:167], v[48:51]
	v_mfma_f32_16x16x32_bf16 v[0:3], v[244:247], v[164:167], v[0:3]
	v_mfma_f32_16x16x32_bf16 v[100:103], v[236:239], v[208:211], v[100:103]
	v_mfma_f32_16x16x32_bf16 v[88:91], v[244:247], v[208:211], v[88:91]
	s_setprio 0
	v_add_u32_e32 v140, 0x18000, v202
	s_barrier
	ds_read_b128 v[128:131], v140
	ds_read_b128 v[132:135], v140 offset:1024
	ds_read_b128 v[136:139], v140 offset:2048
	ds_read_b128 v[140:143], v140 offset:3072
	ds_read_b128 v[144:147], v203 offset:32768
	ds_read_b128 v[148:151], v203 offset:33792
	ds_read_b128 v[152:155], v203 offset:34816
	ds_read_b128 v[156:159], v203 offset:35840
	ds_read_b128 v[160:163], v203 offset:36864
	ds_read_b128 v[164:167], v203 offset:37888
	ds_read_b128 v[204:207], v203 offset:38912
	ds_read_b128 v[208:211], v203 offset:39936
	s_add_u32 s48, s82, 0x80000
	s_addc_u32 s49, s83, 0
	s_mov_b32 m0, s30
	s_nop 0
	global_load_lds_dwordx4 v168, s[48:49]
	s_add_u32 s48, s82, 0x82000
	s_addc_u32 s49, s83, 0
	s_mov_b32 m0, s34
	s_nop 0
	global_load_lds_dwordx4 v168, s[48:49]
	s_waitcnt lgkmcnt(8)
	s_waitcnt vmcnt(10)
	s_barrier
	s_waitcnt lgkmcnt(0)
	s_setprio 1
	s_waitcnt lgkmcnt(7)
	v_mfma_f32_16x16x32_bf16 v[96:99], v[128:131], v[144:147], v[96:99]
	v_mfma_f32_16x16x32_bf16 v[44:47], v[136:139], v[144:147], v[44:47]
	s_waitcnt lgkmcnt(5)
	v_mfma_f32_16x16x32_bf16 v[92:95], v[128:131], v[152:155], v[92:95]
	v_mfma_f32_16x16x32_bf16 v[40:43], v[136:139], v[152:155], v[40:43]
	s_waitcnt lgkmcnt(3)
	v_mfma_f32_16x16x32_bf16 v[84:87], v[128:131], v[160:163], v[84:87]
	v_mfma_f32_16x16x32_bf16 v[36:39], v[136:139], v[160:163], v[36:39]
	s_waitcnt lgkmcnt(1)
	v_mfma_f32_16x16x32_bf16 v[124:127], v[128:131], v[204:207], v[124:127]
	v_mfma_f32_16x16x32_bf16 v[120:123], v[136:139], v[204:207], v[120:123]
	v_mfma_f32_16x16x32_bf16 v[96:99], v[132:135], v[148:151], v[96:99]
	v_mfma_f32_16x16x32_bf16 v[44:47], v[140:143], v[148:151], v[44:47]
	v_mfma_f32_16x16x32_bf16 v[92:95], v[132:135], v[156:159], v[92:95]
	v_mfma_f32_16x16x32_bf16 v[40:43], v[140:143], v[156:159], v[40:43]
	v_mfma_f32_16x16x32_bf16 v[84:87], v[132:135], v[164:167], v[84:87]
	v_mfma_f32_16x16x32_bf16 v[36:39], v[140:143], v[164:167], v[36:39]
	s_waitcnt lgkmcnt(0)
	v_mfma_f32_16x16x32_bf16 v[124:127], v[132:135], v[208:211], v[124:127]
	v_mfma_f32_16x16x32_bf16 v[120:123], v[140:143], v[208:211], v[120:123]
	s_setprio 0
	s_barrier
	v_add_u32_e32 v188, 0x1c000, v202
	ds_read_b128 v[212:215], v188
	ds_read_b128 v[236:239], v188 offset:1024
	ds_read_b128 v[240:243], v188 offset:2048
	ds_read_b128 v[244:247], v188 offset:3072
	s_add_u32 s48, s78, 0x4000
	s_addc_u32 s49, s79, 0
	s_mov_b32 m0, s38
	s_nop 0
	global_load_lds_dwordx4 v168, s[48:49]
	s_add_u32 s48, s78, 0x6000
	s_addc_u32 s49, s79, 0
	s_mov_b32 m0, s39
	s_nop 0
	global_load_lds_dwordx4 v168, s[48:49]
	s_waitcnt vmcnt(10)
	s_barrier
; #define PG8_STAGE(bufoff, gbase, hoff, imm) do { _Pragma("unroll") for (int _i = 0; _i < 2; ++_i) { \
;         asm volatile("s_mov_b32 m0, %0\n\ts_nop 0\n\tglobal_load_lds_dwordx4 %1, %2" \
;             :: "s"(lds0 + (unsigned)((bufoff) + _i * 8192)), "v"(voff0), "s"((const char*)(gbase) + (size_t)(hoff) + (size_t)(_i * 8192)) : "memory"); } } while (0)
; #define PG8_LDA(dst, b, h) do { _Pragma("unroll") for (int m = 0; m < 4; ++m) _Pragma("unroll") for (int k = 0; k < 2; ++k) dst[m][k] = *(const LAS bf16x8*)(lds + PG8_SA(b, h) + aoff + m * 2048 + k * 1024); } while (0)
; #define PG8_LDB(dst, b, h) do { _Pragma("unroll") for (int n = 0; n < 2; ++n) _Pragma("unroll") for (int k = 0; k < 2; ++k) dst[n][k] = *(const LAS bf16x8*)(lds + PG8_SB(b, h) + boff + n * 2048 + k * 1024); } while (0)
; #define PG8_MMA(ai, bj, At, Bt) do { __builtin_amdgcn_s_setprio(1); _Pragma("unroll") for (int m = 0; m < 4; ++m) _Pragma("unroll") for (int n = 0; n < 2; ++n) _Pragma("unroll") for (int k = 0; k < 2; ++k) \
;         acc[ai][bj][m][n] = __builtin_amdgcn_mfma_f32_16x16x32_bf16(Bt[n][k], At[m][k], acc[ai][bj][m][n], 0, 0, 0); __builtin_amdgcn_s_setprio(0); } while (0)
; #define PG8_WAIT_V(n) asm volatile("s_waitcnt vmcnt(" #n ")" ::: "memory")
; #define PG8_WAIT_L(n) asm volatile("s_waitcnt lgkmcnt(" #n ")" ::: "memory")
; #define PG8_BAR __builtin_amdgcn_s_barrier()
; #define PG8_SCHED __builtin_amdgcn_sched_barrier(0)
; template <class Epi>
; __device__ __forceinline__ void gemm_phase(LAS unsigned char* lds, const Gemm g, const StaticOrder& S, const Epi& E) {
;     ...
;             PG8_WAIT_L(8); PG8_BAR; PG8_WAIT_L(0); PG8_MMA(0, 0, At, B0); PG8_BAR; PG8_SCHED;
;             PG8_LDB(B1, 1, 1); PG8_STAGE(PG8_SB(1, 0), b2 + KS, 0, 0);
;             PG8_BAR; PG8_WAIT_L(0); PG8_MMA(0, 1, At, B1); PG8_BAR;
;             PG8_LDA(At, 1, 1); PG8_STAGE(PG8_SA(1, 0), a2 + KS, 0, 0);
;             PG8_BAR; PG8_WAIT_L(0); PG8_MMA(1, 0, At, B0); PG8_BAR; PG8_SCHED;
;             PG8_STAGE(PG8_SB(1, 1), b2 + KS, hB, 0);
;             PG8_WAIT_V(6); PG8_BAR; PG8_MMA(1, 1, At, B1); PG8_BAR;
	s_waitcnt lgkmcnt(0)
	s_setprio 1
	s_waitcnt lgkmcnt(3)
	v_mfma_f32_16x16x32_bf16 v[80:83], v[212:215], v[144:147], v[80:83]
	s_waitcnt lgkmcnt(1)
	v_mfma_f32_16x16x32_bf16 v[32:35], v[240:243], v[144:147], v[32:35]
	v_mfma_f32_16x16x32_bf16 v[76:79], v[212:215], v[152:155], v[76:79]
	v_mfma_f32_16x16x32_bf16 v[28:31], v[240:243], v[152:155], v[28:31]
	v_mfma_f32_16x16x32_bf16 v[72:75], v[212:215], v[160:163], v[72:75]
	v_mfma_f32_16x16x32_bf16 v[24:27], v[240:243], v[160:163], v[24:27]
	v_mfma_f32_16x16x32_bf16 v[116:119], v[212:215], v[204:207], v[116:119]
	v_mfma_f32_16x16x32_bf16 v[112:115], v[240:243], v[204:207], v[112:115]
	v_mfma_f32_16x16x32_bf16 v[80:83], v[236:239], v[148:151], v[80:83]
	s_waitcnt lgkmcnt(0)
	v_mfma_f32_16x16x32_bf16 v[32:35], v[244:247], v[148:151], v[32:35]
	v_mfma_f32_16x16x32_bf16 v[76:79], v[236:239], v[156:159], v[76:79]
	v_mfma_f32_16x16x32_bf16 v[28:31], v[244:247], v[156:159], v[28:31]
	v_mfma_f32_16x16x32_bf16 v[72:75], v[236:239], v[164:167], v[72:75]
	v_mfma_f32_16x16x32_bf16 v[24:27], v[244:247], v[164:167], v[24:27]
	v_mfma_f32_16x16x32_bf16 v[116:119], v[236:239], v[208:211], v[116:119]
	v_mfma_f32_16x16x32_bf16 v[112:115], v[244:247], v[208:211], v[112:115]
	s_setprio 0
	s_barrier
	ds_read_b128 v[144:147], v203 offset:49152
	ds_read_b128 v[148:151], v203 offset:50176
	ds_read_b128 v[152:155], v203 offset:51200
	ds_read_b128 v[156:159], v203 offset:52224
	ds_read_b128 v[160:163], v203 offset:53248
	ds_read_b128 v[164:167], v203 offset:54272
	ds_read_b128 v[204:207], v203 offset:55296
	ds_read_b128 v[208:211], v203 offset:56320
	s_add_u32 s48, s82, 0x4000
	s_addc_u32 s49, s83, 0
	s_mov_b32 m0, s40
	s_nop 0
	global_load_lds_dwordx4 v168, s[48:49]
	s_add_u32 s48, s82, 0x6000
	s_addc_u32 s49, s83, 0
	s_mov_b32 m0, s41
	s_nop 0
	global_load_lds_dwordx4 v168, s[48:49]
	s_barrier
	s_waitcnt lgkmcnt(0)
	s_setprio 1
	s_waitcnt lgkmcnt(7)
	v_mfma_f32_16x16x32_bf16 v[68:71], v[128:131], v[144:147], v[68:71]
	v_mfma_f32_16x16x32_bf16 v[20:23], v[136:139], v[144:147], v[20:23]
	s_waitcnt lgkmcnt(5)
	v_mfma_f32_16x16x32_bf16 v[64:67], v[128:131], v[152:155], v[64:67]
	v_mfma_f32_16x16x32_bf16 v[16:19], v[136:139], v[152:155], v[16:19]
	s_waitcnt lgkmcnt(3)
	v_mfma_f32_16x16x32_bf16 v[60:63], v[128:131], v[160:163], v[60:63]
	v_mfma_f32_16x16x32_bf16 v[12:15], v[136:139], v[160:163], v[12:15]
	s_waitcnt lgkmcnt(1)
	v_mfma_f32_16x16x32_bf16 v[108:111], v[128:131], v[204:207], v[108:111]
	v_mfma_f32_16x16x32_bf16 v[104:107], v[136:139], v[204:207], v[104:107]
	v_mfma_f32_16x16x32_bf16 v[68:71], v[132:135], v[148:151], v[68:71]
	v_mfma_f32_16x16x32_bf16 v[20:23], v[140:143], v[148:151], v[20:23]
	v_mfma_f32_16x16x32_bf16 v[64:67], v[132:135], v[156:159], v[64:67]
	v_mfma_f32_16x16x32_bf16 v[16:19], v[140:143], v[156:159], v[16:19]
	v_mfma_f32_16x16x32_bf16 v[60:63], v[132:135], v[164:167], v[60:63]
	v_mfma_f32_16x16x32_bf16 v[12:15], v[140:143], v[164:167], v[12:15]
	s_waitcnt lgkmcnt(0)
	v_mfma_f32_16x16x32_bf16 v[108:111], v[132:135], v[208:211], v[108:111]
	v_mfma_f32_16x16x32_bf16 v[104:107], v[140:143], v[208:211], v[104:107]
	s_setprio 0
	s_barrier
	s_add_u32 s48, s78, 0x84000
	s_addc_u32 s49, s79, 0
	s_mov_b32 m0, s42
	s_nop 0
	global_load_lds_dwordx4 v168, s[48:49]
	s_add_u32 s48, s78, 0x86000
	s_addc_u32 s49, s79, 0
	s_mov_b32 m0, s43
	s_nop 0
	global_load_lds_dwordx4 v168, s[48:49]
	s_waitcnt vmcnt(10)
	s_barrier
	s_setprio 1
	v_mfma_f32_16x16x32_bf16 v[56:59], v[212:215], v[144:147], v[56:59]
	v_mfma_f32_16x16x32_bf16 v[8:11], v[240:243], v[144:147], v[8:11]
	v_mfma_f32_16x16x32_bf16 v[52:55], v[212:215], v[152:155], v[52:55]
	v_mfma_f32_16x16x32_bf16 v[4:7], v[240:243], v[152:155], v[4:7]
	v_mfma_f32_16x16x32_bf16 v[48:51], v[212:215], v[160:163], v[48:51]
	v_mfma_f32_16x16x32_bf16 v[0:3], v[240:243], v[160:163], v[0:3]
	v_mfma_f32_16x16x32_bf16 v[100:103], v[212:215], v[204:207], v[100:103]
	v_mfma_f32_16x16x32_bf16 v[88:91], v[240:243], v[204:207], v[88:91]
	v_mfma_f32_16x16x32_bf16 v[56:59], v[236:239], v[148:151], v[56:59]
	v_mfma_f32_16x16x32_bf16 v[8:11], v[244:247], v[148:151], v[8:11]
	v_mfma_f32_16x16x32_bf16 v[52:55], v[236:239], v[156:159], v[52:55]
	v_mfma_f32_16x16x32_bf16 v[4:7], v[244:247], v[156:159], v[4:7]
	v_mfma_f32_16x16x32_bf16 v[48:51], v[236:239], v[164:167], v[48:51]
	v_mfma_f32_16x16x32_bf16 v[0:3], v[244:247], v[164:167], v[0:3]
	v_mfma_f32_16x16x32_bf16 v[100:103], v[236:239], v[208:211], v[100:103]
	v_mfma_f32_16x16x32_bf16 v[88:91], v[244:247], v[208:211], v[88:91]
	s_setprio 0
	s_add_i32 s0, s0, 2
	s_add_u32 s9, s9, 0x8000
	s_addc_u32 s63, s63, 0
	s_cmp_gt_u32 s0, 29
	s_mov_b64 s[78:79], s[80:81]
	s_barrier
	s_cbranch_scc1 .LBB0_509

; #define PG8_STAGE(bufoff, gbase, hoff, imm) do { _Pragma("unroll") for (int _i = 0; _i < 2; ++_i) { \
;         asm volatile("s_mov_b32 m0, %0\n\ts_nop 0\n\tglobal_load_lds_dwordx4 %1, %2" \
;             :: "s"(lds0 + (unsigned)((bufoff) + _i * 8192)), "v"(voff0), "s"((const char*)(gbase) + (size_t)(hoff) + (size_t)(_i * 8192)) : "memory"); } } while (0)
; #define PG8_LDA(dst, b, h) do { _Pragma("unroll") for (int m = 0; m < 4; ++m) _Pragma("unroll") for (int k = 0; k < 2; ++k) dst[m][k] = *(const LAS bf16x8*)(lds + PG8_SA(b, h) + aoff + m * 2048 + k * 1024); } while (0)
; #define PG8_LDB(dst, b, h) do { _Pragma("unroll") for (int n = 0; n < 2; ++n) _Pragma("unroll") for (int k = 0; k < 2; ++k) dst[n][k] = *(const LAS bf16x8*)(lds + PG8_SB(b, h) + boff + n * 2048 + k * 1024); } while (0)
; #define PG8_MMA(ai, bj, At, Bt) do { __builtin_amdgcn_s_setprio(1); _Pragma("unroll") for (int m = 0; m < 4; ++m) _Pragma("unroll") for (int n = 0; n < 2; ++n) _Pragma("unroll") for (int k = 0; k < 2; ++k) \
;         acc[ai][bj][m][n] = __builtin_amdgcn_mfma_f32_16x16x32_bf16(Bt[n][k], At[m][k], acc[ai][bj][m][n], 0, 0, 0); __builtin_amdgcn_s_setprio(0); } while (0)
; #define PG8_WAIT_L(n) asm volatile("s_waitcnt lgkmcnt(" #n ")" ::: "memory")
; #define PG8_BAR __builtin_amdgcn_s_barrier()
; #define PG8_SCHED __builtin_amdgcn_sched_barrier(0)
; template <class Epi>
; __device__ __forceinline__ void gemm_phase(LAS unsigned char* lds, const Gemm g, const StaticOrder& S, const Epi& E) {
;     ...
;         for (int t = 0; t < nt; t += 2) {
;             const bool last = (t == nt - 2);
;             if (last) E.pre(cur, wid, lane, (unsigned)(size_t)(lds + STAGE_BYTES));
;             const char* aT = cA + (size_t)t * KS;
;             const char* a2 = last ? nA : aT + 2 * KS; const char* b2 = last ? nB : cB + (size_t)(t + 2) * KS;
;             PG8_LDB(B0, 0, 0); PG8_SCHED; PG8_LDA(At, 0, 0); PG8_STAGE(PG8_SA(1, 1), aT + KS, hA, 0);
;             PG8_WAIT_L(8); PG8_BAR; PG8_WAIT_L(0); PG8_MMA(0, 0, At, B0); PG8_BAR; PG8_SCHED;
;             PG8_LDB(B1, 0, 1); PG8_STAGE(PG8_SB(0, 0), b2, 0, 0);
;             PG8_BAR; PG8_WAIT_L(0); PG8_MMA(0, 1, At, B1); PG8_BAR;
;             PG8_LDA(At, 0, 1); PG8_STAGE(PG8_SA(0, 0), a2, 0, 0);
;             PG8_BAR; PG8_WAIT_L(0); PG8_MMA(1, 0, At, B0); PG8_BAR; PG8_SCHED;
.LBB0_610:
	s_add_u32 s62, s60, 0x8000
	v_add_u32_e32 v132, 0x10000, v236
	s_addc_u32 s63, s61, 0
	ds_read_b128 v[120:123], v132
	ds_read_b128 v[124:127], v132 offset:1024
	ds_read_b128 v[128:131], v132 offset:2048
	ds_read_b128 v[132:135], v132 offset:3072
	s_add_u32 s48, s60, 0x84000
	s_addc_u32 s49, s61, 0
	s_add_u32 s64, s60, 0x86000
	s_addc_u32 s65, s61, 0
	s_cmp_eq_u32 s71, 28
	s_cselect_b32 s61, s0, s63
	s_cselect_b32 s60, s1, s62
	ds_read_b128 v[136:139], v237
	ds_read_b128 v[140:143], v237 offset:1024
	ds_read_b128 v[152:155], v237 offset:2048
	ds_read_b128 v[156:159], v237 offset:3072
	ds_read_b128 v[160:163], v237 offset:4096
	ds_read_b128 v[164:167], v237 offset:5120
	ds_read_b128 v[168:171], v237 offset:6144
	ds_read_b128 v[172:175], v237 offset:7168
	s_mov_b32 m0, s67
	s_nop 0
	global_load_lds_dwordx4 v188, s[48:49]
	s_mov_b32 m0, s68
	s_nop 0
	global_load_lds_dwordx4 v188, s[64:65]
	s_waitcnt lgkmcnt(8)
	s_waitcnt vmcnt(10)
	s_barrier
	s_waitcnt lgkmcnt(0)
	s_setprio 1
	s_waitcnt lgkmcnt(7)
	v_mfma_f32_16x16x32_bf16 v[148:151], v[120:123], v[136:139], v[148:151]
	v_mfma_f32_16x16x32_bf16 v[144:147], v[128:131], v[136:139], v[144:147]
	s_waitcnt lgkmcnt(5)
	v_mfma_f32_16x16x32_bf16 v[108:111], v[120:123], v[152:155], v[108:111]
	v_mfma_f32_16x16x32_bf16 v[104:107], v[128:131], v[152:155], v[104:107]
	s_waitcnt lgkmcnt(3)
	v_mfma_f32_16x16x32_bf16 v[92:95], v[120:123], v[160:163], v[92:95]
	v_mfma_f32_16x16x32_bf16 v[88:91], v[128:131], v[160:163], v[88:91]
	s_waitcnt lgkmcnt(1)
	v_mfma_f32_16x16x32_bf16 v[76:79], v[120:123], v[168:171], v[76:79]
	v_mfma_f32_16x16x32_bf16 v[72:75], v[128:131], v[168:171], v[72:75]
	v_mfma_f32_16x16x32_bf16 v[148:151], v[124:127], v[140:143], v[148:151]
	v_mfma_f32_16x16x32_bf16 v[144:147], v[132:135], v[140:143], v[144:147]
	v_mfma_f32_16x16x32_bf16 v[108:111], v[124:127], v[156:159], v[108:111]
	v_mfma_f32_16x16x32_bf16 v[104:107], v[132:135], v[156:159], v[104:107]
	v_mfma_f32_16x16x32_bf16 v[92:95], v[124:127], v[164:167], v[92:95]
	v_mfma_f32_16x16x32_bf16 v[88:91], v[132:135], v[164:167], v[88:91]
	s_waitcnt lgkmcnt(0)
	v_mfma_f32_16x16x32_bf16 v[76:79], v[124:127], v[172:175], v[76:79]
	v_mfma_f32_16x16x32_bf16 v[72:75], v[132:135], v[172:175], v[72:75]
	s_setprio 0
	s_barrier
	v_add_u32_e32 v200, 0x14000, v236
	ds_read_b128 v[176:179], v200
	ds_read_b128 v[180:183], v200 offset:1024
	ds_read_b128 v[184:187], v200 offset:2048
	ds_read_b128 v[200:203], v200 offset:3072
	s_cselect_b32 s64, s55, s69
	s_cselect_b32 s65, s53, s70
	s_mov_b32 m0, s24
	s_nop 0
	global_load_lds_dwordx4 v188, s[64:65]
	s_add_u32 s48, s64, 0x2000
	s_addc_u32 s49, s65, 0
	s_mov_b32 m0, s25
	s_nop 0
	global_load_lds_dwordx4 v188, s[48:49]
	s_waitcnt vmcnt(10)
	s_barrier
	s_waitcnt lgkmcnt(0)
	s_setprio 1
	s_waitcnt lgkmcnt(3)
	v_mfma_f32_16x16x32_bf16 v[116:119], v[176:179], v[136:139], v[116:119]
	s_waitcnt lgkmcnt(1)
	v_mfma_f32_16x16x32_bf16 v[112:115], v[184:187], v[136:139], v[112:115]
	v_mfma_f32_16x16x32_bf16 v[100:103], v[176:179], v[152:155], v[100:103]
	v_mfma_f32_16x16x32_bf16 v[96:99], v[184:187], v[152:155], v[96:99]
	v_mfma_f32_16x16x32_bf16 v[84:87], v[176:179], v[160:163], v[84:87]
	v_mfma_f32_16x16x32_bf16 v[80:83], v[184:187], v[160:163], v[80:83]
	v_mfma_f32_16x16x32_bf16 v[68:71], v[176:179], v[168:171], v[68:71]
	v_mfma_f32_16x16x32_bf16 v[64:67], v[184:187], v[168:171], v[64:67]
	v_mfma_f32_16x16x32_bf16 v[116:119], v[180:183], v[140:143], v[116:119]
	s_waitcnt lgkmcnt(0)
	v_mfma_f32_16x16x32_bf16 v[112:115], v[200:203], v[140:143], v[112:115]
	v_mfma_f32_16x16x32_bf16 v[100:103], v[180:183], v[156:159], v[100:103]
	v_mfma_f32_16x16x32_bf16 v[96:99], v[200:203], v[156:159], v[96:99]
	v_mfma_f32_16x16x32_bf16 v[84:87], v[180:183], v[164:167], v[84:87]
	v_mfma_f32_16x16x32_bf16 v[80:83], v[200:203], v[164:167], v[80:83]
	v_mfma_f32_16x16x32_bf16 v[68:71], v[180:183], v[172:175], v[68:71]
	v_mfma_f32_16x16x32_bf16 v[64:67], v[200:203], v[172:175], v[64:67]
	s_setprio 0
	s_barrier
	ds_read_b128 v[136:139], v237 offset:16384
	ds_read_b128 v[140:143], v237 offset:17408
	ds_read_b128 v[152:155], v237 offset:18432
	ds_read_b128 v[156:159], v237 offset:19456
	ds_read_b128 v[160:163], v237 offset:20480
	ds_read_b128 v[164:167], v237 offset:21504
	ds_read_b128 v[168:171], v237 offset:22528
	ds_read_b128 v[172:175], v237 offset:23552
	s_mov_b32 m0, s22
	s_nop 0
	global_load_lds_dwordx4 v188, s[60:61]
	s_add_u32 s48, s60, 0x2000
	s_addc_u32 s49, s61, 0
	s_mov_b32 m0, s26
	s_nop 0
	global_load_lds_dwordx4 v188, s[48:49]
	s_barrier
	s_waitcnt lgkmcnt(0)
	s_setprio 1
	s_waitcnt lgkmcnt(7)
	v_mfma_f32_16x16x32_bf16 v[60:63], v[120:123], v[136:139], v[60:63]
	v_mfma_f32_16x16x32_bf16 v[56:59], v[128:131], v[136:139], v[56:59]
	s_waitcnt lgkmcnt(5)
	v_mfma_f32_16x16x32_bf16 v[44:47], v[120:123], v[152:155], v[44:47]
	v_mfma_f32_16x16x32_bf16 v[40:43], v[128:131], v[152:155], v[40:43]
	s_waitcnt lgkmcnt(3)
	v_mfma_f32_16x16x32_bf16 v[28:31], v[120:123], v[160:163], v[28:31]
	v_mfma_f32_16x16x32_bf16 v[24:27], v[128:131], v[160:163], v[24:27]
	s_waitcnt lgkmcnt(1)
	v_mfma_f32_16x16x32_bf16 v[12:15], v[120:123], v[168:171], v[12:15]
	v_mfma_f32_16x16x32_bf16 v[8:11], v[128:131], v[168:171], v[8:11]
	v_mfma_f32_16x16x32_bf16 v[60:63], v[124:127], v[140:143], v[60:63]
	v_mfma_f32_16x16x32_bf16 v[56:59], v[132:135], v[140:143], v[56:59]
	v_mfma_f32_16x16x32_bf16 v[44:47], v[124:127], v[156:159], v[44:47]
	v_mfma_f32_16x16x32_bf16 v[40:43], v[132:135], v[156:159], v[40:43]
	v_mfma_f32_16x16x32_bf16 v[28:31], v[124:127], v[164:167], v[28:31]
	v_mfma_f32_16x16x32_bf16 v[24:27], v[132:135], v[164:167], v[24:27]
	s_waitcnt lgkmcnt(0)
	v_mfma_f32_16x16x32_bf16 v[12:15], v[124:127], v[172:175], v[12:15]
	v_mfma_f32_16x16x32_bf16 v[8:11], v[132:135], v[172:175], v[8:11]
	s_setprio 0
	s_barrier
; #define PG8_STAGE(bufoff, gbase, hoff, imm) do { _Pragma("unroll") for (int _i = 0; _i < 2; ++_i) { \
;         asm volatile("s_mov_b32 m0, %0\n\ts_nop 0\n\tglobal_load_lds_dwordx4 %1, %2" \
;             :: "s"(lds0 + (unsigned)((bufoff) + _i * 8192)), "v"(voff0), "s"((const char*)(gbase) + (size_t)(hoff) + (size_t)(_i * 8192)) : "memory"); } } while (0)
; #define PG8_LDA(dst, b, h) do { _Pragma("unroll") for (int m = 0; m < 4; ++m) _Pragma("unroll") for (int k = 0; k < 2; ++k) dst[m][k] = *(const LAS bf16x8*)(lds + PG8_SA(b, h) + aoff + m * 2048 + k * 1024); } while (0)
; #define PG8_LDB(dst, b, h) do { _Pragma("unroll") for (int n = 0; n < 2; ++n) _Pragma("unroll") for (int k = 0; k < 2; ++k) dst[n][k] = *(const LAS bf16x8*)(lds + PG8_SB(b, h) + boff + n * 2048 + k * 1024); } while (0)
; #define PG8_MMA(ai, bj, At, Bt) do { __builtin_amdgcn_s_setprio(1); _Pragma("unroll") for (int m = 0; m < 4; ++m) _Pragma("unroll") for (int n = 0; n < 2; ++n) _Pragma("unroll") for (int k = 0; k < 2; ++k) \
;         acc[ai][bj][m][n] = __builtin_amdgcn_mfma_f32_16x16x32_bf16(Bt[n][k], At[m][k], acc[ai][bj][m][n], 0, 0, 0); __builtin_amdgcn_s_setprio(0); } while (0)
; #define PG8_WAIT_V(n) asm volatile("s_waitcnt vmcnt(" #n ")" ::: "memory")
; #define PG8_WAIT_L(n) asm volatile("s_waitcnt lgkmcnt(" #n ")" ::: "memory")
; #define PG8_BAR __builtin_amdgcn_s_barrier()
; #define PG8_SCHED __builtin_amdgcn_sched_barrier(0)
; template <class Epi>
; __device__ __forceinline__ void gemm_phase(LAS unsigned char* lds, const Gemm g, const StaticOrder& S, const Epi& E) {
;     ...
;             PG8_STAGE(PG8_SB(0, 1), b2, hB, 0);
;             PG8_WAIT_V(6); PG8_BAR; PG8_MMA(1, 1, At, B1); PG8_BAR;
;             PG8_LDB(B0, 1, 0); PG8_SCHED; PG8_LDA(At, 1, 0); PG8_STAGE(PG8_SA(0, 1), a2, hA, 0);
;             PG8_WAIT_L(8); PG8_BAR; PG8_WAIT_L(0); PG8_MMA(0, 0, At, B0); PG8_BAR; PG8_SCHED;
;             PG8_LDB(B1, 1, 1); PG8_STAGE(PG8_SB(1, 0), b2 + KS, 0, 0);
;             PG8_BAR; PG8_WAIT_L(0); PG8_MMA(0, 1, At, B1); PG8_BAR;
;             PG8_LDA(At, 1, 1); PG8_STAGE(PG8_SA(1, 0), a2 + KS, 0, 0);
	s_add_u32 s48, s64, 0x80000
	s_addc_u32 s49, s65, 0
	s_mov_b32 m0, s27
	s_nop 0
	global_load_lds_dwordx4 v188, s[48:49]
	s_add_u32 s48, s64, 0x82000
	s_addc_u32 s49, s65, 0
	s_mov_b32 m0, s28
	s_nop 0
	global_load_lds_dwordx4 v188, s[48:49]
	s_waitcnt vmcnt(10)
	s_barrier
	s_setprio 1
	v_mfma_f32_16x16x32_bf16 v[52:55], v[176:179], v[136:139], v[52:55]
	v_mfma_f32_16x16x32_bf16 v[48:51], v[184:187], v[136:139], v[48:51]
	v_mfma_f32_16x16x32_bf16 v[36:39], v[176:179], v[152:155], v[36:39]
	v_mfma_f32_16x16x32_bf16 v[32:35], v[184:187], v[152:155], v[32:35]
	v_mfma_f32_16x16x32_bf16 v[20:23], v[176:179], v[160:163], v[20:23]
	v_mfma_f32_16x16x32_bf16 v[16:19], v[184:187], v[160:163], v[16:19]
	v_mfma_f32_16x16x32_bf16 v[4:7], v[176:179], v[168:171], v[4:7]
	v_mfma_f32_16x16x32_bf16 v[0:3], v[184:187], v[168:171], v[0:3]
	v_mfma_f32_16x16x32_bf16 v[52:55], v[180:183], v[140:143], v[52:55]
	v_mfma_f32_16x16x32_bf16 v[48:51], v[200:203], v[140:143], v[48:51]
	v_mfma_f32_16x16x32_bf16 v[36:39], v[180:183], v[156:159], v[36:39]
	v_mfma_f32_16x16x32_bf16 v[32:35], v[200:203], v[156:159], v[32:35]
	v_mfma_f32_16x16x32_bf16 v[20:23], v[180:183], v[164:167], v[20:23]
	v_mfma_f32_16x16x32_bf16 v[16:19], v[200:203], v[164:167], v[16:19]
	v_mfma_f32_16x16x32_bf16 v[4:7], v[180:183], v[172:175], v[4:7]
	v_mfma_f32_16x16x32_bf16 v[0:3], v[200:203], v[172:175], v[0:3]
	s_setprio 0
	v_add_u32_e32 v132, 0x18000, v236
	s_barrier
	ds_read_b128 v[120:123], v132
	ds_read_b128 v[124:127], v132 offset:1024
	ds_read_b128 v[128:131], v132 offset:2048
	ds_read_b128 v[132:135], v132 offset:3072
	ds_read_b128 v[136:139], v237 offset:32768
	ds_read_b128 v[140:143], v237 offset:33792
	ds_read_b128 v[152:155], v237 offset:34816
	ds_read_b128 v[156:159], v237 offset:35840
	ds_read_b128 v[160:163], v237 offset:36864
	ds_read_b128 v[164:167], v237 offset:37888
	ds_read_b128 v[168:171], v237 offset:38912
	ds_read_b128 v[172:175], v237 offset:39936
	s_add_u32 s48, s60, 0x80000
	s_addc_u32 s49, s61, 0
	s_mov_b32 m0, s29
	s_nop 0
	global_load_lds_dwordx4 v188, s[48:49]
	s_add_u32 s48, s60, 0x82000
	s_addc_u32 s49, s61, 0
	s_mov_b32 m0, s30
	s_nop 0
	global_load_lds_dwordx4 v188, s[48:49]
	s_waitcnt lgkmcnt(8)
	s_waitcnt vmcnt(10)
	s_barrier
	s_waitcnt lgkmcnt(0)
	s_setprio 1
	s_waitcnt lgkmcnt(7)
	v_mfma_f32_16x16x32_bf16 v[148:151], v[120:123], v[136:139], v[148:151]
	v_mfma_f32_16x16x32_bf16 v[144:147], v[128:131], v[136:139], v[144:147]
	s_waitcnt lgkmcnt(5)
	v_mfma_f32_16x16x32_bf16 v[108:111], v[120:123], v[152:155], v[108:111]
	v_mfma_f32_16x16x32_bf16 v[104:107], v[128:131], v[152:155], v[104:107]
	s_waitcnt lgkmcnt(3)
	v_mfma_f32_16x16x32_bf16 v[92:95], v[120:123], v[160:163], v[92:95]
	v_mfma_f32_16x16x32_bf16 v[88:91], v[128:131], v[160:163], v[88:91]
	s_waitcnt lgkmcnt(1)
	v_mfma_f32_16x16x32_bf16 v[76:79], v[120:123], v[168:171], v[76:79]
	v_mfma_f32_16x16x32_bf16 v[72:75], v[128:131], v[168:171], v[72:75]
	v_mfma_f32_16x16x32_bf16 v[148:151], v[124:127], v[140:143], v[148:151]
	v_mfma_f32_16x16x32_bf16 v[144:147], v[132:135], v[140:143], v[144:147]
	v_mfma_f32_16x16x32_bf16 v[108:111], v[124:127], v[156:159], v[108:111]
	v_mfma_f32_16x16x32_bf16 v[104:107], v[132:135], v[156:159], v[104:107]
	v_mfma_f32_16x16x32_bf16 v[92:95], v[124:127], v[164:167], v[92:95]
	v_mfma_f32_16x16x32_bf16 v[88:91], v[132:135], v[164:167], v[88:91]
	s_waitcnt lgkmcnt(0)
	v_mfma_f32_16x16x32_bf16 v[76:79], v[124:127], v[172:175], v[76:79]
	v_mfma_f32_16x16x32_bf16 v[72:75], v[132:135], v[172:175], v[72:75]
	s_setprio 0
	s_barrier
	v_add_u32_e32 v200, 0x1c000, v236
	ds_read_b128 v[176:179], v200
	ds_read_b128 v[180:183], v200 offset:1024
	ds_read_b128 v[184:187], v200 offset:2048
	ds_read_b128 v[200:203], v200 offset:3072
	s_add_u32 s48, s64, 0x4000
	s_addc_u32 s49, s65, 0
	s_mov_b32 m0, s39
	s_nop 0
	global_load_lds_dwordx4 v188, s[48:49]
	s_add_u32 s48, s64, 0x6000
	s_addc_u32 s49, s65, 0
	s_mov_b32 m0, s40
	s_nop 0
	global_load_lds_dwordx4 v188, s[48:49]
	s_waitcnt vmcnt(10)
	s_barrier
	s_waitcnt lgkmcnt(0)
	s_setprio 1
	s_waitcnt lgkmcnt(3)
	v_mfma_f32_16x16x32_bf16 v[116:119], v[176:179], v[136:139], v[116:119]
	s_waitcnt lgkmcnt(1)
	v_mfma_f32_16x16x32_bf16 v[112:115], v[184:187], v[136:139], v[112:115]
	v_mfma_f32_16x16x32_bf16 v[100:103], v[176:179], v[152:155], v[100:103]
	v_mfma_f32_16x16x32_bf16 v[96:99], v[184:187], v[152:155], v[96:99]
	v_mfma_f32_16x16x32_bf16 v[84:87], v[176:179], v[160:163], v[84:87]
	v_mfma_f32_16x16x32_bf16 v[80:83], v[184:187], v[160:163], v[80:83]
	v_mfma_f32_16x16x32_bf16 v[68:71], v[176:179], v[168:171], v[68:71]
	v_mfma_f32_16x16x32_bf16 v[64:67], v[184:187], v[168:171], v[64:67]
	v_mfma_f32_16x16x32_bf16 v[116:119], v[180:183], v[140:143], v[116:119]
	s_waitcnt lgkmcnt(0)
	v_mfma_f32_16x16x32_bf16 v[112:115], v[200:203], v[140:143], v[112:115]
	v_mfma_f32_16x16x32_bf16 v[100:103], v[180:183], v[156:159], v[100:103]
	v_mfma_f32_16x16x32_bf16 v[96:99], v[200:203], v[156:159], v[96:99]
	v_mfma_f32_16x16x32_bf16 v[84:87], v[180:183], v[164:167], v[84:87]
	v_mfma_f32_16x16x32_bf16 v[80:83], v[200:203], v[164:167], v[80:83]
	v_mfma_f32_16x16x32_bf16 v[68:71], v[180:183], v[172:175], v[68:71]
	v_mfma_f32_16x16x32_bf16 v[64:67], v[200:203], v[172:175], v[64:67]
	s_setprio 0
	s_barrier
	ds_read_b128 v[136:139], v237 offset:49152
	ds_read_b128 v[140:143], v237 offset:50176
	ds_read_b128 v[152:155], v237 offset:51200
	ds_read_b128 v[156:159], v237 offset:52224
	ds_read_b128 v[160:163], v237 offset:53248
	ds_read_b128 v[164:167], v237 offset:54272
	ds_read_b128 v[168:171], v237 offset:55296
	ds_read_b128 v[172:175], v237 offset:56320
	s_add_u32 s48, s60, 0x4000
	s_addc_u32 s49, s61, 0
	s_mov_b32 m0, s41
	s_nop 0
	global_load_lds_dwordx4 v188, s[48:49]
	s_add_u32 s48, s60, 0x6000
	s_addc_u32 s49, s61, 0
	s_mov_b32 m0, s42
	s_nop 0
	global_load_lds_dwordx4 v188, s[48:49]
	s_barrier
; #define PG8_WAIT_V(n) asm volatile("s_waitcnt vmcnt(" #n ")" ::: "memory")
; template <class Epi>
; __device__ __forceinline__ void gemm_phase(LAS unsigned char* lds, const Gemm g, const StaticOrder& S, const Epi& E) {
;     ...
;             PG8_LDA(At, 1, 1); PG8_STAGE(PG8_SA(1, 0), a2 + KS, 0, 0);
;             PG8_BAR; PG8_WAIT_L(0); PG8_MMA(1, 0, At, B0); PG8_BAR; PG8_SCHED;
;             PG8_STAGE(PG8_SB(1, 1), b2 + KS, hB, 0);
;             PG8_WAIT_V(6); PG8_BAR; PG8_MMA(1, 1, At, B1); PG8_BAR;
;     __device__ __forceinline__ void operator()(f32x4 (&acc)[2][2][4][2], const Unit& u, int wr, int wc, int fr, int fq, LAS unsigned char*) const {
;         const int b = u.pm >> 6;
;         const int col0 = u.pn * BM + wc * 32 + 8 * fq;
;         const size_t off0 = (size_t)(u.pm * BM + wr * 64 + fr) * D + col0;
;         f32x4 sc[2][2];
; #pragma unroll
;         for (int bj = 0; bj < 2; ++bj)
; #pragma unroll
;             for (int n = 0; n < 2; ++n) { f32x4 gt = *(const f32x4*)(gate + (size_t)b * MODW + col0 + bj * HALF + n * 4); sc[bj][n] = gt + 1.0f;
;                 if (cs) sc[bj][n] *= *(const f32x4*)(cs + col0 + bj * HALF + n * 4); }
;         if (IN_F32) {
; #pragma unroll
;             for (int ai = 0; ai < 2; ++ai) {
;                 f32x4 r[4][2][2];
; #pragma unroll
;                 for (int m = 0; m < 4; ++m)
; #pragma unroll
;                     for (int bj = 0; bj < 2; ++bj)
; #pragma unroll
;                         for (int n = 0; n < 2; ++n) r[m][bj][n] = *(const f32x4*)((const float*)in + off0 + (size_t)(ai * HALF + m * 16) * D + bj * HALF + n * 4);
; #pragma unroll
;                 for (int m = 0; m < 4; ++m)
; #pragma unroll
;                     for (int bj = 0; bj < 2; ++bj) { const f32x4 r0 = r[m][bj][0] + sc[bj][0] * acc[ai][bj][m][0], r1 = r[m][bj][1] + sc[bj][1] * acc[ai][bj][m][1];
;                         u32x4 w; w.x = cvt_pk_bf16(r0[0], r0[1]); w.y = cvt_pk_bf16(r0[2], r0[3]); w.z = cvt_pk_bf16(r1[0], r1[1]); w.w = cvt_pk_bf16(r1[2], r1[3]);
;                         *(u32x4*)(out + off0 + (size_t)(ai * HALF + m * 16) * D + bj * HALF) = w; }
;                 asm volatile("" ::: "memory");
;             }
;         } else {
;             u32x4 xb[2][4][2];
; #pragma unroll
;             for (int ai = 0; ai < 2; ++ai)
; #pragma unroll
;                 for (int m = 0; m < 4; ++m)
; #pragma unroll
	s_waitcnt lgkmcnt(0)
	s_setprio 1
	s_waitcnt lgkmcnt(7)
	v_mfma_f32_16x16x32_bf16 v[60:63], v[120:123], v[136:139], v[60:63]
	v_mfma_f32_16x16x32_bf16 v[56:59], v[128:131], v[136:139], v[56:59]
	s_waitcnt lgkmcnt(5)
	v_mfma_f32_16x16x32_bf16 v[44:47], v[120:123], v[152:155], v[44:47]
	v_mfma_f32_16x16x32_bf16 v[40:43], v[128:131], v[152:155], v[40:43]
	s_waitcnt lgkmcnt(3)
	v_mfma_f32_16x16x32_bf16 v[28:31], v[120:123], v[160:163], v[28:31]
	v_mfma_f32_16x16x32_bf16 v[24:27], v[128:131], v[160:163], v[24:27]
	s_waitcnt lgkmcnt(1)
	v_mfma_f32_16x16x32_bf16 v[12:15], v[120:123], v[168:171], v[12:15]
	v_mfma_f32_16x16x32_bf16 v[8:11], v[128:131], v[168:171], v[8:11]
	v_mfma_f32_16x16x32_bf16 v[60:63], v[124:127], v[140:143], v[60:63]
	v_mfma_f32_16x16x32_bf16 v[56:59], v[132:135], v[140:143], v[56:59]
	v_mfma_f32_16x16x32_bf16 v[44:47], v[124:127], v[156:159], v[44:47]
	v_mfma_f32_16x16x32_bf16 v[40:43], v[132:135], v[156:159], v[40:43]
	v_mfma_f32_16x16x32_bf16 v[28:31], v[124:127], v[164:167], v[28:31]
	v_mfma_f32_16x16x32_bf16 v[24:27], v[132:135], v[164:167], v[24:27]
	s_waitcnt lgkmcnt(0)
	v_mfma_f32_16x16x32_bf16 v[12:15], v[124:127], v[172:175], v[12:15]
	v_mfma_f32_16x16x32_bf16 v[8:11], v[132:135], v[172:175], v[8:11]
	s_setprio 0
	s_barrier
	s_add_u32 s48, s64, 0x84000
	s_addc_u32 s49, s65, 0
	s_mov_b32 m0, s43
	s_nop 0
	global_load_lds_dwordx4 v188, s[48:49]
	s_add_u32 s48, s64, 0x86000
	s_addc_u32 s49, s65, 0
	s_mov_b32 m0, s66
	s_nop 0
	global_load_lds_dwordx4 v188, s[48:49]
	s_waitcnt vmcnt(10)
	s_barrier
	s_setprio 1
	v_mfma_f32_16x16x32_bf16 v[52:55], v[176:179], v[136:139], v[52:55]
	v_mfma_f32_16x16x32_bf16 v[48:51], v[184:187], v[136:139], v[48:51]
	v_mfma_f32_16x16x32_bf16 v[36:39], v[176:179], v[152:155], v[36:39]
	v_mfma_f32_16x16x32_bf16 v[32:35], v[184:187], v[152:155], v[32:35]
	v_mfma_f32_16x16x32_bf16 v[20:23], v[176:179], v[160:163], v[20:23]
	v_mfma_f32_16x16x32_bf16 v[16:19], v[184:187], v[160:163], v[16:19]
	v_mfma_f32_16x16x32_bf16 v[4:7], v[176:179], v[168:171], v[4:7]
	v_mfma_f32_16x16x32_bf16 v[0:3], v[184:187], v[168:171], v[0:3]
	v_mfma_f32_16x16x32_bf16 v[52:55], v[180:183], v[140:143], v[52:55]
	v_mfma_f32_16x16x32_bf16 v[48:51], v[200:203], v[140:143], v[48:51]
	v_mfma_f32_16x16x32_bf16 v[36:39], v[180:183], v[156:159], v[36:39]
	v_mfma_f32_16x16x32_bf16 v[32:35], v[200:203], v[156:159], v[32:35]
	v_mfma_f32_16x16x32_bf16 v[20:23], v[180:183], v[164:167], v[20:23]
	v_mfma_f32_16x16x32_bf16 v[16:19], v[200:203], v[164:167], v[16:19]
	v_mfma_f32_16x16x32_bf16 v[4:7], v[180:183], v[172:175], v[4:7]
	v_mfma_f32_16x16x32_bf16 v[0:3], v[200:203], v[172:175], v[0:3]
	s_setprio 0
	s_add_i32 s71, s71, 2
	s_add_u32 s69, s69, 0x8000
	s_addc_u32 s70, s70, 0
	s_cmp_gt_u32 s71, 29
	s_mov_b64 s[60:61], s[62:63]
	s_barrier
	s_cbranch_scc0 .LBB0_610
	s_ashr_i32 s0, s50, 6
	s_mul_hi_i32 s1, s0, 0xc000
	s_mul_i32 s0, s0, 0xc000
	v_lshl_or_b32 v128, s51, 8, v234
	s_add_u32 s0, s37, s0
	v_ashrrev_i32_e32 v129, 31, v128
	s_addc_u32 s1, s38, s1
	v_lshl_add_u64 v[130:131], v[128:129], 2, s[0:1]
	global_load_dwordx4 v[120:123], v[130:131], off offset:16
	global_load_dwordx4 v[124:127], v[130:131], off
	s_mov_b32 s51, s52
	s_mov_b64 s[62:63], s[58:59]
	s_mov_b64 s[60:61], s[56:57]
	s_waitcnt vmcnt(1)
	v_pk_add_f32 v[210:211], v[122:123], 1.0 op_sel_hi:[1,0]
	s_waitcnt vmcnt(0)
	v_pk_add_f32 v[214:215], v[126:127], 1.0 op_sel_hi:[1,0]
	v_pk_add_f32 v[212:213], v[124:125], 1.0 op_sel_hi:[1,0]
	v_pk_add_f32 v[208:209], v[120:121], 1.0 op_sel_hi:[1,0]
	global_load_dwordx4 v[120:123], v[130:131], off offset:528
	global_load_dwordx4 v[124:127], v[130:131], off offset:512
	s_waitcnt vmcnt(1)
	v_pk_add_f32 v[200:201], v[120:121], 1.0 op_sel_hi:[1,0]
	v_lshl_add_u32 v120, s50, 8, v233
	v_ashrrev_i32_e32 v121, 31, v120
	v_lshlrev_b64 v[120:121], 11, v[120:121]
	v_lshl_add_u64 v[120:121], v[120:121], 0, v[128:129]
	v_lshlrev_b64 v[216:217], 1, v[120:121]
	v_lshl_add_u64 v[120:121], s[8:9], 0, v[216:217]
	global_load_dwordx4 v[238:241], v[120:121], off
	global_load_dwordx4 v[184:187], v[120:121], off offset:256
	v_pk_add_f32 v[202:203], v[122:123], 1.0 op_sel_hi:[1,0]
	v_add_co_u32_e32 v122, vcc, s45, v120
	s_waitcnt vmcnt(2)
	v_pk_add_f32 v[206:207], v[126:127], 1.0 op_sel_hi:[1,0]
	v_addc_co_u32_e32 v123, vcc, 0, v121, vcc
	global_load_dwordx4 v[180:183], v[122:123], off
	global_load_dwordx4 v[176:179], v[122:123], off offset:256
	v_add_co_u32_e32 v122, vcc, s36, v120
	v_pk_add_f32 v[204:205], v[124:125], 1.0 op_sel_hi:[1,0]
	s_nop 0
	v_addc_co_u32_e32 v123, vcc, 0, v121, vcc
	global_load_dwordx4 v[172:175], v[122:123], off
	global_load_dwordx4 v[168:171], v[122:123], off offset:256
	v_add_co_u32_e32 v122, vcc, s23, v120
	s_mov_b32 s50, s54
	s_nop 0
	v_addc_co_u32_e32 v123, vcc, 0, v121, vcc
	global_load_dwordx4 v[164:167], v[122:123], off
	global_load_dwordx4 v[160:163], v[122:123], off offset:256
	v_add_co_u32_e32 v122, vcc, s93, v120
	s_waitcnt vmcnt(7)
; __device__ __forceinline__ unsigned cvt_pk_bf16(float lo, float hi) { unsigned r; asm volatile("v_cvt_pk_bf16_f32 %0, %1, %2" : "=v"(r) : "v"(lo), "v"(hi)); return r; }
;     __device__ __forceinline__ void operator()(f32x4 (&acc)[2][2][4][2], const Unit& u, int wr, int wc, int fr, int fq, LAS unsigned char*) const {
;     ...
;             u32x4 xb[2][4][2];
; #pragma unroll
;             for (int ai = 0; ai < 2; ++ai)
; #pragma unroll
;                 for (int m = 0; m < 4; ++m)
; #pragma unroll
;                     for (int bj = 0; bj < 2; ++bj) xb[ai][m][bj] = *(const u32x4*)((const bf16_t*)in + off0 + (size_t)(ai * HALF + m * 16) * D + bj * HALF);
; #pragma unroll
;             for (int ai = 0; ai < 2; ++ai)
; #pragma unroll
;                 for (int m = 0; m < 4; ++m)
; #pragma unroll
;                     for (int bj = 0; bj < 2; ++bj) { const u32x4 x = xb[ai][m][bj];
;                         f32x4 r0 = (f32x4){__uint_as_float(x.x << 16), __uint_as_float(x.x & 0xffff0000u), __uint_as_float(x.y << 16), __uint_as_float(x.y & 0xffff0000u)};
;                         f32x4 r1 = (f32x4){__uint_as_float(x.z << 16), __uint_as_float(x.z & 0xffff0000u), __uint_as_float(x.w << 16), __uint_as_float(x.w & 0xffff0000u)};
;                         r0 += sc[bj][0] * acc[ai][bj][m][0]; r1 += sc[bj][1] * acc[ai][bj][m][1];
;                         u32x4 w; w.x = cvt_pk_bf16(r0[0], r0[1]); w.y = cvt_pk_bf16(r0[2], r0[3]); w.z = cvt_pk_bf16(r1[0], r1[1]); w.w = cvt_pk_bf16(r1[2], r1[3]);
;                         *(u32x4*)(out + off0 + (size_t)(ai * HALF + m * 16) * D + bj * HALF) = w; }
	v_lshlrev_b32_e32 v230, 16, v238
	v_addc_co_u32_e32 v123, vcc, 0, v121, vcc
	global_load_dwordx4 v[156:159], v[122:123], off
	global_load_dwordx4 v[152:155], v[122:123], off offset:256
	v_add_co_u32_e32 v122, vcc, s33, v120
	v_and_b32_e32 v231, 0xffff0000, v238
	s_nop 0
	v_addc_co_u32_e32 v123, vcc, 0, v121, vcc
	global_load_dwordx4 v[140:143], v[122:123], off
	global_load_dwordx4 v[136:139], v[122:123], off offset:256
	v_add_co_u32_e32 v122, vcc, s18, v120
	v_lshlrev_b32_e32 v242, 16, v240
	s_nop 0
	v_addc_co_u32_e32 v123, vcc, 0, v121, vcc
	global_load_dwordx4 v[132:135], v[122:123], off
	global_load_dwordx4 v[128:131], v[122:123], off offset:256
	v_add_co_u32_e32 v120, vcc, s19, v120
	v_and_b32_e32 v243, 0xffff0000, v240
	s_nop 0
	v_addc_co_u32_e32 v121, vcc, 0, v121, vcc
	global_load_dwordx4 v[124:127], v[120:121], off
	s_nop 0
	global_load_dwordx4 v[120:123], v[120:121], off offset:256
	v_lshlrev_b32_e32 v238, 16, v239
	v_and_b32_e32 v239, 0xffff0000, v239
	v_lshlrev_b32_e32 v240, 16, v241
	v_and_b32_e32 v241, 0xffff0000, v241
	v_pk_fma_f32 v[148:149], v[148:149], v[212:213], v[230:231]
	v_pk_fma_f32 v[144:145], v[144:145], v[208:209], v[242:243]
	v_pk_fma_f32 v[150:151], v[150:151], v[214:215], v[238:239]
	v_pk_fma_f32 v[230:231], v[146:147], v[210:211], v[240:241]
	v_cvt_pk_bf16_f32 v146, v148, v149
	v_cvt_pk_bf16_f32 v147, v150, v151
	v_cvt_pk_bf16_f32 v148, v144, v145
	v_lshl_add_u64 v[144:145], s[10:11], 0, v[216:217]
	v_cvt_pk_bf16_f32 v149, v230, v231
	global_store_dwordx4 v[144:145], v[146:149], off
	s_waitcnt vmcnt(15)
	v_lshlrev_b32_e32 v150, 16, v186
	v_and_b32_e32 v151, 0xffff0000, v186
	v_lshlrev_b32_e32 v146, 16, v184
	v_and_b32_e32 v147, 0xffff0000, v184
	v_lshlrev_b32_e32 v148, 16, v185
	v_and_b32_e32 v149, 0xffff0000, v185
	v_lshlrev_b32_e32 v184, 16, v187
	v_and_b32_e32 v185, 0xffff0000, v187
	v_pk_fma_f32 v[118:119], v[118:119], v[206:207], v[148:149]
	v_pk_fma_f32 v[116:117], v[116:117], v[204:205], v[146:147]
	v_pk_fma_f32 v[146:147], v[114:115], v[202:203], v[184:185]
	v_pk_fma_f32 v[114:115], v[112:113], v[200:201], v[150:151]
	v_cvt_pk_bf16_f32 v112, v116, v117
	v_cvt_pk_bf16_f32 v113, v118, v119
	s_waitcnt vmcnt(14)
	v_lshlrev_b32_e32 v116, 16, v182
	v_cvt_pk_bf16_f32 v114, v114, v115
	v_cvt_pk_bf16_f32 v115, v146, v147
	global_store_dwordx4 v[144:145], v[112:115], off offset:256
	v_and_b32_e32 v117, 0xffff0000, v182
	v_lshlrev_b32_e32 v118, 16, v183
	v_lshlrev_b32_e32 v112, 16, v180
	v_and_b32_e32 v113, 0xffff0000, v180
	v_and_b32_e32 v119, 0xffff0000, v183
	v_pk_fma_f32 v[108:109], v[108:109], v[212:213], v[112:113]
	v_lshlrev_b32_e32 v114, 16, v181
	v_and_b32_e32 v115, 0xffff0000, v181
	v_pk_fma_f32 v[112:113], v[106:107], v[210:211], v[118:119]
	v_pk_fma_f32 v[106:107], v[104:105], v[208:209], v[116:117]
	v_cvt_pk_bf16_f32 v104, v108, v109
	v_add_co_u32_e32 v108, vcc, s45, v144
	v_pk_fma_f32 v[110:111], v[110:111], v[214:215], v[114:115]
	s_nop 0
	v_addc_co_u32_e32 v109, vcc, 0, v145, vcc
	v_cvt_pk_bf16_f32 v105, v110, v111
	v_cvt_pk_bf16_f32 v106, v106, v107
	v_cvt_pk_bf16_f32 v107, v112, v113
	global_store_dwordx4 v[108:109], v[104:107], off
	s_waitcnt vmcnt(15)
	v_lshlrev_b32_e32 v110, 16, v178
	v_and_b32_e32 v111, 0xffff0000, v178
	v_lshlrev_b32_e32 v104, 16, v176
	v_and_b32_e32 v105, 0xffff0000, v176
	v_lshlrev_b32_e32 v106, 16, v177
	v_and_b32_e32 v107, 0xffff0000, v177
	v_lshlrev_b32_e32 v112, 16, v179
	v_and_b32_e32 v113, 0xffff0000, v179
	v_pk_fma_f32 v[102:103], v[102:103], v[206:207], v[106:107]
	v_pk_fma_f32 v[100:101], v[100:101], v[204:205], v[104:105]
	v_pk_fma_f32 v[104:105], v[98:99], v[202:203], v[112:113]
	v_pk_fma_f32 v[98:99], v[96:97], v[200:201], v[110:111]
	v_cvt_pk_bf16_f32 v96, v100, v101
	v_cvt_pk_bf16_f32 v97, v102, v103
	s_waitcnt vmcnt(14)
	v_lshlrev_b32_e32 v100, 16, v174
	v_cvt_pk_bf16_f32 v98, v98, v99
	v_cvt_pk_bf16_f32 v99, v104, v105
	global_store_dwordx4 v[108:109], v[96:99], off offset:256
	v_and_b32_e32 v101, 0xffff0000, v174
	v_lshlrev_b32_e32 v102, 16, v175
	v_lshlrev_b32_e32 v96, 16, v172
	v_and_b32_e32 v97, 0xffff0000, v172
	v_and_b32_e32 v103, 0xffff0000, v175
	v_pk_fma_f32 v[92:93], v[92:93], v[212:213], v[96:97]
	v_lshlrev_b32_e32 v98, 16, v173
	v_and_b32_e32 v99, 0xffff0000, v173
	v_pk_fma_f32 v[96:97], v[90:91], v[210:211], v[102:103]
	v_pk_fma_f32 v[90:91], v[88:89], v[208:209], v[100:101]
	v_cvt_pk_bf16_f32 v88, v92, v93
	v_add_co_u32_e32 v92, vcc, s36, v144
	v_pk_fma_f32 v[94:95], v[94:95], v[214:215], v[98:99]
	s_nop 0
	v_addc_co_u32_e32 v93, vcc, 0, v145, vcc
	v_cvt_pk_bf16_f32 v89, v94, v95
	v_cvt_pk_bf16_f32 v90, v90, v91
	v_cvt_pk_bf16_f32 v91, v96, v97
	global_store_dwordx4 v[92:93], v[88:91], off
	s_waitcnt vmcnt(15)
	v_lshlrev_b32_e32 v94, 16, v170
	v_and_b32_e32 v95, 0xffff0000, v170
	v_lshlrev_b32_e32 v88, 16, v168
	v_and_b32_e32 v89, 0xffff0000, v168
	v_lshlrev_b32_e32 v90, 16, v169
	v_and_b32_e32 v91, 0xffff0000, v169
	v_lshlrev_b32_e32 v96, 16, v171
	v_and_b32_e32 v97, 0xffff0000, v171
	v_pk_fma_f32 v[86:87], v[86:87], v[206:207], v[90:91]
	v_pk_fma_f32 v[84:85], v[84:85], v[204:205], v[88:89]
	v_pk_fma_f32 v[88:89], v[82:83], v[202:203], v[96:97]
	v_pk_fma_f32 v[82:83], v[80:81], v[200:201], v[94:95]
	v_cvt_pk_bf16_f32 v80, v84, v85
	v_cvt_pk_bf16_f32 v81, v86, v87
	s_waitcnt vmcnt(14)
; __device__ __forceinline__ unsigned cvt_pk_bf16(float lo, float hi) { unsigned r; asm volatile("v_cvt_pk_bf16_f32 %0, %1, %2" : "=v"(r) : "v"(lo), "v"(hi)); return r; }
;     __device__ __forceinline__ void operator()(f32x4 (&acc)[2][2][4][2], const Unit& u, int wr, int wc, int fr, int fq, LAS unsigned char*) const {
;     ...
;                     for (int bj = 0; bj < 2; ++bj) { const u32x4 x = xb[ai][m][bj];
;                         f32x4 r0 = (f32x4){__uint_as_float(x.x << 16), __uint_as_float(x.x & 0xffff0000u), __uint_as_float(x.y << 16), __uint_as_float(x.y & 0xffff0000u)};
;                         f32x4 r1 = (f32x4){__uint_as_float(x.z << 16), __uint_as_float(x.z & 0xffff0000u), __uint_as_float(x.w << 16), __uint_as_float(x.w & 0xffff0000u)};
;                         r0 += sc[bj][0] * acc[ai][bj][m][0]; r1 += sc[bj][1] * acc[ai][bj][m][1];
;                         u32x4 w; w.x = cvt_pk_bf16(r0[0], r0[1]); w.y = cvt_pk_bf16(r0[2], r0[3]); w.z = cvt_pk_bf16(r1[0], r1[1]); w.w = cvt_pk_bf16(r1[2], r1[3]);
;                         *(u32x4*)(out + off0 + (size_t)(ai * HALF + m * 16) * D + bj * HALF) = w; }
	v_lshlrev_b32_e32 v84, 16, v166
	v_cvt_pk_bf16_f32 v82, v82, v83
	v_cvt_pk_bf16_f32 v83, v88, v89
	global_store_dwordx4 v[92:93], v[80:83], off offset:256
	v_and_b32_e32 v85, 0xffff0000, v166
	v_lshlrev_b32_e32 v86, 16, v167
	v_lshlrev_b32_e32 v80, 16, v164
	v_and_b32_e32 v81, 0xffff0000, v164
	v_and_b32_e32 v87, 0xffff0000, v167
	v_pk_fma_f32 v[76:77], v[76:77], v[212:213], v[80:81]
	v_lshlrev_b32_e32 v82, 16, v165
	v_and_b32_e32 v83, 0xffff0000, v165
	v_pk_fma_f32 v[80:81], v[74:75], v[210:211], v[86:87]
	v_pk_fma_f32 v[74:75], v[72:73], v[208:209], v[84:85]
	v_cvt_pk_bf16_f32 v72, v76, v77
	v_add_co_u32_e32 v76, vcc, s23, v144
	v_pk_fma_f32 v[78:79], v[78:79], v[214:215], v[82:83]
	s_nop 0
	v_addc_co_u32_e32 v77, vcc, 0, v145, vcc
	v_cvt_pk_bf16_f32 v73, v78, v79
	v_cvt_pk_bf16_f32 v74, v74, v75
	v_cvt_pk_bf16_f32 v75, v80, v81
	global_store_dwordx4 v[76:77], v[72:75], off
	s_waitcnt vmcnt(15)
	v_lshlrev_b32_e32 v78, 16, v162
	v_and_b32_e32 v79, 0xffff0000, v162
	v_lshlrev_b32_e32 v72, 16, v160
	v_and_b32_e32 v73, 0xffff0000, v160
	v_lshlrev_b32_e32 v74, 16, v161
	v_and_b32_e32 v75, 0xffff0000, v161
	v_lshlrev_b32_e32 v80, 16, v163
	v_and_b32_e32 v81, 0xffff0000, v163
	v_pk_fma_f32 v[70:71], v[70:71], v[206:207], v[74:75]
	v_pk_fma_f32 v[68:69], v[68:69], v[204:205], v[72:73]
	v_pk_fma_f32 v[72:73], v[66:67], v[202:203], v[80:81]
	v_pk_fma_f32 v[66:67], v[64:65], v[200:201], v[78:79]
	v_cvt_pk_bf16_f32 v64, v68, v69
	v_cvt_pk_bf16_f32 v65, v70, v71
	s_waitcnt vmcnt(14)
	v_lshlrev_b32_e32 v68, 16, v158
	v_cvt_pk_bf16_f32 v66, v66, v67
	v_cvt_pk_bf16_f32 v67, v72, v73
	global_store_dwordx4 v[76:77], v[64:67], off offset:256
	v_and_b32_e32 v69, 0xffff0000, v158
	v_lshlrev_b32_e32 v70, 16, v159
	v_lshlrev_b32_e32 v64, 16, v156
	v_and_b32_e32 v65, 0xffff0000, v156
	v_and_b32_e32 v71, 0xffff0000, v159
	v_pk_fma_f32 v[60:61], v[60:61], v[212:213], v[64:65]
	v_lshlrev_b32_e32 v66, 16, v157
	v_and_b32_e32 v67, 0xffff0000, v157
	v_pk_fma_f32 v[64:65], v[58:59], v[210:211], v[70:71]
	v_pk_fma_f32 v[58:59], v[56:57], v[208:209], v[68:69]
	v_cvt_pk_bf16_f32 v56, v60, v61
	v_add_co_u32_e32 v60, vcc, s93, v144
	v_pk_fma_f32 v[62:63], v[62:63], v[214:215], v[66:67]
	s_nop 0
	v_addc_co_u32_e32 v61, vcc, 0, v145, vcc
	v_cvt_pk_bf16_f32 v57, v62, v63
	v_cvt_pk_bf16_f32 v58, v58, v59
	v_cvt_pk_bf16_f32 v59, v64, v65
	global_store_dwordx4 v[60:61], v[56:59], off
	s_waitcnt vmcnt(15)
	v_lshlrev_b32_e32 v62, 16, v154
	v_and_b32_e32 v63, 0xffff0000, v154
	v_lshlrev_b32_e32 v56, 16, v152
	v_and_b32_e32 v57, 0xffff0000, v152
	v_lshlrev_b32_e32 v58, 16, v153
	v_and_b32_e32 v59, 0xffff0000, v153
	v_lshlrev_b32_e32 v64, 16, v155
	v_and_b32_e32 v65, 0xffff0000, v155
	v_pk_fma_f32 v[54:55], v[54:55], v[206:207], v[58:59]
	v_pk_fma_f32 v[52:53], v[52:53], v[204:205], v[56:57]
	v_pk_fma_f32 v[56:57], v[50:51], v[202:203], v[64:65]
	v_pk_fma_f32 v[50:51], v[48:49], v[200:201], v[62:63]
	v_cvt_pk_bf16_f32 v48, v52, v53
	v_cvt_pk_bf16_f32 v49, v54, v55
	s_waitcnt vmcnt(14)
	v_lshlrev_b32_e32 v52, 16, v142
	v_cvt_pk_bf16_f32 v50, v50, v51
	v_cvt_pk_bf16_f32 v51, v56, v57
	global_store_dwordx4 v[60:61], v[48:51], off offset:256
	v_and_b32_e32 v53, 0xffff0000, v142
	v_lshlrev_b32_e32 v54, 16, v143
	v_lshlrev_b32_e32 v48, 16, v140
	v_and_b32_e32 v49, 0xffff0000, v140
	v_and_b32_e32 v55, 0xffff0000, v143
	v_pk_fma_f32 v[44:45], v[44:45], v[212:213], v[48:49]
	v_lshlrev_b32_e32 v50, 16, v141
	v_and_b32_e32 v51, 0xffff0000, v141
	v_pk_fma_f32 v[48:49], v[42:43], v[210:211], v[54:55]
	v_pk_fma_f32 v[42:43], v[40:41], v[208:209], v[52:53]
	v_cvt_pk_bf16_f32 v40, v44, v45
	v_add_co_u32_e32 v44, vcc, s33, v144
	v_pk_fma_f32 v[46:47], v[46:47], v[214:215], v[50:51]
	s_nop 0
	v_addc_co_u32_e32 v45, vcc, 0, v145, vcc
	v_cvt_pk_bf16_f32 v41, v46, v47
	v_cvt_pk_bf16_f32 v42, v42, v43
	v_cvt_pk_bf16_f32 v43, v48, v49
	global_store_dwordx4 v[44:45], v[40:43], off
	s_waitcnt vmcnt(15)
; __device__ __forceinline__ unsigned cvt_pk_bf16(float lo, float hi) { unsigned r; asm volatile("v_cvt_pk_bf16_f32 %0, %1, %2" : "=v"(r) : "v"(lo), "v"(hi)); return r; }
;     __device__ __forceinline__ void operator()(f32x4 (&acc)[2][2][4][2], const Unit& u, int wr, int wc, int fr, int fq, LAS unsigned char*) const {
;     ...
;                     for (int bj = 0; bj < 2; ++bj) { const u32x4 x = xb[ai][m][bj];
;                         f32x4 r0 = (f32x4){__uint_as_float(x.x << 16), __uint_as_float(x.x & 0xffff0000u), __uint_as_float(x.y << 16), __uint_as_float(x.y & 0xffff0000u)};
;                         f32x4 r1 = (f32x4){__uint_as_float(x.z << 16), __uint_as_float(x.z & 0xffff0000u), __uint_as_float(x.w << 16), __uint_as_float(x.w & 0xffff0000u)};
;                         r0 += sc[bj][0] * acc[ai][bj][m][0]; r1 += sc[bj][1] * acc[ai][bj][m][1];
;                         u32x4 w; w.x = cvt_pk_bf16(r0[0], r0[1]); w.y = cvt_pk_bf16(r0[2], r0[3]); w.z = cvt_pk_bf16(r1[0], r1[1]); w.w = cvt_pk_bf16(r1[2], r1[3]);
;                         *(u32x4*)(out + off0 + (size_t)(ai * HALF + m * 16) * D + bj * HALF) = w; }
	v_lshlrev_b32_e32 v46, 16, v138
	v_and_b32_e32 v47, 0xffff0000, v138
	v_lshlrev_b32_e32 v40, 16, v136
	v_and_b32_e32 v41, 0xffff0000, v136
	v_lshlrev_b32_e32 v42, 16, v137
	v_and_b32_e32 v43, 0xffff0000, v137
	v_lshlrev_b32_e32 v48, 16, v139
	v_and_b32_e32 v49, 0xffff0000, v139
	v_pk_fma_f32 v[38:39], v[38:39], v[206:207], v[42:43]
	v_pk_fma_f32 v[36:37], v[36:37], v[204:205], v[40:41]
	v_pk_fma_f32 v[40:41], v[34:35], v[202:203], v[48:49]
	v_pk_fma_f32 v[34:35], v[32:33], v[200:201], v[46:47]
	v_cvt_pk_bf16_f32 v32, v36, v37
	v_cvt_pk_bf16_f32 v33, v38, v39
	s_waitcnt vmcnt(14)
	v_lshlrev_b32_e32 v36, 16, v134
	v_cvt_pk_bf16_f32 v34, v34, v35
	v_cvt_pk_bf16_f32 v35, v40, v41
	global_store_dwordx4 v[44:45], v[32:35], off offset:256
	v_and_b32_e32 v37, 0xffff0000, v134
	v_lshlrev_b32_e32 v38, 16, v135
	v_lshlrev_b32_e32 v32, 16, v132
	v_and_b32_e32 v33, 0xffff0000, v132
	v_and_b32_e32 v39, 0xffff0000, v135
	v_pk_fma_f32 v[28:29], v[28:29], v[212:213], v[32:33]
	v_lshlrev_b32_e32 v34, 16, v133
	v_and_b32_e32 v35, 0xffff0000, v133
	v_pk_fma_f32 v[32:33], v[26:27], v[210:211], v[38:39]
	v_pk_fma_f32 v[26:27], v[24:25], v[208:209], v[36:37]
	v_cvt_pk_bf16_f32 v24, v28, v29
	v_add_co_u32_e32 v28, vcc, s18, v144
	v_pk_fma_f32 v[30:31], v[30:31], v[214:215], v[34:35]
	s_nop 0
	v_addc_co_u32_e32 v29, vcc, 0, v145, vcc
	v_cvt_pk_bf16_f32 v25, v30, v31
	v_cvt_pk_bf16_f32 v26, v26, v27
	v_cvt_pk_bf16_f32 v27, v32, v33
	global_store_dwordx4 v[28:29], v[24:27], off
	s_waitcnt vmcnt(15)
	v_lshlrev_b32_e32 v30, 16, v130
	v_and_b32_e32 v31, 0xffff0000, v130
	v_lshlrev_b32_e32 v24, 16, v128
	v_and_b32_e32 v25, 0xffff0000, v128
	v_lshlrev_b32_e32 v26, 16, v129
	v_and_b32_e32 v27, 0xffff0000, v129
	v_lshlrev_b32_e32 v32, 16, v131
	v_and_b32_e32 v33, 0xffff0000, v131
	v_pk_fma_f32 v[22:23], v[22:23], v[206:207], v[26:27]
	v_pk_fma_f32 v[20:21], v[20:21], v[204:205], v[24:25]
	v_pk_fma_f32 v[24:25], v[18:19], v[202:203], v[32:33]
	v_pk_fma_f32 v[18:19], v[16:17], v[200:201], v[30:31]
	v_cvt_pk_bf16_f32 v16, v20, v21
	v_cvt_pk_bf16_f32 v17, v22, v23
	s_waitcnt vmcnt(14)
	v_lshlrev_b32_e32 v20, 16, v126
	v_cvt_pk_bf16_f32 v18, v18, v19
	v_cvt_pk_bf16_f32 v19, v24, v25
	global_store_dwordx4 v[28:29], v[16:19], off offset:256
	v_and_b32_e32 v21, 0xffff0000, v126
	v_lshlrev_b32_e32 v22, 16, v127
	v_lshlrev_b32_e32 v16, 16, v124
	v_and_b32_e32 v17, 0xffff0000, v124
	v_and_b32_e32 v23, 0xffff0000, v127
	v_pk_fma_f32 v[12:13], v[12:13], v[212:213], v[16:17]
	v_lshlrev_b32_e32 v18, 16, v125
	v_and_b32_e32 v19, 0xffff0000, v125
	v_pk_fma_f32 v[16:17], v[10:11], v[210:211], v[22:23]
	v_pk_fma_f32 v[10:11], v[8:9], v[208:209], v[20:21]
	v_cvt_pk_bf16_f32 v8, v12, v13
	v_add_co_u32_e32 v12, vcc, s19, v144
	v_pk_fma_f32 v[14:15], v[14:15], v[214:215], v[18:19]
	s_nop 0
	v_addc_co_u32_e32 v13, vcc, 0, v145, vcc
	v_cvt_pk_bf16_f32 v9, v14, v15
	v_cvt_pk_bf16_f32 v10, v10, v11
	v_cvt_pk_bf16_f32 v11, v16, v17
	global_store_dwordx4 v[12:13], v[8:11], off
	s_waitcnt vmcnt(15)
	v_lshlrev_b32_e32 v14, 16, v122
	v_and_b32_e32 v15, 0xffff0000, v122
	v_lshlrev_b32_e32 v8, 16, v120
	v_and_b32_e32 v9, 0xffff0000, v120
	v_lshlrev_b32_e32 v16, 16, v123
	v_and_b32_e32 v17, 0xffff0000, v123
	v_lshlrev_b32_e32 v10, 16, v121
	v_and_b32_e32 v11, 0xffff0000, v121
	v_pk_fma_f32 v[4:5], v[4:5], v[204:205], v[8:9]
	v_pk_fma_f32 v[8:9], v[2:3], v[202:203], v[16:17]
	v_pk_fma_f32 v[2:3], v[0:1], v[200:201], v[14:15]
	s_and_b64 vcc, exec, s[4:5]
	v_pk_fma_f32 v[6:7], v[6:7], v[206:207], v[10:11]
	v_cvt_pk_bf16_f32 v0, v4, v5
	s_nop 0
	v_cvt_pk_bf16_f32 v1, v6, v7
	v_cvt_pk_bf16_f32 v2, v2, v3
	v_cvt_pk_bf16_f32 v3, v8, v9
	global_store_dwordx4 v[12:13], v[0:3], off offset:256
	s_cbranch_vccz .LBB0_603
	s_waitcnt vmcnt(0)
	s_cmpk_gt_u32 s16, 0xff
	v_readlane_b32 s38, v255, 44
	s_movk_i32 s30, 0x7ff
	s_cbranch_scc1 .LBB0_614
	s_barrier

; #define PG8_STAGE(bufoff, gbase, hoff, imm) do { _Pragma("unroll") for (int _i = 0; _i < 2; ++_i) { \
;         asm volatile("s_mov_b32 m0, %0\n\ts_nop 0\n\tglobal_load_lds_dwordx4 %1, %2" \
;             :: "s"(lds0 + (unsigned)((bufoff) + _i * 8192)), "v"(voff0), "s"((const char*)(gbase) + (size_t)(hoff) + (size_t)(_i * 8192)) : "memory"); } } while (0)
; #define PG8_LDA(dst, b, h) do { _Pragma("unroll") for (int m = 0; m < 4; ++m) _Pragma("unroll") for (int k = 0; k < 2; ++k) dst[m][k] = *(const LAS bf16x8*)(lds + PG8_SA(b, h) + aoff + m * 2048 + k * 1024); } while (0)
; #define PG8_LDB(dst, b, h) do { _Pragma("unroll") for (int n = 0; n < 2; ++n) _Pragma("unroll") for (int k = 0; k < 2; ++k) dst[n][k] = *(const LAS bf16x8*)(lds + PG8_SB(b, h) + boff + n * 2048 + k * 1024); } while (0)
; #define PG8_MMA(ai, bj, At, Bt) do { __builtin_amdgcn_s_setprio(1); _Pragma("unroll") for (int m = 0; m < 4; ++m) _Pragma("unroll") for (int n = 0; n < 2; ++n) _Pragma("unroll") for (int k = 0; k < 2; ++k) \
;         acc[ai][bj][m][n] = __builtin_amdgcn_mfma_f32_16x16x32_bf16(Bt[n][k], At[m][k], acc[ai][bj][m][n], 0, 0, 0); __builtin_amdgcn_s_setprio(0); } while (0)
; #define PG8_WAIT_L(n) asm volatile("s_waitcnt lgkmcnt(" #n ")" ::: "memory")
; #define PG8_BAR __builtin_amdgcn_s_barrier()
; #define PG8_SCHED __builtin_amdgcn_sched_barrier(0)
; template <class Epi>
; __device__ __forceinline__ void gemm_phase(LAS unsigned char* lds, const Gemm g, const StaticOrder& S, const Epi& E) {
;     ...
;         for (int t = 0; t < nt; t += 2) {
;             const bool last = (t == nt - 2);
;             if (last) E.pre(cur, wid, lane, (unsigned)(size_t)(lds + STAGE_BYTES));
;             const char* aT = cA + (size_t)t * KS;
;             const char* a2 = last ? nA : aT + 2 * KS; const char* b2 = last ? nB : cB + (size_t)(t + 2) * KS;
;             PG8_LDB(B0, 0, 0); PG8_SCHED; PG8_LDA(At, 0, 0); PG8_STAGE(PG8_SA(1, 1), aT + KS, hA, 0);
;             PG8_WAIT_L(8); PG8_BAR; PG8_WAIT_L(0); PG8_MMA(0, 0, At, B0); PG8_BAR; PG8_SCHED;
;             PG8_LDB(B1, 0, 1); PG8_STAGE(PG8_SB(0, 0), b2, 0, 0);
;             PG8_BAR; PG8_WAIT_L(0); PG8_MMA(0, 1, At, B1); PG8_BAR;
;             PG8_LDA(At, 0, 1); PG8_STAGE(PG8_SA(0, 0), a2, 0, 0);
;             PG8_BAR; PG8_WAIT_L(0); PG8_MMA(1, 0, At, B0); PG8_BAR; PG8_SCHED;
.LBB0_738:
	v_add_u32_e32 v140, 0x10000, v177
	ds_read_b128 v[128:131], v140
	ds_read_b128 v[132:135], v140 offset:1024
	ds_read_b128 v[136:139], v140 offset:2048
	ds_read_b128 v[140:143], v140 offset:3072
	s_add_u32 s78, s76, 0x8000
	s_addc_u32 s79, s77, 0
	s_and_b64 s[48:49], s[82:83], exec
	s_cselect_b32 s81, s50, s79
	s_cselect_b32 s80, s51, s78
	ds_read_b128 v[144:147], v178
	ds_read_b128 v[148:151], v178 offset:1024
	ds_read_b128 v[184:187], v178 offset:2048
	ds_read_b128 v[200:203], v178 offset:3072
	ds_read_b128 v[204:207], v178 offset:4096
	ds_read_b128 v[208:211], v178 offset:5120
	ds_read_b128 v[212:215], v178 offset:6144
	ds_read_b128 v[236:239], v178 offset:7168
	s_add_u32 s48, s76, 0x84000
	s_addc_u32 s49, s77, 0
	s_mov_b32 m0, s34
	s_nop 0
	global_load_lds_dwordx4 v152, s[48:49]
	s_add_u32 s48, s76, 0x86000
	s_addc_u32 s49, s77, 0
	s_mov_b32 m0, s25
	s_nop 0
	global_load_lds_dwordx4 v152, s[48:49]
	s_waitcnt lgkmcnt(8)
	s_waitcnt vmcnt(10)
	s_barrier
	s_waitcnt lgkmcnt(0)
	s_setprio 1
	s_waitcnt lgkmcnt(7)
	v_mfma_f32_16x16x32_bf16 v[116:119], v[128:131], v[144:147], v[116:119]
	v_mfma_f32_16x16x32_bf16 v[80:83], v[136:139], v[144:147], v[80:83]
	s_waitcnt lgkmcnt(5)
	v_mfma_f32_16x16x32_bf16 v[88:91], v[128:131], v[184:187], v[88:91]
	v_mfma_f32_16x16x32_bf16 v[84:87], v[136:139], v[184:187], v[84:87]
	s_waitcnt lgkmcnt(3)
	v_mfma_f32_16x16x32_bf16 v[120:123], v[128:131], v[204:207], v[120:123]
	v_mfma_f32_16x16x32_bf16 v[92:95], v[136:139], v[204:207], v[92:95]
	s_waitcnt lgkmcnt(1)
	v_mfma_f32_16x16x32_bf16 v[124:127], v[128:131], v[212:215], v[124:127]
	v_mfma_f32_16x16x32_bf16 v[96:99], v[136:139], v[212:215], v[96:99]
	v_mfma_f32_16x16x32_bf16 v[116:119], v[132:135], v[148:151], v[116:119]
	v_mfma_f32_16x16x32_bf16 v[80:83], v[140:143], v[148:151], v[80:83]
	v_mfma_f32_16x16x32_bf16 v[88:91], v[132:135], v[200:203], v[88:91]
	v_mfma_f32_16x16x32_bf16 v[84:87], v[140:143], v[200:203], v[84:87]
	v_mfma_f32_16x16x32_bf16 v[120:123], v[132:135], v[208:211], v[120:123]
	v_mfma_f32_16x16x32_bf16 v[92:95], v[140:143], v[208:211], v[92:95]
	s_waitcnt lgkmcnt(0)
	v_mfma_f32_16x16x32_bf16 v[124:127], v[132:135], v[236:239], v[124:127]
	v_mfma_f32_16x16x32_bf16 v[96:99], v[140:143], v[236:239], v[96:99]
	s_setprio 0
	s_barrier
	v_add_u32_e32 v188, 0x14000, v177
	ds_read_b128 v[240:243], v188
	ds_read_b128 v[244:247], v188 offset:1024
	ds_read_b128 v[248:251], v188 offset:2048
	ds_read_b128 v[230:233], v188 offset:3072
	s_and_b64 s[48:49], s[82:83], exec
	s_cselect_b32 s76, s0, s1
	s_cselect_b32 s77, s69, s9
	s_mov_b32 m0, s28
	s_nop 0
	global_load_lds_dwordx4 v152, s[76:77]
	s_add_u32 s48, s76, 0x2000
	s_addc_u32 s49, s77, 0
	s_mov_b32 m0, s29
	s_nop 0
	global_load_lds_dwordx4 v152, s[48:49]
	s_waitcnt vmcnt(10)
	s_barrier
	s_waitcnt lgkmcnt(0)
	s_setprio 1
	s_waitcnt lgkmcnt(3)
	v_mfma_f32_16x16x32_bf16 v[48:51], v[240:243], v[144:147], v[48:51]
	s_waitcnt lgkmcnt(1)
	v_mfma_f32_16x16x32_bf16 v[16:19], v[248:251], v[144:147], v[16:19]
	v_mfma_f32_16x16x32_bf16 v[52:55], v[240:243], v[184:187], v[52:55]
	v_mfma_f32_16x16x32_bf16 v[20:23], v[248:251], v[184:187], v[20:23]
	v_mfma_f32_16x16x32_bf16 v[56:59], v[240:243], v[204:207], v[56:59]
	v_mfma_f32_16x16x32_bf16 v[24:27], v[248:251], v[204:207], v[24:27]
	v_mfma_f32_16x16x32_bf16 v[60:63], v[240:243], v[212:215], v[60:63]
	v_mfma_f32_16x16x32_bf16 v[28:31], v[248:251], v[212:215], v[28:31]
	v_mfma_f32_16x16x32_bf16 v[48:51], v[244:247], v[148:151], v[48:51]
	s_waitcnt lgkmcnt(0)
	v_mfma_f32_16x16x32_bf16 v[16:19], v[230:233], v[148:151], v[16:19]
	v_mfma_f32_16x16x32_bf16 v[52:55], v[244:247], v[200:203], v[52:55]
	v_mfma_f32_16x16x32_bf16 v[20:23], v[230:233], v[200:203], v[20:23]
	v_mfma_f32_16x16x32_bf16 v[56:59], v[244:247], v[208:211], v[56:59]
	v_mfma_f32_16x16x32_bf16 v[24:27], v[230:233], v[208:211], v[24:27]
	v_mfma_f32_16x16x32_bf16 v[60:63], v[244:247], v[236:239], v[60:63]
	v_mfma_f32_16x16x32_bf16 v[28:31], v[230:233], v[236:239], v[28:31]
	s_setprio 0
	s_barrier
	ds_read_b128 v[144:147], v178 offset:16384
	ds_read_b128 v[148:151], v178 offset:17408
	ds_read_b128 v[184:187], v178 offset:18432
	ds_read_b128 v[200:203], v178 offset:19456
	ds_read_b128 v[204:207], v178 offset:20480
	ds_read_b128 v[208:211], v178 offset:21504
	ds_read_b128 v[212:215], v178 offset:22528
	ds_read_b128 v[236:239], v178 offset:23552
	s_mov_b32 m0, s89
	s_nop 0
	global_load_lds_dwordx4 v152, s[80:81]
	s_add_u32 s48, s80, 0x2000
	s_addc_u32 s49, s81, 0
	s_mov_b32 m0, s40
	s_nop 0
	global_load_lds_dwordx4 v152, s[48:49]
	s_barrier
	s_waitcnt lgkmcnt(0)
	s_setprio 1
	s_waitcnt lgkmcnt(7)
	v_mfma_f32_16x16x32_bf16 v[100:103], v[128:131], v[144:147], v[100:103]
	v_mfma_f32_16x16x32_bf16 v[64:67], v[136:139], v[144:147], v[64:67]
	s_waitcnt lgkmcnt(5)
	v_mfma_f32_16x16x32_bf16 v[104:107], v[128:131], v[184:187], v[104:107]
	v_mfma_f32_16x16x32_bf16 v[68:71], v[136:139], v[184:187], v[68:71]
	s_waitcnt lgkmcnt(3)
	v_mfma_f32_16x16x32_bf16 v[108:111], v[128:131], v[204:207], v[108:111]
	v_mfma_f32_16x16x32_bf16 v[72:75], v[136:139], v[204:207], v[72:75]
	s_waitcnt lgkmcnt(1)
	v_mfma_f32_16x16x32_bf16 v[112:115], v[128:131], v[212:215], v[112:115]
	v_mfma_f32_16x16x32_bf16 v[76:79], v[136:139], v[212:215], v[76:79]
	v_mfma_f32_16x16x32_bf16 v[100:103], v[132:135], v[148:151], v[100:103]
	v_mfma_f32_16x16x32_bf16 v[64:67], v[140:143], v[148:151], v[64:67]
	v_mfma_f32_16x16x32_bf16 v[104:107], v[132:135], v[200:203], v[104:107]
	v_mfma_f32_16x16x32_bf16 v[68:71], v[140:143], v[200:203], v[68:71]
	v_mfma_f32_16x16x32_bf16 v[108:111], v[132:135], v[208:211], v[108:111]
	v_mfma_f32_16x16x32_bf16 v[72:75], v[140:143], v[208:211], v[72:75]
	s_waitcnt lgkmcnt(0)
	v_mfma_f32_16x16x32_bf16 v[112:115], v[132:135], v[236:239], v[112:115]
	v_mfma_f32_16x16x32_bf16 v[76:79], v[140:143], v[236:239], v[76:79]
	s_setprio 0
	s_barrier
; #define PG8_STAGE(bufoff, gbase, hoff, imm) do { _Pragma("unroll") for (int _i = 0; _i < 2; ++_i) { \
;         asm volatile("s_mov_b32 m0, %0\n\ts_nop 0\n\tglobal_load_lds_dwordx4 %1, %2" \
;             :: "s"(lds0 + (unsigned)((bufoff) + _i * 8192)), "v"(voff0), "s"((const char*)(gbase) + (size_t)(hoff) + (size_t)(_i * 8192)) : "memory"); } } while (0)
; #define PG8_LDA(dst, b, h) do { _Pragma("unroll") for (int m = 0; m < 4; ++m) _Pragma("unroll") for (int k = 0; k < 2; ++k) dst[m][k] = *(const LAS bf16x8*)(lds + PG8_SA(b, h) + aoff + m * 2048 + k * 1024); } while (0)
; #define PG8_LDB(dst, b, h) do { _Pragma("unroll") for (int n = 0; n < 2; ++n) _Pragma("unroll") for (int k = 0; k < 2; ++k) dst[n][k] = *(const LAS bf16x8*)(lds + PG8_SB(b, h) + boff + n * 2048 + k * 1024); } while (0)
; #define PG8_MMA(ai, bj, At, Bt) do { __builtin_amdgcn_s_setprio(1); _Pragma("unroll") for (int m = 0; m < 4; ++m) _Pragma("unroll") for (int n = 0; n < 2; ++n) _Pragma("unroll") for (int k = 0; k < 2; ++k) \
;         acc[ai][bj][m][n] = __builtin_amdgcn_mfma_f32_16x16x32_bf16(Bt[n][k], At[m][k], acc[ai][bj][m][n], 0, 0, 0); __builtin_amdgcn_s_setprio(0); } while (0)
; #define PG8_WAIT_V(n) asm volatile("s_waitcnt vmcnt(" #n ")" ::: "memory")
; #define PG8_WAIT_L(n) asm volatile("s_waitcnt lgkmcnt(" #n ")" ::: "memory")
; #define PG8_BAR __builtin_amdgcn_s_barrier()
; #define PG8_SCHED __builtin_amdgcn_sched_barrier(0)
; template <class Epi>
; __device__ __forceinline__ void gemm_phase(LAS unsigned char* lds, const Gemm g, const StaticOrder& S, const Epi& E) {
;     ...
;             PG8_STAGE(PG8_SB(0, 1), b2, hB, 0);
;             PG8_WAIT_V(6); PG8_BAR; PG8_MMA(1, 1, At, B1); PG8_BAR;
;             PG8_LDB(B0, 1, 0); PG8_SCHED; PG8_LDA(At, 1, 0); PG8_STAGE(PG8_SA(0, 1), a2, hA, 0);
;             PG8_WAIT_L(8); PG8_BAR; PG8_WAIT_L(0); PG8_MMA(0, 0, At, B0); PG8_BAR; PG8_SCHED;
	s_add_u32 s48, s76, 0x80000
	s_addc_u32 s49, s77, 0
	s_mov_b32 m0, s41
	s_nop 0
	global_load_lds_dwordx4 v152, s[48:49]
	s_add_u32 s48, s76, 0x82000
	s_addc_u32 s49, s77, 0
	s_mov_b32 m0, s42
	s_nop 0
	global_load_lds_dwordx4 v152, s[48:49]
	s_waitcnt vmcnt(10)
	s_barrier
	s_setprio 1
	v_mfma_f32_16x16x32_bf16 v[32:35], v[240:243], v[144:147], v[32:35]
	v_mfma_f32_16x16x32_bf16 v[0:3], v[248:251], v[144:147], v[0:3]
	v_mfma_f32_16x16x32_bf16 v[36:39], v[240:243], v[184:187], v[36:39]
	v_mfma_f32_16x16x32_bf16 v[4:7], v[248:251], v[184:187], v[4:7]
	v_mfma_f32_16x16x32_bf16 v[40:43], v[240:243], v[204:207], v[40:43]
	v_mfma_f32_16x16x32_bf16 v[8:11], v[248:251], v[204:207], v[8:11]
	v_mfma_f32_16x16x32_bf16 v[44:47], v[240:243], v[212:215], v[44:47]
	v_mfma_f32_16x16x32_bf16 v[12:15], v[248:251], v[212:215], v[12:15]
	v_mfma_f32_16x16x32_bf16 v[32:35], v[244:247], v[148:151], v[32:35]
	v_mfma_f32_16x16x32_bf16 v[0:3], v[230:233], v[148:151], v[0:3]
	v_mfma_f32_16x16x32_bf16 v[36:39], v[244:247], v[200:203], v[36:39]
	v_mfma_f32_16x16x32_bf16 v[4:7], v[230:233], v[200:203], v[4:7]
	v_mfma_f32_16x16x32_bf16 v[40:43], v[244:247], v[208:211], v[40:43]
	v_mfma_f32_16x16x32_bf16 v[8:11], v[230:233], v[208:211], v[8:11]
	v_mfma_f32_16x16x32_bf16 v[44:47], v[244:247], v[236:239], v[44:47]
	v_mfma_f32_16x16x32_bf16 v[12:15], v[230:233], v[236:239], v[12:15]
	s_setprio 0
	v_add_u32_e32 v140, 0x18000, v177
	s_barrier
	ds_read_b128 v[128:131], v140
	ds_read_b128 v[132:135], v140 offset:1024
	ds_read_b128 v[136:139], v140 offset:2048
	ds_read_b128 v[140:143], v140 offset:3072
	ds_read_b128 v[144:147], v178 offset:32768
	ds_read_b128 v[148:151], v178 offset:33792
	ds_read_b128 v[184:187], v178 offset:34816
	ds_read_b128 v[200:203], v178 offset:35840
	ds_read_b128 v[204:207], v178 offset:36864
	ds_read_b128 v[208:211], v178 offset:37888
	ds_read_b128 v[212:215], v178 offset:38912
	ds_read_b128 v[230:233], v178 offset:39936
	s_add_u32 s48, s80, 0x80000
	s_addc_u32 s49, s81, 0
	s_mov_b32 m0, s43
	s_nop 0
	global_load_lds_dwordx4 v152, s[48:49]
	s_add_u32 s48, s80, 0x82000
	s_addc_u32 s49, s81, 0
	s_mov_b32 m0, s92
	s_nop 0
	global_load_lds_dwordx4 v152, s[48:49]
	s_waitcnt lgkmcnt(8)
	s_waitcnt vmcnt(10)
	s_barrier
	s_waitcnt lgkmcnt(0)
	s_setprio 1
	s_waitcnt lgkmcnt(7)
	v_mfma_f32_16x16x32_bf16 v[116:119], v[128:131], v[144:147], v[116:119]
	v_mfma_f32_16x16x32_bf16 v[80:83], v[136:139], v[144:147], v[80:83]
	s_waitcnt lgkmcnt(5)
	v_mfma_f32_16x16x32_bf16 v[88:91], v[128:131], v[184:187], v[88:91]
	v_mfma_f32_16x16x32_bf16 v[84:87], v[136:139], v[184:187], v[84:87]
	s_waitcnt lgkmcnt(3)
	v_mfma_f32_16x16x32_bf16 v[120:123], v[128:131], v[204:207], v[120:123]
	v_mfma_f32_16x16x32_bf16 v[92:95], v[136:139], v[204:207], v[92:95]
	s_waitcnt lgkmcnt(1)
	v_mfma_f32_16x16x32_bf16 v[124:127], v[128:131], v[212:215], v[124:127]
	v_mfma_f32_16x16x32_bf16 v[96:99], v[136:139], v[212:215], v[96:99]
	v_mfma_f32_16x16x32_bf16 v[116:119], v[132:135], v[148:151], v[116:119]
	v_mfma_f32_16x16x32_bf16 v[80:83], v[140:143], v[148:151], v[80:83]
	v_mfma_f32_16x16x32_bf16 v[88:91], v[132:135], v[200:203], v[88:91]
	v_mfma_f32_16x16x32_bf16 v[84:87], v[140:143], v[200:203], v[84:87]
	v_mfma_f32_16x16x32_bf16 v[120:123], v[132:135], v[208:211], v[120:123]
	v_mfma_f32_16x16x32_bf16 v[92:95], v[140:143], v[208:211], v[92:95]
	s_waitcnt lgkmcnt(0)
	v_mfma_f32_16x16x32_bf16 v[124:127], v[132:135], v[230:233], v[124:127]
	v_mfma_f32_16x16x32_bf16 v[96:99], v[140:143], v[230:233], v[96:99]
	s_setprio 0
	s_barrier
	v_add_u32_e32 v188, 0x1c000, v177
	ds_read_b128 v[236:239], v188
	ds_read_b128 v[240:243], v188 offset:1024
	ds_read_b128 v[244:247], v188 offset:2048
	ds_read_b128 v[248:251], v188 offset:3072
	s_add_u32 s48, s76, 0x4000
	s_addc_u32 s49, s77, 0
	s_mov_b32 m0, s16
	s_nop 0
	global_load_lds_dwordx4 v152, s[48:49]
	s_add_u32 s48, s76, 0x6000
	s_addc_u32 s49, s77, 0
	s_mov_b32 m0, s17
	s_nop 0
	global_load_lds_dwordx4 v152, s[48:49]
	s_waitcnt vmcnt(10)
	s_barrier
; #define PG8_STAGE(bufoff, gbase, hoff, imm) do { _Pragma("unroll") for (int _i = 0; _i < 2; ++_i) { \
;         asm volatile("s_mov_b32 m0, %0\n\ts_nop 0\n\tglobal_load_lds_dwordx4 %1, %2" \
;             :: "s"(lds0 + (unsigned)((bufoff) + _i * 8192)), "v"(voff0), "s"((const char*)(gbase) + (size_t)(hoff) + (size_t)(_i * 8192)) : "memory"); } } while (0)
; #define PG8_LDA(dst, b, h) do { _Pragma("unroll") for (int m = 0; m < 4; ++m) _Pragma("unroll") for (int k = 0; k < 2; ++k) dst[m][k] = *(const LAS bf16x8*)(lds + PG8_SA(b, h) + aoff + m * 2048 + k * 1024); } while (0)
; #define PG8_LDB(dst, b, h) do { _Pragma("unroll") for (int n = 0; n < 2; ++n) _Pragma("unroll") for (int k = 0; k < 2; ++k) dst[n][k] = *(const LAS bf16x8*)(lds + PG8_SB(b, h) + boff + n * 2048 + k * 1024); } while (0)
; #define PG8_MMA(ai, bj, At, Bt) do { __builtin_amdgcn_s_setprio(1); _Pragma("unroll") for (int m = 0; m < 4; ++m) _Pragma("unroll") for (int n = 0; n < 2; ++n) _Pragma("unroll") for (int k = 0; k < 2; ++k) \
;         acc[ai][bj][m][n] = __builtin_amdgcn_mfma_f32_16x16x32_bf16(Bt[n][k], At[m][k], acc[ai][bj][m][n], 0, 0, 0); __builtin_amdgcn_s_setprio(0); } while (0)
; #define PG8_WAIT_V(n) asm volatile("s_waitcnt vmcnt(" #n ")" ::: "memory")
; #define PG8_WAIT_L(n) asm volatile("s_waitcnt lgkmcnt(" #n ")" ::: "memory")
; #define PG8_BAR __builtin_amdgcn_s_barrier()
; #define PG8_SCHED __builtin_amdgcn_sched_barrier(0)
; template <class Epi>
; __device__ __forceinline__ void gemm_phase(LAS unsigned char* lds, const Gemm g, const StaticOrder& S, const Epi& E) {
;     ...
;             PG8_WAIT_L(8); PG8_BAR; PG8_WAIT_L(0); PG8_MMA(0, 0, At, B0); PG8_BAR; PG8_SCHED;
;             PG8_LDB(B1, 1, 1); PG8_STAGE(PG8_SB(1, 0), b2 + KS, 0, 0);
;             PG8_BAR; PG8_WAIT_L(0); PG8_MMA(0, 1, At, B1); PG8_BAR;
;             PG8_LDA(At, 1, 1); PG8_STAGE(PG8_SA(1, 0), a2 + KS, 0, 0);
;             PG8_BAR; PG8_WAIT_L(0); PG8_MMA(1, 0, At, B0); PG8_BAR; PG8_SCHED;
;             PG8_STAGE(PG8_SB(1, 1), b2 + KS, hB, 0);
;             PG8_WAIT_V(6); PG8_BAR; PG8_MMA(1, 1, At, B1); PG8_BAR;
	s_waitcnt lgkmcnt(0)
	s_setprio 1
	s_waitcnt lgkmcnt(3)
	v_mfma_f32_16x16x32_bf16 v[48:51], v[236:239], v[144:147], v[48:51]
	s_waitcnt lgkmcnt(1)
	v_mfma_f32_16x16x32_bf16 v[16:19], v[244:247], v[144:147], v[16:19]
	v_mfma_f32_16x16x32_bf16 v[52:55], v[236:239], v[184:187], v[52:55]
	v_mfma_f32_16x16x32_bf16 v[20:23], v[244:247], v[184:187], v[20:23]
	v_mfma_f32_16x16x32_bf16 v[56:59], v[236:239], v[204:207], v[56:59]
	v_mfma_f32_16x16x32_bf16 v[24:27], v[244:247], v[204:207], v[24:27]
	v_mfma_f32_16x16x32_bf16 v[60:63], v[236:239], v[212:215], v[60:63]
	v_mfma_f32_16x16x32_bf16 v[28:31], v[244:247], v[212:215], v[28:31]
	v_mfma_f32_16x16x32_bf16 v[48:51], v[240:243], v[148:151], v[48:51]
	s_waitcnt lgkmcnt(0)
	v_mfma_f32_16x16x32_bf16 v[16:19], v[248:251], v[148:151], v[16:19]
	v_mfma_f32_16x16x32_bf16 v[52:55], v[240:243], v[200:203], v[52:55]
	v_mfma_f32_16x16x32_bf16 v[20:23], v[248:251], v[200:203], v[20:23]
	v_mfma_f32_16x16x32_bf16 v[56:59], v[240:243], v[208:211], v[56:59]
	v_mfma_f32_16x16x32_bf16 v[24:27], v[248:251], v[208:211], v[24:27]
	v_mfma_f32_16x16x32_bf16 v[60:63], v[240:243], v[230:233], v[60:63]
	v_mfma_f32_16x16x32_bf16 v[28:31], v[248:251], v[230:233], v[28:31]
	s_setprio 0
	s_barrier
	ds_read_b128 v[144:147], v178 offset:49152
	ds_read_b128 v[148:151], v178 offset:50176
	ds_read_b128 v[184:187], v178 offset:51200
	ds_read_b128 v[200:203], v178 offset:52224
	ds_read_b128 v[204:207], v178 offset:53248
	ds_read_b128 v[208:211], v178 offset:54272
	ds_read_b128 v[212:215], v178 offset:55296
	ds_read_b128 v[230:233], v178 offset:56320
	s_add_u32 s48, s80, 0x4000
	s_addc_u32 s49, s81, 0
	s_mov_b32 m0, s24
	s_nop 0
	global_load_lds_dwordx4 v152, s[48:49]
	s_add_u32 s48, s80, 0x6000
	s_addc_u32 s49, s81, 0
	s_mov_b32 m0, s37
	s_nop 0
	global_load_lds_dwordx4 v152, s[48:49]
	s_barrier
	s_waitcnt lgkmcnt(0)
	s_setprio 1
	s_waitcnt lgkmcnt(7)
	v_mfma_f32_16x16x32_bf16 v[100:103], v[128:131], v[144:147], v[100:103]
	v_mfma_f32_16x16x32_bf16 v[64:67], v[136:139], v[144:147], v[64:67]
	s_waitcnt lgkmcnt(5)
	v_mfma_f32_16x16x32_bf16 v[104:107], v[128:131], v[184:187], v[104:107]
	v_mfma_f32_16x16x32_bf16 v[68:71], v[136:139], v[184:187], v[68:71]
	s_waitcnt lgkmcnt(3)
	v_mfma_f32_16x16x32_bf16 v[108:111], v[128:131], v[204:207], v[108:111]
	v_mfma_f32_16x16x32_bf16 v[72:75], v[136:139], v[204:207], v[72:75]
	s_waitcnt lgkmcnt(1)
	v_mfma_f32_16x16x32_bf16 v[112:115], v[128:131], v[212:215], v[112:115]
	v_mfma_f32_16x16x32_bf16 v[76:79], v[136:139], v[212:215], v[76:79]
	v_mfma_f32_16x16x32_bf16 v[100:103], v[132:135], v[148:151], v[100:103]
	v_mfma_f32_16x16x32_bf16 v[64:67], v[140:143], v[148:151], v[64:67]
	v_mfma_f32_16x16x32_bf16 v[104:107], v[132:135], v[200:203], v[104:107]
	v_mfma_f32_16x16x32_bf16 v[68:71], v[140:143], v[200:203], v[68:71]
	v_mfma_f32_16x16x32_bf16 v[108:111], v[132:135], v[208:211], v[108:111]
	v_mfma_f32_16x16x32_bf16 v[72:75], v[140:143], v[208:211], v[72:75]
	s_waitcnt lgkmcnt(0)
	v_mfma_f32_16x16x32_bf16 v[112:115], v[132:135], v[230:233], v[112:115]
	v_mfma_f32_16x16x32_bf16 v[76:79], v[140:143], v[230:233], v[76:79]
	s_setprio 0
	s_barrier
	s_add_u32 s48, s76, 0x84000
	s_addc_u32 s49, s77, 0
	s_mov_b32 m0, s97
	s_nop 0
	global_load_lds_dwordx4 v152, s[48:49]
	s_add_u32 s48, s76, 0x86000
	s_addc_u32 s49, s77, 0
	s_mov_b32 m0, s38
	s_nop 0
	global_load_lds_dwordx4 v152, s[48:49]
	s_waitcnt vmcnt(10)
	s_barrier
	s_setprio 1
	v_mfma_f32_16x16x32_bf16 v[32:35], v[236:239], v[144:147], v[32:35]
	v_mfma_f32_16x16x32_bf16 v[0:3], v[244:247], v[144:147], v[0:3]
	v_mfma_f32_16x16x32_bf16 v[36:39], v[236:239], v[184:187], v[36:39]
	v_mfma_f32_16x16x32_bf16 v[4:7], v[244:247], v[184:187], v[4:7]
	v_mfma_f32_16x16x32_bf16 v[40:43], v[236:239], v[204:207], v[40:43]
	v_mfma_f32_16x16x32_bf16 v[8:11], v[244:247], v[204:207], v[8:11]
	v_mfma_f32_16x16x32_bf16 v[44:47], v[236:239], v[212:215], v[44:47]
	v_mfma_f32_16x16x32_bf16 v[12:15], v[244:247], v[212:215], v[12:15]
	v_mfma_f32_16x16x32_bf16 v[32:35], v[240:243], v[148:151], v[32:35]
	v_mfma_f32_16x16x32_bf16 v[0:3], v[248:251], v[148:151], v[0:3]
	v_mfma_f32_16x16x32_bf16 v[36:39], v[240:243], v[200:203], v[36:39]
	v_mfma_f32_16x16x32_bf16 v[4:7], v[248:251], v[200:203], v[4:7]
	v_mfma_f32_16x16x32_bf16 v[40:43], v[240:243], v[208:211], v[40:43]
	v_mfma_f32_16x16x32_bf16 v[8:11], v[248:251], v[208:211], v[8:11]
	v_mfma_f32_16x16x32_bf16 v[44:47], v[240:243], v[230:233], v[44:47]
	v_mfma_f32_16x16x32_bf16 v[12:15], v[248:251], v[230:233], v[12:15]
	s_setprio 0
	s_add_i32 s71, s71, 2
	s_add_u32 s1, s1, 0x8000
	s_addc_u32 s9, s9, 0
	s_cmp_gt_u32 s71, 29
	s_mov_b64 s[76:77], s[78:79]
	s_barrier
	s_cbranch_scc1 .LBB0_741

; #define PG8_STAGE(bufoff, gbase, hoff, imm) do { _Pragma("unroll") for (int _i = 0; _i < 2; ++_i) { \
;         asm volatile("s_mov_b32 m0, %0\n\ts_nop 0\n\tglobal_load_lds_dwordx4 %1, %2" \
;             :: "s"(lds0 + (unsigned)((bufoff) + _i * 8192)), "v"(voff0), "s"((const char*)(gbase) + (size_t)(hoff) + (size_t)(_i * 8192)) : "memory"); } } while (0)
; #define PG8_LDA(dst, b, h) do { _Pragma("unroll") for (int m = 0; m < 4; ++m) _Pragma("unroll") for (int k = 0; k < 2; ++k) dst[m][k] = *(const LAS bf16x8*)(lds + PG8_SA(b, h) + aoff + m * 2048 + k * 1024); } while (0)
; #define PG8_LDB(dst, b, h) do { _Pragma("unroll") for (int n = 0; n < 2; ++n) _Pragma("unroll") for (int k = 0; k < 2; ++k) dst[n][k] = *(const LAS bf16x8*)(lds + PG8_SB(b, h) + boff + n * 2048 + k * 1024); } while (0)
; #define PG8_MMA(ai, bj, At, Bt) do { __builtin_amdgcn_s_setprio(1); _Pragma("unroll") for (int m = 0; m < 4; ++m) _Pragma("unroll") for (int n = 0; n < 2; ++n) _Pragma("unroll") for (int k = 0; k < 2; ++k) \
;         acc[ai][bj][m][n] = __builtin_amdgcn_mfma_f32_16x16x32_bf16(Bt[n][k], At[m][k], acc[ai][bj][m][n], 0, 0, 0); __builtin_amdgcn_s_setprio(0); } while (0)
; #define PG8_WAIT_L(n) asm volatile("s_waitcnt lgkmcnt(" #n ")" ::: "memory")
; #define PG8_BAR __builtin_amdgcn_s_barrier()
; #define PG8_SCHED __builtin_amdgcn_sched_barrier(0)
; template <class Epi>
; __device__ __forceinline__ void gemm_phase(LAS unsigned char* lds, const Gemm g, const StaticOrder& S, const Epi& E) {
;     ...
;         for (int t = 0; t < nt; t += 2) {
;             const bool last = (t == nt - 2);
;             if (last) E.pre(cur, wid, lane, (unsigned)(size_t)(lds + STAGE_BYTES));
;             const char* aT = cA + (size_t)t * KS;
;             const char* a2 = last ? nA : aT + 2 * KS; const char* b2 = last ? nB : cB + (size_t)(t + 2) * KS;
;             PG8_LDB(B0, 0, 0); PG8_SCHED; PG8_LDA(At, 0, 0); PG8_STAGE(PG8_SA(1, 1), aT + KS, hA, 0);
;             PG8_WAIT_L(8); PG8_BAR; PG8_WAIT_L(0); PG8_MMA(0, 0, At, B0); PG8_BAR; PG8_SCHED;
;             PG8_LDB(B1, 0, 1); PG8_STAGE(PG8_SB(0, 0), b2, 0, 0);
;             PG8_BAR; PG8_WAIT_L(0); PG8_MMA(0, 1, At, B1); PG8_BAR;
;             PG8_LDA(At, 0, 1); PG8_STAGE(PG8_SA(0, 0), a2, 0, 0);
;             PG8_BAR; PG8_WAIT_L(0); PG8_MMA(1, 0, At, B0); PG8_BAR; PG8_SCHED;
.LBB0_860:
	s_add_u32 s58, s56, 0x8000
	v_add_u32_e32 v132, 0x10000, v236
	s_addc_u32 s59, s57, 0
	ds_read_b128 v[120:123], v132
	ds_read_b128 v[124:127], v132 offset:1024
	ds_read_b128 v[128:131], v132 offset:2048
	ds_read_b128 v[132:135], v132 offset:3072
	s_add_u32 s48, s56, 0x164000
	s_addc_u32 s49, s57, 0
	s_add_u32 s60, s56, 0x166000
	s_addc_u32 s61, s57, 0
	s_cmpk_eq_i32 s69, 0x54
	s_cselect_b32 s57, s7, s59
	s_cselect_b32 s56, s6, s58
	ds_read_b128 v[136:139], v237
	ds_read_b128 v[140:143], v237 offset:1024
	ds_read_b128 v[152:155], v237 offset:2048
	ds_read_b128 v[156:159], v237 offset:3072
	ds_read_b128 v[160:163], v237 offset:4096
	ds_read_b128 v[164:167], v237 offset:5120
	ds_read_b128 v[168:171], v237 offset:6144
	ds_read_b128 v[172:175], v237 offset:7168
	s_mov_b32 m0, s65
	s_nop 0
	global_load_lds_dwordx4 v188, s[48:49]
	s_mov_b32 m0, s66
	s_nop 0
	global_load_lds_dwordx4 v188, s[60:61]
	s_waitcnt lgkmcnt(8)
	s_waitcnt vmcnt(10)
	s_barrier
	s_waitcnt lgkmcnt(0)
	s_setprio 1
	s_waitcnt lgkmcnt(7)
	v_mfma_f32_16x16x32_bf16 v[148:151], v[120:123], v[136:139], v[148:151]
	v_mfma_f32_16x16x32_bf16 v[144:147], v[128:131], v[136:139], v[144:147]
	s_waitcnt lgkmcnt(5)
	v_mfma_f32_16x16x32_bf16 v[108:111], v[120:123], v[152:155], v[108:111]
	v_mfma_f32_16x16x32_bf16 v[104:107], v[128:131], v[152:155], v[104:107]
	s_waitcnt lgkmcnt(3)
	v_mfma_f32_16x16x32_bf16 v[92:95], v[120:123], v[160:163], v[92:95]
	v_mfma_f32_16x16x32_bf16 v[88:91], v[128:131], v[160:163], v[88:91]
	s_waitcnt lgkmcnt(1)
	v_mfma_f32_16x16x32_bf16 v[76:79], v[120:123], v[168:171], v[76:79]
	v_mfma_f32_16x16x32_bf16 v[72:75], v[128:131], v[168:171], v[72:75]
	v_mfma_f32_16x16x32_bf16 v[148:151], v[124:127], v[140:143], v[148:151]
	v_mfma_f32_16x16x32_bf16 v[144:147], v[132:135], v[140:143], v[144:147]
	v_mfma_f32_16x16x32_bf16 v[108:111], v[124:127], v[156:159], v[108:111]
	v_mfma_f32_16x16x32_bf16 v[104:107], v[132:135], v[156:159], v[104:107]
	v_mfma_f32_16x16x32_bf16 v[92:95], v[124:127], v[164:167], v[92:95]
	v_mfma_f32_16x16x32_bf16 v[88:91], v[132:135], v[164:167], v[88:91]
	s_waitcnt lgkmcnt(0)
	v_mfma_f32_16x16x32_bf16 v[76:79], v[124:127], v[172:175], v[76:79]
	v_mfma_f32_16x16x32_bf16 v[72:75], v[132:135], v[172:175], v[72:75]
	s_setprio 0
	s_barrier
	v_add_u32_e32 v200, 0x14000, v236
	ds_read_b128 v[176:179], v200
	ds_read_b128 v[180:183], v200 offset:1024
	ds_read_b128 v[184:187], v200 offset:2048
	ds_read_b128 v[200:203], v200 offset:3072
	s_cselect_b32 s60, s8, s0
	s_cselect_b32 s61, s9, s1
	s_mov_b32 m0, s26
	s_nop 0
	global_load_lds_dwordx4 v188, s[60:61]
	s_add_u32 s48, s60, 0x2000
	s_addc_u32 s49, s61, 0
	s_mov_b32 m0, s27
	s_nop 0
	global_load_lds_dwordx4 v188, s[48:49]
	s_waitcnt vmcnt(10)
	s_barrier
	s_waitcnt lgkmcnt(0)
	s_setprio 1
	s_waitcnt lgkmcnt(3)
	v_mfma_f32_16x16x32_bf16 v[116:119], v[176:179], v[136:139], v[116:119]
	s_waitcnt lgkmcnt(1)
	v_mfma_f32_16x16x32_bf16 v[112:115], v[184:187], v[136:139], v[112:115]
	v_mfma_f32_16x16x32_bf16 v[100:103], v[176:179], v[152:155], v[100:103]
	v_mfma_f32_16x16x32_bf16 v[96:99], v[184:187], v[152:155], v[96:99]
	v_mfma_f32_16x16x32_bf16 v[84:87], v[176:179], v[160:163], v[84:87]
	v_mfma_f32_16x16x32_bf16 v[80:83], v[184:187], v[160:163], v[80:83]
	v_mfma_f32_16x16x32_bf16 v[68:71], v[176:179], v[168:171], v[68:71]
	v_mfma_f32_16x16x32_bf16 v[64:67], v[184:187], v[168:171], v[64:67]
	v_mfma_f32_16x16x32_bf16 v[116:119], v[180:183], v[140:143], v[116:119]
	s_waitcnt lgkmcnt(0)
	v_mfma_f32_16x16x32_bf16 v[112:115], v[200:203], v[140:143], v[112:115]
	v_mfma_f32_16x16x32_bf16 v[100:103], v[180:183], v[156:159], v[100:103]
	v_mfma_f32_16x16x32_bf16 v[96:99], v[200:203], v[156:159], v[96:99]
	v_mfma_f32_16x16x32_bf16 v[84:87], v[180:183], v[164:167], v[84:87]
	v_mfma_f32_16x16x32_bf16 v[80:83], v[200:203], v[164:167], v[80:83]
	v_mfma_f32_16x16x32_bf16 v[68:71], v[180:183], v[172:175], v[68:71]
	v_mfma_f32_16x16x32_bf16 v[64:67], v[200:203], v[172:175], v[64:67]
	s_setprio 0
	s_barrier
	ds_read_b128 v[136:139], v237 offset:16384
	ds_read_b128 v[140:143], v237 offset:17408
	ds_read_b128 v[152:155], v237 offset:18432
	ds_read_b128 v[156:159], v237 offset:19456
	ds_read_b128 v[160:163], v237 offset:20480
	ds_read_b128 v[164:167], v237 offset:21504
	ds_read_b128 v[168:171], v237 offset:22528
	ds_read_b128 v[172:175], v237 offset:23552
	s_mov_b32 m0, s25
	s_nop 0
	global_load_lds_dwordx4 v188, s[56:57]
	s_add_u32 s48, s56, 0x2000
	s_addc_u32 s49, s57, 0
	s_mov_b32 m0, s28
	s_nop 0
	global_load_lds_dwordx4 v188, s[48:49]
	s_barrier
	s_waitcnt lgkmcnt(0)
	s_setprio 1
	s_waitcnt lgkmcnt(7)
	v_mfma_f32_16x16x32_bf16 v[60:63], v[120:123], v[136:139], v[60:63]
	v_mfma_f32_16x16x32_bf16 v[56:59], v[128:131], v[136:139], v[56:59]
	s_waitcnt lgkmcnt(5)
	v_mfma_f32_16x16x32_bf16 v[44:47], v[120:123], v[152:155], v[44:47]
	v_mfma_f32_16x16x32_bf16 v[40:43], v[128:131], v[152:155], v[40:43]
	s_waitcnt lgkmcnt(3)
	v_mfma_f32_16x16x32_bf16 v[28:31], v[120:123], v[160:163], v[28:31]
	v_mfma_f32_16x16x32_bf16 v[24:27], v[128:131], v[160:163], v[24:27]
	s_waitcnt lgkmcnt(1)
	v_mfma_f32_16x16x32_bf16 v[12:15], v[120:123], v[168:171], v[12:15]
	v_mfma_f32_16x16x32_bf16 v[8:11], v[128:131], v[168:171], v[8:11]
	v_mfma_f32_16x16x32_bf16 v[60:63], v[124:127], v[140:143], v[60:63]
	v_mfma_f32_16x16x32_bf16 v[56:59], v[132:135], v[140:143], v[56:59]
	v_mfma_f32_16x16x32_bf16 v[44:47], v[124:127], v[156:159], v[44:47]
	v_mfma_f32_16x16x32_bf16 v[40:43], v[132:135], v[156:159], v[40:43]
	v_mfma_f32_16x16x32_bf16 v[28:31], v[124:127], v[164:167], v[28:31]
	v_mfma_f32_16x16x32_bf16 v[24:27], v[132:135], v[164:167], v[24:27]
	s_waitcnt lgkmcnt(0)
	v_mfma_f32_16x16x32_bf16 v[12:15], v[124:127], v[172:175], v[12:15]
	v_mfma_f32_16x16x32_bf16 v[8:11], v[132:135], v[172:175], v[8:11]
	s_setprio 0
	s_barrier
; #define PG8_STAGE(bufoff, gbase, hoff, imm) do { _Pragma("unroll") for (int _i = 0; _i < 2; ++_i) { \
;         asm volatile("s_mov_b32 m0, %0\n\ts_nop 0\n\tglobal_load_lds_dwordx4 %1, %2" \
;             :: "s"(lds0 + (unsigned)((bufoff) + _i * 8192)), "v"(voff0), "s"((const char*)(gbase) + (size_t)(hoff) + (size_t)(_i * 8192)) : "memory"); } } while (0)
; #define PG8_LDA(dst, b, h) do { _Pragma("unroll") for (int m = 0; m < 4; ++m) _Pragma("unroll") for (int k = 0; k < 2; ++k) dst[m][k] = *(const LAS bf16x8*)(lds + PG8_SA(b, h) + aoff + m * 2048 + k * 1024); } while (0)
; #define PG8_LDB(dst, b, h) do { _Pragma("unroll") for (int n = 0; n < 2; ++n) _Pragma("unroll") for (int k = 0; k < 2; ++k) dst[n][k] = *(const LAS bf16x8*)(lds + PG8_SB(b, h) + boff + n * 2048 + k * 1024); } while (0)
; #define PG8_MMA(ai, bj, At, Bt) do { __builtin_amdgcn_s_setprio(1); _Pragma("unroll") for (int m = 0; m < 4; ++m) _Pragma("unroll") for (int n = 0; n < 2; ++n) _Pragma("unroll") for (int k = 0; k < 2; ++k) \
;         acc[ai][bj][m][n] = __builtin_amdgcn_mfma_f32_16x16x32_bf16(Bt[n][k], At[m][k], acc[ai][bj][m][n], 0, 0, 0); __builtin_amdgcn_s_setprio(0); } while (0)
; #define PG8_WAIT_V(n) asm volatile("s_waitcnt vmcnt(" #n ")" ::: "memory")
; #define PG8_WAIT_L(n) asm volatile("s_waitcnt lgkmcnt(" #n ")" ::: "memory")
; #define PG8_BAR __builtin_amdgcn_s_barrier()
; #define PG8_SCHED __builtin_amdgcn_sched_barrier(0)
; template <class Epi>
; __device__ __forceinline__ void gemm_phase(LAS unsigned char* lds, const Gemm g, const StaticOrder& S, const Epi& E) {
;     ...
;             PG8_STAGE(PG8_SB(0, 1), b2, hB, 0);
;             PG8_WAIT_V(6); PG8_BAR; PG8_MMA(1, 1, At, B1); PG8_BAR;
;             PG8_LDB(B0, 1, 0); PG8_SCHED; PG8_LDA(At, 1, 0); PG8_STAGE(PG8_SA(0, 1), a2, hA, 0);
;             PG8_WAIT_L(8); PG8_BAR; PG8_WAIT_L(0); PG8_MMA(0, 0, At, B0); PG8_BAR; PG8_SCHED;
;             PG8_LDB(B1, 1, 1); PG8_STAGE(PG8_SB(1, 0), b2 + KS, 0, 0);
;             PG8_BAR; PG8_WAIT_L(0); PG8_MMA(0, 1, At, B1); PG8_BAR;
;             PG8_LDA(At, 1, 1); PG8_STAGE(PG8_SA(1, 0), a2 + KS, 0, 0);
	s_add_u32 s48, s60, 0x160000
	s_addc_u32 s49, s61, 0
	s_mov_b32 m0, s29
	s_nop 0
	global_load_lds_dwordx4 v188, s[48:49]
	s_add_u32 s48, s60, 0x162000
	s_addc_u32 s49, s61, 0
	s_mov_b32 m0, s30
	s_nop 0
	global_load_lds_dwordx4 v188, s[48:49]
	s_waitcnt vmcnt(10)
	s_barrier
	s_setprio 1
	v_mfma_f32_16x16x32_bf16 v[52:55], v[176:179], v[136:139], v[52:55]
	v_mfma_f32_16x16x32_bf16 v[48:51], v[184:187], v[136:139], v[48:51]
	v_mfma_f32_16x16x32_bf16 v[36:39], v[176:179], v[152:155], v[36:39]
	v_mfma_f32_16x16x32_bf16 v[32:35], v[184:187], v[152:155], v[32:35]
	v_mfma_f32_16x16x32_bf16 v[20:23], v[176:179], v[160:163], v[20:23]
	v_mfma_f32_16x16x32_bf16 v[16:19], v[184:187], v[160:163], v[16:19]
	v_mfma_f32_16x16x32_bf16 v[4:7], v[176:179], v[168:171], v[4:7]
	v_mfma_f32_16x16x32_bf16 v[0:3], v[184:187], v[168:171], v[0:3]
	v_mfma_f32_16x16x32_bf16 v[52:55], v[180:183], v[140:143], v[52:55]
	v_mfma_f32_16x16x32_bf16 v[48:51], v[200:203], v[140:143], v[48:51]
	v_mfma_f32_16x16x32_bf16 v[36:39], v[180:183], v[156:159], v[36:39]
	v_mfma_f32_16x16x32_bf16 v[32:35], v[200:203], v[156:159], v[32:35]
	v_mfma_f32_16x16x32_bf16 v[20:23], v[180:183], v[164:167], v[20:23]
	v_mfma_f32_16x16x32_bf16 v[16:19], v[200:203], v[164:167], v[16:19]
	v_mfma_f32_16x16x32_bf16 v[4:7], v[180:183], v[172:175], v[4:7]
	v_mfma_f32_16x16x32_bf16 v[0:3], v[200:203], v[172:175], v[0:3]
	s_setprio 0
	v_add_u32_e32 v132, 0x18000, v236
	s_barrier
	ds_read_b128 v[120:123], v132
	ds_read_b128 v[124:127], v132 offset:1024
	ds_read_b128 v[128:131], v132 offset:2048
	ds_read_b128 v[132:135], v132 offset:3072
	ds_read_b128 v[136:139], v237 offset:32768
	ds_read_b128 v[140:143], v237 offset:33792
	ds_read_b128 v[152:155], v237 offset:34816
	ds_read_b128 v[156:159], v237 offset:35840
	ds_read_b128 v[160:163], v237 offset:36864
	ds_read_b128 v[164:167], v237 offset:37888
	ds_read_b128 v[168:171], v237 offset:38912
	ds_read_b128 v[172:175], v237 offset:39936
	s_add_u32 s48, s56, 0x160000
	s_addc_u32 s49, s57, 0
	s_mov_b32 m0, s34
	s_nop 0
	global_load_lds_dwordx4 v188, s[48:49]
	s_add_u32 s48, s56, 0x162000
	s_addc_u32 s49, s57, 0
	s_mov_b32 m0, s37
	s_nop 0
	global_load_lds_dwordx4 v188, s[48:49]
	s_waitcnt lgkmcnt(8)
	s_waitcnt vmcnt(10)
	s_barrier
	s_waitcnt lgkmcnt(0)
	s_setprio 1
	s_waitcnt lgkmcnt(7)
	v_mfma_f32_16x16x32_bf16 v[148:151], v[120:123], v[136:139], v[148:151]
	v_mfma_f32_16x16x32_bf16 v[144:147], v[128:131], v[136:139], v[144:147]
	s_waitcnt lgkmcnt(5)
	v_mfma_f32_16x16x32_bf16 v[108:111], v[120:123], v[152:155], v[108:111]
	v_mfma_f32_16x16x32_bf16 v[104:107], v[128:131], v[152:155], v[104:107]
	s_waitcnt lgkmcnt(3)
	v_mfma_f32_16x16x32_bf16 v[92:95], v[120:123], v[160:163], v[92:95]
	v_mfma_f32_16x16x32_bf16 v[88:91], v[128:131], v[160:163], v[88:91]
	s_waitcnt lgkmcnt(1)
	v_mfma_f32_16x16x32_bf16 v[76:79], v[120:123], v[168:171], v[76:79]
	v_mfma_f32_16x16x32_bf16 v[72:75], v[128:131], v[168:171], v[72:75]
	v_mfma_f32_16x16x32_bf16 v[148:151], v[124:127], v[140:143], v[148:151]
	v_mfma_f32_16x16x32_bf16 v[144:147], v[132:135], v[140:143], v[144:147]
	v_mfma_f32_16x16x32_bf16 v[108:111], v[124:127], v[156:159], v[108:111]
	v_mfma_f32_16x16x32_bf16 v[104:107], v[132:135], v[156:159], v[104:107]
	v_mfma_f32_16x16x32_bf16 v[92:95], v[124:127], v[164:167], v[92:95]
	v_mfma_f32_16x16x32_bf16 v[88:91], v[132:135], v[164:167], v[88:91]
	s_waitcnt lgkmcnt(0)
	v_mfma_f32_16x16x32_bf16 v[76:79], v[124:127], v[172:175], v[76:79]
	v_mfma_f32_16x16x32_bf16 v[72:75], v[132:135], v[172:175], v[72:75]
	s_setprio 0
	s_barrier
	v_add_u32_e32 v200, 0x1c000, v236
	ds_read_b128 v[176:179], v200
	ds_read_b128 v[180:183], v200 offset:1024
	ds_read_b128 v[184:187], v200 offset:2048
	ds_read_b128 v[200:203], v200 offset:3072
	s_add_u32 s48, s60, 0x4000
	s_addc_u32 s49, s61, 0
	s_mov_b32 m0, s41
	s_nop 0
	global_load_lds_dwordx4 v188, s[48:49]
	s_add_u32 s48, s60, 0x6000
	s_addc_u32 s49, s61, 0
	s_mov_b32 m0, s42
	s_nop 0
	global_load_lds_dwordx4 v188, s[48:49]
	s_waitcnt vmcnt(10)
	s_barrier
	s_waitcnt lgkmcnt(0)
	s_setprio 1
	s_waitcnt lgkmcnt(3)
	v_mfma_f32_16x16x32_bf16 v[116:119], v[176:179], v[136:139], v[116:119]
	s_waitcnt lgkmcnt(1)
	v_mfma_f32_16x16x32_bf16 v[112:115], v[184:187], v[136:139], v[112:115]
	v_mfma_f32_16x16x32_bf16 v[100:103], v[176:179], v[152:155], v[100:103]
	v_mfma_f32_16x16x32_bf16 v[96:99], v[184:187], v[152:155], v[96:99]
	v_mfma_f32_16x16x32_bf16 v[84:87], v[176:179], v[160:163], v[84:87]
	v_mfma_f32_16x16x32_bf16 v[80:83], v[184:187], v[160:163], v[80:83]
	v_mfma_f32_16x16x32_bf16 v[68:71], v[176:179], v[168:171], v[68:71]
	v_mfma_f32_16x16x32_bf16 v[64:67], v[184:187], v[168:171], v[64:67]
	v_mfma_f32_16x16x32_bf16 v[116:119], v[180:183], v[140:143], v[116:119]
	s_waitcnt lgkmcnt(0)
	v_mfma_f32_16x16x32_bf16 v[112:115], v[200:203], v[140:143], v[112:115]
	v_mfma_f32_16x16x32_bf16 v[100:103], v[180:183], v[156:159], v[100:103]
	v_mfma_f32_16x16x32_bf16 v[96:99], v[200:203], v[156:159], v[96:99]
	v_mfma_f32_16x16x32_bf16 v[84:87], v[180:183], v[164:167], v[84:87]
	v_mfma_f32_16x16x32_bf16 v[80:83], v[200:203], v[164:167], v[80:83]
	v_mfma_f32_16x16x32_bf16 v[68:71], v[180:183], v[172:175], v[68:71]
	v_mfma_f32_16x16x32_bf16 v[64:67], v[200:203], v[172:175], v[64:67]
	s_setprio 0
	s_barrier
	ds_read_b128 v[136:139], v237 offset:49152
	ds_read_b128 v[140:143], v237 offset:50176
	ds_read_b128 v[152:155], v237 offset:51200
	ds_read_b128 v[156:159], v237 offset:52224
	ds_read_b128 v[160:163], v237 offset:53248
	ds_read_b128 v[164:167], v237 offset:54272
	ds_read_b128 v[168:171], v237 offset:55296
	ds_read_b128 v[172:175], v237 offset:56320
	s_add_u32 s48, s56, 0x4000
	s_addc_u32 s49, s57, 0
	s_mov_b32 m0, s43
	s_nop 0
	global_load_lds_dwordx4 v188, s[48:49]
	s_add_u32 s48, s56, 0x6000
	s_addc_u32 s49, s57, 0
	s_mov_b32 m0, s62
	s_nop 0
	global_load_lds_dwordx4 v188, s[48:49]
	s_barrier
; #define PG8_WAIT_V(n) asm volatile("s_waitcnt vmcnt(" #n ")" ::: "memory")
; template <class Epi>
; __device__ __forceinline__ void gemm_phase(LAS unsigned char* lds, const Gemm g, const StaticOrder& S, const Epi& E) {
;     ...
;             PG8_LDA(At, 1, 1); PG8_STAGE(PG8_SA(1, 0), a2 + KS, 0, 0);
;             PG8_BAR; PG8_WAIT_L(0); PG8_MMA(1, 0, At, B0); PG8_BAR; PG8_SCHED;
;             PG8_STAGE(PG8_SB(1, 1), b2 + KS, hB, 0);
;             PG8_WAIT_V(6); PG8_BAR; PG8_MMA(1, 1, At, B1); PG8_BAR;
;     __device__ __forceinline__ void operator()(f32x4 (&acc)[2][2][4][2], const Unit& u, int wr, int wc, int fr, int fq, LAS unsigned char*) const {
;         const int b = u.pm >> 6;
;         const int col0 = u.pn * BM + wc * 32 + 8 * fq;
;         const size_t off0 = (size_t)(u.pm * BM + wr * 64 + fr) * D + col0;
;         f32x4 sc[2][2];
; #pragma unroll
;         for (int bj = 0; bj < 2; ++bj)
; #pragma unroll
;             for (int n = 0; n < 2; ++n) { f32x4 gt = *(const f32x4*)(gate + (size_t)b * MODW + col0 + bj * HALF + n * 4); sc[bj][n] = gt + 1.0f;
;                 if (cs) sc[bj][n] *= *(const f32x4*)(cs + col0 + bj * HALF + n * 4); }
;         if (IN_F32) {
; #pragma unroll
;             for (int ai = 0; ai < 2; ++ai) {
;                 f32x4 r[4][2][2];
; #pragma unroll
;                 for (int m = 0; m < 4; ++m)
; #pragma unroll
;                     for (int bj = 0; bj < 2; ++bj)
; #pragma unroll
;                         for (int n = 0; n < 2; ++n) r[m][bj][n] = *(const f32x4*)((const float*)in + off0 + (size_t)(ai * HALF + m * 16) * D + bj * HALF + n * 4);
; #pragma unroll
;                 for (int m = 0; m < 4; ++m)
; #pragma unroll
;                     for (int bj = 0; bj < 2; ++bj) { const f32x4 r0 = r[m][bj][0] + sc[bj][0] * acc[ai][bj][m][0], r1 = r[m][bj][1] + sc[bj][1] * acc[ai][bj][m][1];
;                         u32x4 w; w.x = cvt_pk_bf16(r0[0], r0[1]); w.y = cvt_pk_bf16(r0[2], r0[3]); w.z = cvt_pk_bf16(r1[0], r1[1]); w.w = cvt_pk_bf16(r1[2], r1[3]);
;                         *(u32x4*)(out + off0 + (size_t)(ai * HALF + m * 16) * D + bj * HALF) = w; }
;                 asm volatile("" ::: "memory");
;             }
;         } else {
;             u32x4 xb[2][4][2];
; #pragma unroll
;             for (int ai = 0; ai < 2; ++ai)
; #pragma unroll
;                 for (int m = 0; m < 4; ++m)
; #pragma unroll
	s_waitcnt lgkmcnt(0)
	s_setprio 1
	s_waitcnt lgkmcnt(7)
	v_mfma_f32_16x16x32_bf16 v[60:63], v[120:123], v[136:139], v[60:63]
	v_mfma_f32_16x16x32_bf16 v[56:59], v[128:131], v[136:139], v[56:59]
	s_waitcnt lgkmcnt(5)
	v_mfma_f32_16x16x32_bf16 v[44:47], v[120:123], v[152:155], v[44:47]
	v_mfma_f32_16x16x32_bf16 v[40:43], v[128:131], v[152:155], v[40:43]
	s_waitcnt lgkmcnt(3)
	v_mfma_f32_16x16x32_bf16 v[28:31], v[120:123], v[160:163], v[28:31]
	v_mfma_f32_16x16x32_bf16 v[24:27], v[128:131], v[160:163], v[24:27]
	s_waitcnt lgkmcnt(1)
	v_mfma_f32_16x16x32_bf16 v[12:15], v[120:123], v[168:171], v[12:15]
	v_mfma_f32_16x16x32_bf16 v[8:11], v[128:131], v[168:171], v[8:11]
	v_mfma_f32_16x16x32_bf16 v[60:63], v[124:127], v[140:143], v[60:63]
	v_mfma_f32_16x16x32_bf16 v[56:59], v[132:135], v[140:143], v[56:59]
	v_mfma_f32_16x16x32_bf16 v[44:47], v[124:127], v[156:159], v[44:47]
	v_mfma_f32_16x16x32_bf16 v[40:43], v[132:135], v[156:159], v[40:43]
	v_mfma_f32_16x16x32_bf16 v[28:31], v[124:127], v[164:167], v[28:31]
	v_mfma_f32_16x16x32_bf16 v[24:27], v[132:135], v[164:167], v[24:27]
	s_waitcnt lgkmcnt(0)
	v_mfma_f32_16x16x32_bf16 v[12:15], v[124:127], v[172:175], v[12:15]
	v_mfma_f32_16x16x32_bf16 v[8:11], v[132:135], v[172:175], v[8:11]
	s_setprio 0
	s_barrier
	s_add_u32 s48, s60, 0x164000
	s_addc_u32 s49, s61, 0
	s_mov_b32 m0, s63
	s_nop 0
	global_load_lds_dwordx4 v188, s[48:49]
	s_add_u32 s48, s60, 0x166000
	s_addc_u32 s49, s61, 0
	s_mov_b32 m0, s64
	s_nop 0
	global_load_lds_dwordx4 v188, s[48:49]
	s_waitcnt vmcnt(10)
	s_barrier
	s_setprio 1
	v_mfma_f32_16x16x32_bf16 v[52:55], v[176:179], v[136:139], v[52:55]
	v_mfma_f32_16x16x32_bf16 v[48:51], v[184:187], v[136:139], v[48:51]
	v_mfma_f32_16x16x32_bf16 v[36:39], v[176:179], v[152:155], v[36:39]
	v_mfma_f32_16x16x32_bf16 v[32:35], v[184:187], v[152:155], v[32:35]
	v_mfma_f32_16x16x32_bf16 v[20:23], v[176:179], v[160:163], v[20:23]
	v_mfma_f32_16x16x32_bf16 v[16:19], v[184:187], v[160:163], v[16:19]
	v_mfma_f32_16x16x32_bf16 v[4:7], v[176:179], v[168:171], v[4:7]
	v_mfma_f32_16x16x32_bf16 v[0:3], v[184:187], v[168:171], v[0:3]
	v_mfma_f32_16x16x32_bf16 v[52:55], v[180:183], v[140:143], v[52:55]
	v_mfma_f32_16x16x32_bf16 v[48:51], v[200:203], v[140:143], v[48:51]
	v_mfma_f32_16x16x32_bf16 v[36:39], v[180:183], v[156:159], v[36:39]
	v_mfma_f32_16x16x32_bf16 v[32:35], v[200:203], v[156:159], v[32:35]
	v_mfma_f32_16x16x32_bf16 v[20:23], v[180:183], v[164:167], v[20:23]
	v_mfma_f32_16x16x32_bf16 v[16:19], v[200:203], v[164:167], v[16:19]
	v_mfma_f32_16x16x32_bf16 v[4:7], v[180:183], v[172:175], v[4:7]
	v_mfma_f32_16x16x32_bf16 v[0:3], v[200:203], v[172:175], v[0:3]
	s_setprio 0
	s_add_i32 s69, s69, 2
	s_add_u32 s0, s0, 0x8000
	s_addc_u32 s1, s1, 0
	s_cmpk_gt_u32 s69, 0x55
	s_mov_b64 s[56:57], s[58:59]
	s_barrier
	s_cbranch_scc0 .LBB0_860
	s_ashr_i32 s0, s50, 6
	s_mul_hi_i32 s1, s0, 0xc000
	s_mul_i32 s0, s0, 0xc000
	v_lshl_or_b32 v128, s51, 8, v234
	s_add_u32 s0, s39, s0
	v_ashrrev_i32_e32 v129, 31, v128
	s_addc_u32 s1, s40, s1
	v_lshl_add_u64 v[130:131], v[128:129], 2, s[0:1]
	global_load_dwordx4 v[120:123], v[130:131], off offset:16
	global_load_dwordx4 v[124:127], v[130:131], off
	s_mov_b32 s51, s67
	s_mov_b64 s[58:59], s[8:9]
	s_mov_b64 s[56:57], s[6:7]
	s_waitcnt vmcnt(1)
	v_pk_add_f32 v[210:211], v[122:123], 1.0 op_sel_hi:[1,0]
	s_waitcnt vmcnt(0)
	v_pk_add_f32 v[214:215], v[126:127], 1.0 op_sel_hi:[1,0]
	v_pk_add_f32 v[212:213], v[124:125], 1.0 op_sel_hi:[1,0]
	v_pk_add_f32 v[208:209], v[120:121], 1.0 op_sel_hi:[1,0]
	global_load_dwordx4 v[120:123], v[130:131], off offset:528
	global_load_dwordx4 v[124:127], v[130:131], off offset:512
	s_waitcnt vmcnt(1)
	v_pk_add_f32 v[200:201], v[120:121], 1.0 op_sel_hi:[1,0]
	v_lshl_add_u32 v120, s50, 8, v233
	v_ashrrev_i32_e32 v121, 31, v120
	v_lshlrev_b64 v[120:121], 11, v[120:121]
	v_lshl_add_u64 v[120:121], v[120:121], 0, v[128:129]
	v_lshlrev_b64 v[216:217], 1, v[120:121]
	v_lshl_add_u64 v[120:121], s[52:53], 0, v[216:217]
	global_load_dwordx4 v[238:241], v[120:121], off
	global_load_dwordx4 v[184:187], v[120:121], off offset:256
	v_pk_add_f32 v[202:203], v[122:123], 1.0 op_sel_hi:[1,0]
	v_add_co_u32_e32 v122, vcc, s45, v120
	s_waitcnt vmcnt(2)
	v_pk_add_f32 v[206:207], v[126:127], 1.0 op_sel_hi:[1,0]
	v_addc_co_u32_e32 v123, vcc, 0, v121, vcc
	global_load_dwordx4 v[180:183], v[122:123], off
	global_load_dwordx4 v[176:179], v[122:123], off offset:256
	v_add_co_u32_e32 v122, vcc, s36, v120
	v_pk_add_f32 v[204:205], v[124:125], 1.0 op_sel_hi:[1,0]
	s_nop 0
	v_addc_co_u32_e32 v123, vcc, 0, v121, vcc
	global_load_dwordx4 v[172:175], v[122:123], off
	global_load_dwordx4 v[168:171], v[122:123], off offset:256
	v_add_co_u32_e32 v122, vcc, s23, v120
	s_mov_b32 s50, s68
	s_nop 0
	v_addc_co_u32_e32 v123, vcc, 0, v121, vcc
	global_load_dwordx4 v[164:167], v[122:123], off
	global_load_dwordx4 v[160:163], v[122:123], off offset:256
	v_add_co_u32_e32 v122, vcc, s93, v120
	s_waitcnt vmcnt(7)
; __device__ __forceinline__ unsigned cvt_pk_bf16(float lo, float hi) { unsigned r; asm volatile("v_cvt_pk_bf16_f32 %0, %1, %2" : "=v"(r) : "v"(lo), "v"(hi)); return r; }
;     __device__ __forceinline__ void operator()(f32x4 (&acc)[2][2][4][2], const Unit& u, int wr, int wc, int fr, int fq, LAS unsigned char*) const {
;     ...
;             u32x4 xb[2][4][2];
; #pragma unroll
;             for (int ai = 0; ai < 2; ++ai)
; #pragma unroll
;                 for (int m = 0; m < 4; ++m)
; #pragma unroll
;                     for (int bj = 0; bj < 2; ++bj) xb[ai][m][bj] = *(const u32x4*)((const bf16_t*)in + off0 + (size_t)(ai * HALF + m * 16) * D + bj * HALF);
; #pragma unroll
;             for (int ai = 0; ai < 2; ++ai)
; #pragma unroll
;                 for (int m = 0; m < 4; ++m)
; #pragma unroll
;                     for (int bj = 0; bj < 2; ++bj) { const u32x4 x = xb[ai][m][bj];
;                         f32x4 r0 = (f32x4){__uint_as_float(x.x << 16), __uint_as_float(x.x & 0xffff0000u), __uint_as_float(x.y << 16), __uint_as_float(x.y & 0xffff0000u)};
;                         f32x4 r1 = (f32x4){__uint_as_float(x.z << 16), __uint_as_float(x.z & 0xffff0000u), __uint_as_float(x.w << 16), __uint_as_float(x.w & 0xffff0000u)};
;                         r0 += sc[bj][0] * acc[ai][bj][m][0]; r1 += sc[bj][1] * acc[ai][bj][m][1];
;                         u32x4 w; w.x = cvt_pk_bf16(r0[0], r0[1]); w.y = cvt_pk_bf16(r0[2], r0[3]); w.z = cvt_pk_bf16(r1[0], r1[1]); w.w = cvt_pk_bf16(r1[2], r1[3]);
;                         *(u32x4*)(out + off0 + (size_t)(ai * HALF + m * 16) * D + bj * HALF) = w; }
	v_lshlrev_b32_e32 v230, 16, v238
	v_addc_co_u32_e32 v123, vcc, 0, v121, vcc
	global_load_dwordx4 v[156:159], v[122:123], off
	global_load_dwordx4 v[152:155], v[122:123], off offset:256
	v_add_co_u32_e32 v122, vcc, s33, v120
	v_and_b32_e32 v231, 0xffff0000, v238
	s_nop 0
	v_addc_co_u32_e32 v123, vcc, 0, v121, vcc
	global_load_dwordx4 v[140:143], v[122:123], off
	global_load_dwordx4 v[136:139], v[122:123], off offset:256
	v_add_co_u32_e32 v122, vcc, s18, v120
	v_lshlrev_b32_e32 v242, 16, v240
	s_nop 0
	v_addc_co_u32_e32 v123, vcc, 0, v121, vcc
	global_load_dwordx4 v[132:135], v[122:123], off
	global_load_dwordx4 v[128:131], v[122:123], off offset:256
	v_add_co_u32_e32 v120, vcc, s19, v120
	v_and_b32_e32 v243, 0xffff0000, v240
	s_nop 0
	v_addc_co_u32_e32 v121, vcc, 0, v121, vcc
	global_load_dwordx4 v[124:127], v[120:121], off
	s_nop 0
	global_load_dwordx4 v[120:123], v[120:121], off offset:256
	v_lshlrev_b32_e32 v238, 16, v239
	v_and_b32_e32 v239, 0xffff0000, v239
	v_lshlrev_b32_e32 v240, 16, v241
	v_and_b32_e32 v241, 0xffff0000, v241
	v_pk_fma_f32 v[148:149], v[148:149], v[212:213], v[230:231]
	v_pk_fma_f32 v[144:145], v[144:145], v[208:209], v[242:243]
	v_pk_fma_f32 v[150:151], v[150:151], v[214:215], v[238:239]
	v_pk_fma_f32 v[230:231], v[146:147], v[210:211], v[240:241]
	v_cvt_pk_bf16_f32 v146, v148, v149
	v_cvt_pk_bf16_f32 v147, v150, v151
	v_cvt_pk_bf16_f32 v148, v144, v145
	v_lshl_add_u64 v[144:145], s[54:55], 0, v[216:217]
	v_cvt_pk_bf16_f32 v149, v230, v231
	global_store_dwordx4 v[144:145], v[146:149], off
	s_waitcnt vmcnt(15)
	v_lshlrev_b32_e32 v150, 16, v186
	v_and_b32_e32 v151, 0xffff0000, v186
	v_lshlrev_b32_e32 v146, 16, v184
	v_and_b32_e32 v147, 0xffff0000, v184
	v_lshlrev_b32_e32 v148, 16, v185
	v_and_b32_e32 v149, 0xffff0000, v185
	v_lshlrev_b32_e32 v184, 16, v187
	v_and_b32_e32 v185, 0xffff0000, v187
	v_pk_fma_f32 v[118:119], v[118:119], v[206:207], v[148:149]
	v_pk_fma_f32 v[116:117], v[116:117], v[204:205], v[146:147]
	v_pk_fma_f32 v[146:147], v[114:115], v[202:203], v[184:185]
	v_pk_fma_f32 v[114:115], v[112:113], v[200:201], v[150:151]
	v_cvt_pk_bf16_f32 v112, v116, v117
	v_cvt_pk_bf16_f32 v113, v118, v119
	s_waitcnt vmcnt(14)
	v_lshlrev_b32_e32 v116, 16, v182
	v_cvt_pk_bf16_f32 v114, v114, v115
	v_cvt_pk_bf16_f32 v115, v146, v147
	global_store_dwordx4 v[144:145], v[112:115], off offset:256
	v_and_b32_e32 v117, 0xffff0000, v182
	v_lshlrev_b32_e32 v118, 16, v183
	v_lshlrev_b32_e32 v112, 16, v180
	v_and_b32_e32 v113, 0xffff0000, v180
	v_and_b32_e32 v119, 0xffff0000, v183
	v_pk_fma_f32 v[108:109], v[108:109], v[212:213], v[112:113]
	v_lshlrev_b32_e32 v114, 16, v181
	v_and_b32_e32 v115, 0xffff0000, v181
	v_pk_fma_f32 v[112:113], v[106:107], v[210:211], v[118:119]
	v_pk_fma_f32 v[106:107], v[104:105], v[208:209], v[116:117]
	v_cvt_pk_bf16_f32 v104, v108, v109
	v_add_co_u32_e32 v108, vcc, s45, v144
	v_pk_fma_f32 v[110:111], v[110:111], v[214:215], v[114:115]
	s_nop 0
	v_addc_co_u32_e32 v109, vcc, 0, v145, vcc
	v_cvt_pk_bf16_f32 v105, v110, v111
	v_cvt_pk_bf16_f32 v106, v106, v107
	v_cvt_pk_bf16_f32 v107, v112, v113
	global_store_dwordx4 v[108:109], v[104:107], off
	s_waitcnt vmcnt(15)
	v_lshlrev_b32_e32 v110, 16, v178
	v_and_b32_e32 v111, 0xffff0000, v178
	v_lshlrev_b32_e32 v104, 16, v176
	v_and_b32_e32 v105, 0xffff0000, v176
	v_lshlrev_b32_e32 v106, 16, v177
	v_and_b32_e32 v107, 0xffff0000, v177
	v_lshlrev_b32_e32 v112, 16, v179
	v_and_b32_e32 v113, 0xffff0000, v179
	v_pk_fma_f32 v[102:103], v[102:103], v[206:207], v[106:107]
	v_pk_fma_f32 v[100:101], v[100:101], v[204:205], v[104:105]
	v_pk_fma_f32 v[104:105], v[98:99], v[202:203], v[112:113]
	v_pk_fma_f32 v[98:99], v[96:97], v[200:201], v[110:111]
	v_cvt_pk_bf16_f32 v96, v100, v101
	v_cvt_pk_bf16_f32 v97, v102, v103
	s_waitcnt vmcnt(14)
	v_lshlrev_b32_e32 v100, 16, v174
	v_cvt_pk_bf16_f32 v98, v98, v99
	v_cvt_pk_bf16_f32 v99, v104, v105
	global_store_dwordx4 v[108:109], v[96:99], off offset:256
	v_and_b32_e32 v101, 0xffff0000, v174
	v_lshlrev_b32_e32 v102, 16, v175
	v_lshlrev_b32_e32 v96, 16, v172
	v_and_b32_e32 v97, 0xffff0000, v172
	v_and_b32_e32 v103, 0xffff0000, v175
	v_pk_fma_f32 v[92:93], v[92:93], v[212:213], v[96:97]
	v_lshlrev_b32_e32 v98, 16, v173
	v_and_b32_e32 v99, 0xffff0000, v173
	v_pk_fma_f32 v[96:97], v[90:91], v[210:211], v[102:103]
	v_pk_fma_f32 v[90:91], v[88:89], v[208:209], v[100:101]
	v_cvt_pk_bf16_f32 v88, v92, v93
	v_add_co_u32_e32 v92, vcc, s36, v144
	v_pk_fma_f32 v[94:95], v[94:95], v[214:215], v[98:99]
	s_nop 0
	v_addc_co_u32_e32 v93, vcc, 0, v145, vcc
	v_cvt_pk_bf16_f32 v89, v94, v95
	v_cvt_pk_bf16_f32 v90, v90, v91
	v_cvt_pk_bf16_f32 v91, v96, v97
	global_store_dwordx4 v[92:93], v[88:91], off
	s_waitcnt vmcnt(15)
	v_lshlrev_b32_e32 v94, 16, v170
	v_and_b32_e32 v95, 0xffff0000, v170
	v_lshlrev_b32_e32 v88, 16, v168
	v_and_b32_e32 v89, 0xffff0000, v168
	v_lshlrev_b32_e32 v90, 16, v169
	v_and_b32_e32 v91, 0xffff0000, v169
	v_lshlrev_b32_e32 v96, 16, v171
	v_and_b32_e32 v97, 0xffff0000, v171
	v_pk_fma_f32 v[86:87], v[86:87], v[206:207], v[90:91]
	v_pk_fma_f32 v[84:85], v[84:85], v[204:205], v[88:89]
	v_pk_fma_f32 v[88:89], v[82:83], v[202:203], v[96:97]
	v_pk_fma_f32 v[82:83], v[80:81], v[200:201], v[94:95]
	v_cvt_pk_bf16_f32 v80, v84, v85
	v_cvt_pk_bf16_f32 v81, v86, v87
	s_waitcnt vmcnt(14)
; __device__ __forceinline__ unsigned cvt_pk_bf16(float lo, float hi) { unsigned r; asm volatile("v_cvt_pk_bf16_f32 %0, %1, %2" : "=v"(r) : "v"(lo), "v"(hi)); return r; }
;     __device__ __forceinline__ void operator()(f32x4 (&acc)[2][2][4][2], const Unit& u, int wr, int wc, int fr, int fq, LAS unsigned char*) const {
;     ...
;             for (int ai = 0; ai < 2; ++ai)
; #pragma unroll
;                 for (int m = 0; m < 4; ++m)
; #pragma unroll
;                     for (int bj = 0; bj < 2; ++bj) { const u32x4 x = xb[ai][m][bj];
;                         f32x4 r0 = (f32x4){__uint_as_float(x.x << 16), __uint_as_float(x.x & 0xffff0000u), __uint_as_float(x.y << 16), __uint_as_float(x.y & 0xffff0000u)};
;                         f32x4 r1 = (f32x4){__uint_as_float(x.z << 16), __uint_as_float(x.z & 0xffff0000u), __uint_as_float(x.w << 16), __uint_as_float(x.w & 0xffff0000u)};
;                         r0 += sc[bj][0] * acc[ai][bj][m][0]; r1 += sc[bj][1] * acc[ai][bj][m][1];
;                         u32x4 w; w.x = cvt_pk_bf16(r0[0], r0[1]); w.y = cvt_pk_bf16(r0[2], r0[3]); w.z = cvt_pk_bf16(r1[0], r1[1]); w.w = cvt_pk_bf16(r1[2], r1[3]);
;                         *(u32x4*)(out + off0 + (size_t)(ai * HALF + m * 16) * D + bj * HALF) = w; }
	v_lshlrev_b32_e32 v84, 16, v166
	v_cvt_pk_bf16_f32 v82, v82, v83
	v_cvt_pk_bf16_f32 v83, v88, v89
	global_store_dwordx4 v[92:93], v[80:83], off offset:256
	v_and_b32_e32 v85, 0xffff0000, v166
	v_lshlrev_b32_e32 v86, 16, v167
	v_lshlrev_b32_e32 v80, 16, v164
	v_and_b32_e32 v81, 0xffff0000, v164
	v_and_b32_e32 v87, 0xffff0000, v167
	v_pk_fma_f32 v[76:77], v[76:77], v[212:213], v[80:81]
	v_lshlrev_b32_e32 v82, 16, v165
	v_and_b32_e32 v83, 0xffff0000, v165
	v_pk_fma_f32 v[80:81], v[74:75], v[210:211], v[86:87]
	v_pk_fma_f32 v[74:75], v[72:73], v[208:209], v[84:85]
	v_cvt_pk_bf16_f32 v72, v76, v77
	v_add_co_u32_e32 v76, vcc, s23, v144
	v_pk_fma_f32 v[78:79], v[78:79], v[214:215], v[82:83]
	s_nop 0
	v_addc_co_u32_e32 v77, vcc, 0, v145, vcc
	v_cvt_pk_bf16_f32 v73, v78, v79
	v_cvt_pk_bf16_f32 v74, v74, v75
	v_cvt_pk_bf16_f32 v75, v80, v81
	global_store_dwordx4 v[76:77], v[72:75], off
	s_waitcnt vmcnt(15)
	v_lshlrev_b32_e32 v78, 16, v162
	v_and_b32_e32 v79, 0xffff0000, v162
	v_lshlrev_b32_e32 v72, 16, v160
	v_and_b32_e32 v73, 0xffff0000, v160
	v_lshlrev_b32_e32 v74, 16, v161
	v_and_b32_e32 v75, 0xffff0000, v161
	v_lshlrev_b32_e32 v80, 16, v163
	v_and_b32_e32 v81, 0xffff0000, v163
	v_pk_fma_f32 v[70:71], v[70:71], v[206:207], v[74:75]
	v_pk_fma_f32 v[68:69], v[68:69], v[204:205], v[72:73]
	v_pk_fma_f32 v[72:73], v[66:67], v[202:203], v[80:81]
	v_pk_fma_f32 v[66:67], v[64:65], v[200:201], v[78:79]
	v_cvt_pk_bf16_f32 v64, v68, v69
	v_cvt_pk_bf16_f32 v65, v70, v71
	s_waitcnt vmcnt(14)
	v_lshlrev_b32_e32 v68, 16, v158
	v_cvt_pk_bf16_f32 v66, v66, v67
	v_cvt_pk_bf16_f32 v67, v72, v73
	global_store_dwordx4 v[76:77], v[64:67], off offset:256
	v_and_b32_e32 v69, 0xffff0000, v158
	v_lshlrev_b32_e32 v70, 16, v159
	v_lshlrev_b32_e32 v64, 16, v156
	v_and_b32_e32 v65, 0xffff0000, v156
	v_and_b32_e32 v71, 0xffff0000, v159
	v_pk_fma_f32 v[60:61], v[60:61], v[212:213], v[64:65]
	v_lshlrev_b32_e32 v66, 16, v157
	v_and_b32_e32 v67, 0xffff0000, v157
	v_pk_fma_f32 v[64:65], v[58:59], v[210:211], v[70:71]
	v_pk_fma_f32 v[58:59], v[56:57], v[208:209], v[68:69]
	v_cvt_pk_bf16_f32 v56, v60, v61
	v_add_co_u32_e32 v60, vcc, s93, v144
	v_pk_fma_f32 v[62:63], v[62:63], v[214:215], v[66:67]
	s_nop 0
	v_addc_co_u32_e32 v61, vcc, 0, v145, vcc
	v_cvt_pk_bf16_f32 v57, v62, v63
	v_cvt_pk_bf16_f32 v58, v58, v59
	v_cvt_pk_bf16_f32 v59, v64, v65
	global_store_dwordx4 v[60:61], v[56:59], off
	s_waitcnt vmcnt(15)
	v_lshlrev_b32_e32 v62, 16, v154
	v_and_b32_e32 v63, 0xffff0000, v154
	v_lshlrev_b32_e32 v56, 16, v152
	v_and_b32_e32 v57, 0xffff0000, v152
	v_lshlrev_b32_e32 v58, 16, v153
	v_and_b32_e32 v59, 0xffff0000, v153
	v_lshlrev_b32_e32 v64, 16, v155
	v_and_b32_e32 v65, 0xffff0000, v155
	v_pk_fma_f32 v[54:55], v[54:55], v[206:207], v[58:59]
	v_pk_fma_f32 v[52:53], v[52:53], v[204:205], v[56:57]
	v_pk_fma_f32 v[56:57], v[50:51], v[202:203], v[64:65]
	v_pk_fma_f32 v[50:51], v[48:49], v[200:201], v[62:63]
	v_cvt_pk_bf16_f32 v48, v52, v53
	v_cvt_pk_bf16_f32 v49, v54, v55
	s_waitcnt vmcnt(14)
	v_lshlrev_b32_e32 v52, 16, v142
	v_cvt_pk_bf16_f32 v50, v50, v51
	v_cvt_pk_bf16_f32 v51, v56, v57
	global_store_dwordx4 v[60:61], v[48:51], off offset:256
	v_and_b32_e32 v53, 0xffff0000, v142
	v_lshlrev_b32_e32 v54, 16, v143
	v_lshlrev_b32_e32 v48, 16, v140
	v_and_b32_e32 v49, 0xffff0000, v140
	v_and_b32_e32 v55, 0xffff0000, v143
	v_pk_fma_f32 v[44:45], v[44:45], v[212:213], v[48:49]
	v_lshlrev_b32_e32 v50, 16, v141
	v_and_b32_e32 v51, 0xffff0000, v141
	v_pk_fma_f32 v[48:49], v[42:43], v[210:211], v[54:55]
	v_pk_fma_f32 v[42:43], v[40:41], v[208:209], v[52:53]
	v_cvt_pk_bf16_f32 v40, v44, v45
	v_add_co_u32_e32 v44, vcc, s33, v144
	v_pk_fma_f32 v[46:47], v[46:47], v[214:215], v[50:51]
	s_nop 0
	v_addc_co_u32_e32 v45, vcc, 0, v145, vcc
	v_cvt_pk_bf16_f32 v41, v46, v47
	v_cvt_pk_bf16_f32 v42, v42, v43
	v_cvt_pk_bf16_f32 v43, v48, v49
	global_store_dwordx4 v[44:45], v[40:43], off
	s_waitcnt vmcnt(15)
; __device__ __forceinline__ unsigned cvt_pk_bf16(float lo, float hi) { unsigned r; asm volatile("v_cvt_pk_bf16_f32 %0, %1, %2" : "=v"(r) : "v"(lo), "v"(hi)); return r; }
; #define PG8_WAIT_V(n) asm volatile("s_waitcnt vmcnt(" #n ")" ::: "memory")
; #define PG8_BAR __builtin_amdgcn_s_barrier()
; template <class Epi>
; __device__ __forceinline__ void gemm_phase(LAS unsigned char* lds, const Gemm g, const StaticOrder& S, const Epi& E) {
;     ...
;         if (!has_next) break;
; #pragma unroll
;         for (int a = 0; a < 2; ++a)
; #pragma unroll
;             for (int b = 0; b < 2; ++b)
; #pragma unroll
;                 for (int m = 0; m < 4; ++m)
; #pragma unroll
;                     for (int n = 0; n < 2; ++n) acc[a][b][m][n] = (f32x4){0.f, 0.f, 0.f, 0.f};
;         cur = nxt; cA = nA; cB = nB; ++ui;
;     }
;     PG8_WAIT_V(0);
;     if (wr == 0) PG8_BAR;
;     PG8_BAR;
;     __device__ __forceinline__ void operator()(f32x4 (&acc)[2][2][4][2], const Unit& u, int wr, int wc, int fr, int fq, LAS unsigned char*) const {
;     ...
;             for (int ai = 0; ai < 2; ++ai)
; #pragma unroll
;                 for (int m = 0; m < 4; ++m)
; #pragma unroll
;                     for (int bj = 0; bj < 2; ++bj) { const u32x4 x = xb[ai][m][bj];
;                         f32x4 r0 = (f32x4){__uint_as_float(x.x << 16), __uint_as_float(x.x & 0xffff0000u), __uint_as_float(x.y << 16), __uint_as_float(x.y & 0xffff0000u)};
;                         f32x4 r1 = (f32x4){__uint_as_float(x.z << 16), __uint_as_float(x.z & 0xffff0000u), __uint_as_float(x.w << 16), __uint_as_float(x.w & 0xffff0000u)};
;                         r0 += sc[bj][0] * acc[ai][bj][m][0]; r1 += sc[bj][1] * acc[ai][bj][m][1];
;                         u32x4 w; w.x = cvt_pk_bf16(r0[0], r0[1]); w.y = cvt_pk_bf16(r0[2], r0[3]); w.z = cvt_pk_bf16(r1[0], r1[1]); w.w = cvt_pk_bf16(r1[2], r1[3]);
;                         *(u32x4*)(out + off0 + (size_t)(ai * HALF + m * 16) * D + bj * HALF) = w; }
	v_lshlrev_b32_e32 v46, 16, v138
	v_and_b32_e32 v47, 0xffff0000, v138
	v_lshlrev_b32_e32 v40, 16, v136
	v_and_b32_e32 v41, 0xffff0000, v136
	v_lshlrev_b32_e32 v42, 16, v137
	v_and_b32_e32 v43, 0xffff0000, v137
	v_lshlrev_b32_e32 v48, 16, v139
	v_and_b32_e32 v49, 0xffff0000, v139
	v_pk_fma_f32 v[38:39], v[38:39], v[206:207], v[42:43]
	v_pk_fma_f32 v[36:37], v[36:37], v[204:205], v[40:41]
	v_pk_fma_f32 v[40:41], v[34:35], v[202:203], v[48:49]
	v_pk_fma_f32 v[34:35], v[32:33], v[200:201], v[46:47]
	v_cvt_pk_bf16_f32 v32, v36, v37
	v_cvt_pk_bf16_f32 v33, v38, v39
	s_waitcnt vmcnt(14)
	v_lshlrev_b32_e32 v36, 16, v134
	v_cvt_pk_bf16_f32 v34, v34, v35
	v_cvt_pk_bf16_f32 v35, v40, v41
	global_store_dwordx4 v[44:45], v[32:35], off offset:256
	v_and_b32_e32 v37, 0xffff0000, v134
	v_lshlrev_b32_e32 v38, 16, v135
	v_lshlrev_b32_e32 v32, 16, v132
	v_and_b32_e32 v33, 0xffff0000, v132
	v_and_b32_e32 v39, 0xffff0000, v135
	v_pk_fma_f32 v[28:29], v[28:29], v[212:213], v[32:33]
	v_lshlrev_b32_e32 v34, 16, v133
	v_and_b32_e32 v35, 0xffff0000, v133
	v_pk_fma_f32 v[32:33], v[26:27], v[210:211], v[38:39]
	v_pk_fma_f32 v[26:27], v[24:25], v[208:209], v[36:37]
	v_cvt_pk_bf16_f32 v24, v28, v29
	v_add_co_u32_e32 v28, vcc, s18, v144
	v_pk_fma_f32 v[30:31], v[30:31], v[214:215], v[34:35]
	s_nop 0
	v_addc_co_u32_e32 v29, vcc, 0, v145, vcc
	v_cvt_pk_bf16_f32 v25, v30, v31
	v_cvt_pk_bf16_f32 v26, v26, v27
	v_cvt_pk_bf16_f32 v27, v32, v33
	global_store_dwordx4 v[28:29], v[24:27], off
	s_waitcnt vmcnt(15)
	v_lshlrev_b32_e32 v30, 16, v130
	v_and_b32_e32 v31, 0xffff0000, v130
	v_lshlrev_b32_e32 v24, 16, v128
	v_and_b32_e32 v25, 0xffff0000, v128
	v_lshlrev_b32_e32 v26, 16, v129
	v_and_b32_e32 v27, 0xffff0000, v129
	v_lshlrev_b32_e32 v32, 16, v131
	v_and_b32_e32 v33, 0xffff0000, v131
	v_pk_fma_f32 v[22:23], v[22:23], v[206:207], v[26:27]
	v_pk_fma_f32 v[20:21], v[20:21], v[204:205], v[24:25]
	v_pk_fma_f32 v[24:25], v[18:19], v[202:203], v[32:33]
	v_pk_fma_f32 v[18:19], v[16:17], v[200:201], v[30:31]
	v_cvt_pk_bf16_f32 v16, v20, v21
	v_cvt_pk_bf16_f32 v17, v22, v23
	s_waitcnt vmcnt(14)
	v_lshlrev_b32_e32 v20, 16, v126
	v_cvt_pk_bf16_f32 v18, v18, v19
	v_cvt_pk_bf16_f32 v19, v24, v25
	global_store_dwordx4 v[28:29], v[16:19], off offset:256
	v_and_b32_e32 v21, 0xffff0000, v126
	v_lshlrev_b32_e32 v22, 16, v127
	v_lshlrev_b32_e32 v16, 16, v124
	v_and_b32_e32 v17, 0xffff0000, v124
	v_and_b32_e32 v23, 0xffff0000, v127
	v_pk_fma_f32 v[12:13], v[12:13], v[212:213], v[16:17]
	v_lshlrev_b32_e32 v18, 16, v125
	v_and_b32_e32 v19, 0xffff0000, v125
	v_pk_fma_f32 v[16:17], v[10:11], v[210:211], v[22:23]
	v_pk_fma_f32 v[10:11], v[8:9], v[208:209], v[20:21]
	v_cvt_pk_bf16_f32 v8, v12, v13
	v_add_co_u32_e32 v12, vcc, s19, v144
	v_pk_fma_f32 v[14:15], v[14:15], v[214:215], v[18:19]
	s_nop 0
	v_addc_co_u32_e32 v13, vcc, 0, v145, vcc
	v_cvt_pk_bf16_f32 v9, v14, v15
	v_cvt_pk_bf16_f32 v10, v10, v11
	v_cvt_pk_bf16_f32 v11, v16, v17
	global_store_dwordx4 v[12:13], v[8:11], off
	s_waitcnt vmcnt(15)
	v_lshlrev_b32_e32 v14, 16, v122
	v_and_b32_e32 v15, 0xffff0000, v122
	v_lshlrev_b32_e32 v8, 16, v120
	v_and_b32_e32 v9, 0xffff0000, v120
	v_lshlrev_b32_e32 v16, 16, v123
	v_and_b32_e32 v17, 0xffff0000, v123
	v_lshlrev_b32_e32 v10, 16, v121
	v_and_b32_e32 v11, 0xffff0000, v121
	v_pk_fma_f32 v[4:5], v[4:5], v[204:205], v[8:9]
	v_pk_fma_f32 v[8:9], v[2:3], v[202:203], v[16:17]
	v_pk_fma_f32 v[2:3], v[0:1], v[200:201], v[14:15]
	s_and_b64 vcc, exec, s[4:5]
	v_pk_fma_f32 v[6:7], v[6:7], v[206:207], v[10:11]
	v_cvt_pk_bf16_f32 v0, v4, v5
	s_nop 0
	v_cvt_pk_bf16_f32 v1, v6, v7
	v_cvt_pk_bf16_f32 v2, v2, v3
	v_cvt_pk_bf16_f32 v3, v8, v9
	global_store_dwordx4 v[12:13], v[0:3], off offset:256
	s_cbranch_vccz .LBB0_849
	s_waitcnt vmcnt(0)
	s_cmpk_gt_u32 s21, 0xff
	v_readlane_b32 s38, v255, 44
	s_cbranch_scc1 .LBB0_864
	s_barrier
